# K-loop LDS-DMA loads switched to SGPR-base (saddr) addressing, removing the loader's per-load 64-bit VALU address adds, on top of barrier realignment and setprio removal
# speedup vs baseline: 1.0197x; 1.0127x over previous
; #define PG8_STAGE(bufoff, gbase, voff) do { _Pragma("unroll") for (int _i = 0; _i < 2; ++_i) \
;     __builtin_amdgcn_global_load_lds((const unsigned*)((const char*)(gbase) + (voff)[_i]), (LAS unsigned*)(lds + (bufoff) + ldsw + _i * 8192), 16, 0, 0); } while (0)
; #define PG8_LDA(dst, b, h) do { _Pragma("unroll") for (int m = 0; m < 4; ++m) _Pragma("unroll") for (int k = 0; k < 2; ++k) dst[m][k] = *(const LAS bf16x8*)(lds + PG8_SA(b, h) + aoff + m * 2048 + k * 1024); } while (0)
; #define PG8_LDB(dst, b, h) do { _Pragma("unroll") for (int n = 0; n < 2; ++n) _Pragma("unroll") for (int k = 0; k < 2; ++k) dst[n][k] = *(const LAS bf16x8*)(lds + PG8_SB(b, h) + boff + n * 2048 + k * 1024); } while (0)
; #define PG8_MMA(ai, bj, At, Bt) do { __builtin_amdgcn_s_setprio(1); _Pragma("unroll") for (int m = 0; m < 4; ++m) _Pragma("unroll") for (int n = 0; n < 2; ++n) _Pragma("unroll") for (int k = 0; k < 2; ++k) \
;     acc[ai][bj][m][n] = __builtin_amdgcn_mfma_f32_16x16x32_bf16(Bt[n][k], At[m][k], acc[ai][bj][m][n], 0, 0, 0); __builtin_amdgcn_s_setprio(0); } while (0)
; #define PG8_WAIT_V(n) asm volatile("s_waitcnt vmcnt(" #n ")" ::: "memory")
; #define PG8_WAIT_L(n) asm volatile("s_waitcnt lgkmcnt(" #n ")" ::: "memory")
; #define PG8_BAR __builtin_amdgcn_s_barrier()
; #define PG8_SCHED __builtin_amdgcn_sched_barrier(0)
; template <class Epi, class Sched>
; __device__ __forceinline__ void gemm_phase(LAS unsigned char* lds, const Gemm g, const Sched& S, const Epi& E) {
;     ...
;       const bool last = (t == nt - 2);
;       const char* a1 = cA + (size_t)(t + 1) * kstep;
;       const char* a2 = last ? nA : cA + (size_t)(t + 2) * kstep; const char* b2 = last ? nB : cB + (size_t)(t + 2) * kstep;
;       const char* a3 = a2 + kstep; const char* b3 = b2 + kstep;
;       if (last && has_next) S.a_ready(nxt);
;       PG8_LDB(B0, 0, 0); PG8_SCHED; PG8_LDA(At, 0, 0); PG8_STAGE(PG8_SA(1, 1), a1 + hstep, voffA);
;       PG8_WAIT_L(8); PG8_BAR; PG8_WAIT_L(0); PG8_MMA(0, 0, At, B0); PG8_BAR; PG8_SCHED;
;       PG8_LDB(B1, 0, 1); PG8_STAGE(PG8_SB(0, 0), b2, voffB);
;       PG8_BAR; PG8_WAIT_L(0); PG8_MMA(0, 1, At, B1); PG8_BAR;
;       PG8_LDA(At, 0, 1); PG8_STAGE(PG8_SA(0, 0), a2, voffA);
;       PG8_BAR; PG8_WAIT_L(0); PG8_MMA(1, 0, At, B0); PG8_BAR; PG8_SCHED;
;       PG8_STAGE(PG8_SB(0, 1), b2 + hstep, voffB);
;       PG8_WAIT_V(6); PG8_BAR; PG8_MMA(1, 1, At, B1); PG8_BAR;
.Lxs_e0:
.LBB0_208:
	s_add_u32 s44, s42, 0xfffc0080
	s_addc_u32 s45, s43, -1
	s_add_i32 s73, 0, 0x10000
	v_add_u32_e32 v151, s73, v141
	ds_read_b128 v[152:155], v151
	ds_read_b128 v[156:159], v151 offset:1024
	ds_read_b128 v[174:177], v151 offset:2048
	ds_read_b128 v[178:181], v151 offset:3072
	s_cmp_eq_u32 s72, 12
	s_cselect_b32 vcc_hi, s35, s45
	s_cselect_b32 vcc_lo, s69, s44
	s_cselect_b32 s45, s23, s52
	s_cselect_b32 s44, s70, s71
	s_add_i32 m0, s12, 0xc000
	ds_read_b128 v[182:185], v150
	ds_read_b128 v[186:189], v150 offset:1024
	ds_read_b128 v[190:193], v150 offset:2048
	ds_read_b128 v[194:197], v150 offset:3072
	ds_read_b128 v[198:201], v150 offset:4096
	ds_read_b128 v[202:205], v150 offset:5120
	ds_read_b128 v[206:209], v150 offset:6144
	ds_read_b128 v[210:213], v150 offset:7168
	global_load_lds_dwordx4 v136, s[42:43]
	s_add_i32 m0, s12, 0xe000
	s_nop 0
	global_load_lds_dwordx4 v138, s[42:43]
	s_waitcnt lgkmcnt(8)
	s_barrier
	s_waitcnt lgkmcnt(0)
	s_waitcnt lgkmcnt(0)
	v_mfma_f32_16x16x32_bf16 v[124:127], v[152:155], v[182:185], v[124:127]
	v_mfma_f32_16x16x32_bf16 v[116:119], v[174:177], v[182:185], v[116:119]
	v_mfma_f32_16x16x32_bf16 v[108:111], v[152:155], v[190:193], v[108:111]
	v_mfma_f32_16x16x32_bf16 v[100:103], v[174:177], v[190:193], v[100:103]
	v_mfma_f32_16x16x32_bf16 v[92:95], v[152:155], v[198:201], v[92:95]
	v_mfma_f32_16x16x32_bf16 v[84:87], v[174:177], v[198:201], v[84:87]
	v_mfma_f32_16x16x32_bf16 v[76:79], v[152:155], v[206:209], v[76:79]
	v_mfma_f32_16x16x32_bf16 v[68:71], v[174:177], v[206:209], v[68:71]
	v_mfma_f32_16x16x32_bf16 v[124:127], v[156:159], v[186:189], v[124:127]
	v_mfma_f32_16x16x32_bf16 v[116:119], v[178:181], v[186:189], v[116:119]
	v_mfma_f32_16x16x32_bf16 v[108:111], v[156:159], v[194:197], v[108:111]
	v_mfma_f32_16x16x32_bf16 v[100:103], v[178:181], v[194:197], v[100:103]
	v_mfma_f32_16x16x32_bf16 v[92:95], v[156:159], v[202:205], v[92:95]
	v_mfma_f32_16x16x32_bf16 v[84:87], v[178:181], v[202:205], v[84:87]
	v_mfma_f32_16x16x32_bf16 v[76:79], v[156:159], v[210:213], v[76:79]
	v_mfma_f32_16x16x32_bf16 v[68:71], v[178:181], v[210:213], v[68:71]
	s_barrier
	s_add_i32 s76, 0, 0x14000
	s_add_i32 s73, s73, s7
	v_add_u32_e32 v151, s76, v141
	s_mov_b32 m0, s73
	ds_read_b128 v[226:229], v151
	ds_read_b128 v[232:235], v151 offset:1024
	ds_read_b128 v[236:239], v151 offset:2048
	ds_read_b128 v[240:243], v151 offset:3072
	global_load_lds_dwordx4 v132, s[44:45]
	s_add_i32 m0, s73, 0x2000
	s_nop 0
	global_load_lds_dwordx4 v128, s[44:45]
	s_barrier
	s_waitcnt lgkmcnt(0)
	s_waitcnt lgkmcnt(0)
	v_mfma_f32_16x16x32_bf16 v[120:123], v[226:229], v[182:185], v[120:123]
	v_mfma_f32_16x16x32_bf16 v[112:115], v[236:239], v[182:185], v[112:115]
	v_mfma_f32_16x16x32_bf16 v[104:107], v[226:229], v[190:193], v[104:107]
	v_mfma_f32_16x16x32_bf16 v[96:99], v[236:239], v[190:193], v[96:99]
	v_mfma_f32_16x16x32_bf16 v[88:91], v[226:229], v[198:201], v[88:91]
	v_mfma_f32_16x16x32_bf16 v[80:83], v[236:239], v[198:201], v[80:83]
	v_mfma_f32_16x16x32_bf16 v[72:75], v[226:229], v[206:209], v[72:75]
	v_mfma_f32_16x16x32_bf16 v[64:67], v[236:239], v[206:209], v[64:67]
	v_mfma_f32_16x16x32_bf16 v[120:123], v[232:235], v[186:189], v[120:123]
	v_mfma_f32_16x16x32_bf16 v[112:115], v[240:243], v[186:189], v[112:115]
	v_mfma_f32_16x16x32_bf16 v[104:107], v[232:235], v[194:197], v[104:107]
	v_mfma_f32_16x16x32_bf16 v[96:99], v[240:243], v[194:197], v[96:99]
	v_mfma_f32_16x16x32_bf16 v[88:91], v[232:235], v[202:205], v[88:91]
	v_mfma_f32_16x16x32_bf16 v[80:83], v[240:243], v[202:205], v[80:83]
	v_mfma_f32_16x16x32_bf16 v[72:75], v[232:235], v[210:213], v[72:75]
	v_mfma_f32_16x16x32_bf16 v[64:67], v[240:243], v[210:213], v[64:67]
	s_mov_b32 m0, s12
	s_barrier
	ds_read_b128 v[182:185], v150 offset:16384
	ds_read_b128 v[186:189], v150 offset:17408
	ds_read_b128 v[190:193], v150 offset:18432
	ds_read_b128 v[194:197], v150 offset:19456
	ds_read_b128 v[198:201], v150 offset:20480
	ds_read_b128 v[202:205], v150 offset:21504
	ds_read_b128 v[206:209], v150 offset:22528
	ds_read_b128 v[210:213], v150 offset:23552
	global_load_lds_dwordx4 v134, vcc
	s_mov_b32 m0, s13
	s_nop 0
	global_load_lds_dwordx4 v130, vcc
	s_barrier
	s_waitcnt lgkmcnt(0)
	s_waitcnt lgkmcnt(0)
	v_mfma_f32_16x16x32_bf16 v[60:63], v[152:155], v[182:185], v[60:63]
	v_mfma_f32_16x16x32_bf16 v[52:55], v[174:177], v[182:185], v[52:55]
	v_mfma_f32_16x16x32_bf16 v[44:47], v[152:155], v[190:193], v[44:47]
	v_mfma_f32_16x16x32_bf16 v[36:39], v[174:177], v[190:193], v[36:39]
	v_mfma_f32_16x16x32_bf16 v[28:31], v[152:155], v[198:201], v[28:31]
	v_mfma_f32_16x16x32_bf16 v[20:23], v[174:177], v[198:201], v[20:23]
	v_mfma_f32_16x16x32_bf16 v[12:15], v[152:155], v[206:209], v[12:15]
	v_mfma_f32_16x16x32_bf16 v[4:7], v[174:177], v[206:209], v[4:7]
	v_mfma_f32_16x16x32_bf16 v[60:63], v[156:159], v[186:189], v[60:63]
	v_mfma_f32_16x16x32_bf16 v[52:55], v[178:181], v[186:189], v[52:55]
	v_mfma_f32_16x16x32_bf16 v[44:47], v[156:159], v[194:197], v[44:47]
	v_mfma_f32_16x16x32_bf16 v[36:39], v[178:181], v[194:197], v[36:39]
	v_mfma_f32_16x16x32_bf16 v[28:31], v[156:159], v[202:205], v[28:31]
	v_mfma_f32_16x16x32_bf16 v[20:23], v[178:181], v[202:205], v[20:23]
	v_mfma_f32_16x16x32_bf16 v[12:15], v[156:159], v[210:213], v[12:15]
	v_mfma_f32_16x16x32_bf16 v[4:7], v[178:181], v[210:213], v[4:7]
	s_barrier
	s_add_u32 s74, s44, 0x40000
	s_addc_u32 s75, s45, 0
	s_add_i32 s73, s76, s7
	s_mov_b32 m0, s73
	s_nop 0
	global_load_lds_dwordx4 v132, s[74:75]
	s_add_i32 m0, s73, 0x2000
	s_nop 0
	global_load_lds_dwordx4 v128, s[74:75]
	s_waitcnt vmcnt(6)
	s_barrier
; #define PG8_STAGE(bufoff, gbase, voff) do { _Pragma("unroll") for (int _i = 0; _i < 2; ++_i) \
;     __builtin_amdgcn_global_load_lds((const unsigned*)((const char*)(gbase) + (voff)[_i]), (LAS unsigned*)(lds + (bufoff) + ldsw + _i * 8192), 16, 0, 0); } while (0)
; #define PG8_LDA(dst, b, h) do { _Pragma("unroll") for (int m = 0; m < 4; ++m) _Pragma("unroll") for (int k = 0; k < 2; ++k) dst[m][k] = *(const LAS bf16x8*)(lds + PG8_SA(b, h) + aoff + m * 2048 + k * 1024); } while (0)
; #define PG8_LDB(dst, b, h) do { _Pragma("unroll") for (int n = 0; n < 2; ++n) _Pragma("unroll") for (int k = 0; k < 2; ++k) dst[n][k] = *(const LAS bf16x8*)(lds + PG8_SB(b, h) + boff + n * 2048 + k * 1024); } while (0)
; #define PG8_MMA(ai, bj, At, Bt) do { __builtin_amdgcn_s_setprio(1); _Pragma("unroll") for (int m = 0; m < 4; ++m) _Pragma("unroll") for (int n = 0; n < 2; ++n) _Pragma("unroll") for (int k = 0; k < 2; ++k) \
;     acc[ai][bj][m][n] = __builtin_amdgcn_mfma_f32_16x16x32_bf16(Bt[n][k], At[m][k], acc[ai][bj][m][n], 0, 0, 0); __builtin_amdgcn_s_setprio(0); } while (0)
; #define PG8_WAIT_V(n) asm volatile("s_waitcnt vmcnt(" #n ")" ::: "memory")
; #define PG8_WAIT_L(n) asm volatile("s_waitcnt lgkmcnt(" #n ")" ::: "memory")
; #define PG8_BAR __builtin_amdgcn_s_barrier()
; #define PG8_SCHED __builtin_amdgcn_sched_barrier(0)
; template <class Epi, class Sched>
; __device__ __forceinline__ void gemm_phase(LAS unsigned char* lds, const Gemm g, const Sched& S, const Epi& E) {
;     ...
;       PG8_WAIT_V(6); PG8_BAR; PG8_MMA(1, 1, At, B1); PG8_BAR;
;       PG8_LDB(B0, 1, 0); PG8_SCHED; PG8_LDA(At, 1, 0); PG8_STAGE(PG8_SA(0, 1), a2 + hstep, voffA);
;       PG8_WAIT_L(8); PG8_BAR; PG8_WAIT_L(0); PG8_MMA(0, 0, At, B0); PG8_BAR; PG8_SCHED;
;       PG8_LDB(B1, 1, 1); PG8_STAGE(PG8_SB(1, 0), b3, voffB);
	v_mfma_f32_16x16x32_bf16 v[56:59], v[226:229], v[182:185], v[56:59]
	v_mfma_f32_16x16x32_bf16 v[48:51], v[236:239], v[182:185], v[48:51]
	v_mfma_f32_16x16x32_bf16 v[40:43], v[226:229], v[190:193], v[40:43]
	v_mfma_f32_16x16x32_bf16 v[32:35], v[236:239], v[190:193], v[32:35]
	v_mfma_f32_16x16x32_bf16 v[24:27], v[226:229], v[198:201], v[24:27]
	v_mfma_f32_16x16x32_bf16 v[16:19], v[236:239], v[198:201], v[16:19]
	v_mfma_f32_16x16x32_bf16 v[8:11], v[226:229], v[206:209], v[8:11]
	v_mfma_f32_16x16x32_bf16 v[0:3], v[236:239], v[206:209], v[0:3]
	v_mfma_f32_16x16x32_bf16 v[56:59], v[232:235], v[186:189], v[56:59]
	v_mfma_f32_16x16x32_bf16 v[48:51], v[240:243], v[186:189], v[48:51]
	v_mfma_f32_16x16x32_bf16 v[40:43], v[232:235], v[194:197], v[40:43]
	v_mfma_f32_16x16x32_bf16 v[32:35], v[240:243], v[194:197], v[32:35]
	v_mfma_f32_16x16x32_bf16 v[24:27], v[232:235], v[202:205], v[24:27]
	v_mfma_f32_16x16x32_bf16 v[16:19], v[240:243], v[202:205], v[16:19]
	v_mfma_f32_16x16x32_bf16 v[8:11], v[232:235], v[210:213], v[8:11]
	v_mfma_f32_16x16x32_bf16 v[0:3], v[240:243], v[210:213], v[0:3]
	s_add_i32 s73, 0, 0x18000
	v_add_u32_e32 v151, s73, v141
	s_barrier
	ds_read_b128 v[152:155], v151
	ds_read_b128 v[156:159], v151 offset:1024
	ds_read_b128 v[174:177], v151 offset:2048
	ds_read_b128 v[178:181], v151 offset:3072
	s_add_u32 s74, vcc_lo, 0x40000
	s_addc_u32 s75, vcc_hi, 0
	s_mov_b32 m0, s48
	ds_read_b128 v[182:185], v150 offset:32768
	ds_read_b128 v[186:189], v150 offset:33792
	ds_read_b128 v[190:193], v150 offset:34816
	ds_read_b128 v[194:197], v150 offset:35840
	ds_read_b128 v[198:201], v150 offset:36864
	ds_read_b128 v[202:205], v150 offset:37888
	ds_read_b128 v[206:209], v150 offset:38912
	ds_read_b128 v[210:213], v150 offset:39936
	global_load_lds_dwordx4 v134, s[74:75]
	s_mov_b32 m0, s49
	s_nop 0
	global_load_lds_dwordx4 v130, s[74:75]
	s_waitcnt lgkmcnt(8)
	s_barrier
	s_waitcnt lgkmcnt(0)
	s_waitcnt lgkmcnt(0)
	v_mfma_f32_16x16x32_bf16 v[124:127], v[152:155], v[182:185], v[124:127]
	v_mfma_f32_16x16x32_bf16 v[116:119], v[174:177], v[182:185], v[116:119]
	v_mfma_f32_16x16x32_bf16 v[108:111], v[152:155], v[190:193], v[108:111]
	v_mfma_f32_16x16x32_bf16 v[100:103], v[174:177], v[190:193], v[100:103]
	v_mfma_f32_16x16x32_bf16 v[92:95], v[152:155], v[198:201], v[92:95]
	v_mfma_f32_16x16x32_bf16 v[84:87], v[174:177], v[198:201], v[84:87]
	v_mfma_f32_16x16x32_bf16 v[76:79], v[152:155], v[206:209], v[76:79]
	v_mfma_f32_16x16x32_bf16 v[68:71], v[174:177], v[206:209], v[68:71]
	v_mfma_f32_16x16x32_bf16 v[124:127], v[156:159], v[186:189], v[124:127]
	v_mfma_f32_16x16x32_bf16 v[116:119], v[178:181], v[186:189], v[116:119]
	v_mfma_f32_16x16x32_bf16 v[108:111], v[156:159], v[194:197], v[108:111]
	v_mfma_f32_16x16x32_bf16 v[100:103], v[178:181], v[194:197], v[100:103]
	v_mfma_f32_16x16x32_bf16 v[92:95], v[156:159], v[202:205], v[92:95]
	v_mfma_f32_16x16x32_bf16 v[84:87], v[178:181], v[202:205], v[84:87]
	v_mfma_f32_16x16x32_bf16 v[76:79], v[156:159], v[210:213], v[76:79]
	v_mfma_f32_16x16x32_bf16 v[68:71], v[178:181], v[210:213], v[68:71]
	s_barrier
	s_add_i32 s74, 0, 0x1c000
	s_add_i32 s73, s73, s7
	v_add_u32_e32 v151, s74, v141
	s_add_u32 s60, s44, s80
	s_addc_u32 s61, s45, s81
	s_mov_b32 m0, s73
	ds_read_b128 v[226:229], v151
	ds_read_b128 v[232:235], v151 offset:1024
	ds_read_b128 v[236:239], v151 offset:2048
	ds_read_b128 v[240:243], v151 offset:3072
	global_load_lds_dwordx4 v132, s[60:61]
	s_add_i32 m0, s73, 0x2000
	s_nop 0
	global_load_lds_dwordx4 v128, s[60:61]
	s_barrier
; #define PG8_STAGE(bufoff, gbase, voff) do { _Pragma("unroll") for (int _i = 0; _i < 2; ++_i) \
;     __builtin_amdgcn_global_load_lds((const unsigned*)((const char*)(gbase) + (voff)[_i]), (LAS unsigned*)(lds + (bufoff) + ldsw + _i * 8192), 16, 0, 0); } while (0)
; #define PG8_LDA(dst, b, h) do { _Pragma("unroll") for (int m = 0; m < 4; ++m) _Pragma("unroll") for (int k = 0; k < 2; ++k) dst[m][k] = *(const LAS bf16x8*)(lds + PG8_SA(b, h) + aoff + m * 2048 + k * 1024); } while (0)
; #define PG8_MMA(ai, bj, At, Bt) do { __builtin_amdgcn_s_setprio(1); _Pragma("unroll") for (int m = 0; m < 4; ++m) _Pragma("unroll") for (int n = 0; n < 2; ++n) _Pragma("unroll") for (int k = 0; k < 2; ++k) \
;     acc[ai][bj][m][n] = __builtin_amdgcn_mfma_f32_16x16x32_bf16(Bt[n][k], At[m][k], acc[ai][bj][m][n], 0, 0, 0); __builtin_amdgcn_s_setprio(0); } while (0)
; #define PG8_WAIT_V(n) asm volatile("s_waitcnt vmcnt(" #n ")" ::: "memory")
; #define PG8_WAIT_L(n) asm volatile("s_waitcnt lgkmcnt(" #n ")" ::: "memory")
; #define PG8_BAR __builtin_amdgcn_s_barrier()
; #define PG8_SCHED __builtin_amdgcn_sched_barrier(0)
; template <class Epi, class Sched>
; __device__ __forceinline__ void gemm_phase(LAS unsigned char* lds, const Gemm g, const Sched& S, const Epi& E) {
;     ...
;       PG8_BAR; PG8_WAIT_L(0); PG8_MMA(0, 1, At, B1); PG8_BAR;
;       PG8_LDA(At, 1, 1); PG8_STAGE(PG8_SA(1, 0), a3, voffA);
;       PG8_BAR; PG8_WAIT_L(0); PG8_MMA(1, 0, At, B0); PG8_BAR; PG8_SCHED;
;       PG8_STAGE(PG8_SB(1, 1), b3 + hstep, voffB);
;       PG8_WAIT_V(6); PG8_BAR; PG8_MMA(1, 1, At, B1); PG8_BAR;
;     }
	s_waitcnt lgkmcnt(0)
	s_waitcnt lgkmcnt(0)
	v_mfma_f32_16x16x32_bf16 v[120:123], v[226:229], v[182:185], v[120:123]
	v_mfma_f32_16x16x32_bf16 v[112:115], v[236:239], v[182:185], v[112:115]
	v_mfma_f32_16x16x32_bf16 v[104:107], v[226:229], v[190:193], v[104:107]
	v_mfma_f32_16x16x32_bf16 v[96:99], v[236:239], v[190:193], v[96:99]
	v_mfma_f32_16x16x32_bf16 v[88:91], v[226:229], v[198:201], v[88:91]
	v_mfma_f32_16x16x32_bf16 v[80:83], v[236:239], v[198:201], v[80:83]
	v_mfma_f32_16x16x32_bf16 v[72:75], v[226:229], v[206:209], v[72:75]
	v_mfma_f32_16x16x32_bf16 v[64:67], v[236:239], v[206:209], v[64:67]
	v_mfma_f32_16x16x32_bf16 v[120:123], v[232:235], v[186:189], v[120:123]
	v_mfma_f32_16x16x32_bf16 v[112:115], v[240:243], v[186:189], v[112:115]
	v_mfma_f32_16x16x32_bf16 v[104:107], v[232:235], v[194:197], v[104:107]
	v_mfma_f32_16x16x32_bf16 v[96:99], v[240:243], v[194:197], v[96:99]
	v_mfma_f32_16x16x32_bf16 v[88:91], v[232:235], v[202:205], v[88:91]
	v_mfma_f32_16x16x32_bf16 v[80:83], v[240:243], v[202:205], v[80:83]
	v_mfma_f32_16x16x32_bf16 v[72:75], v[232:235], v[210:213], v[72:75]
	v_mfma_f32_16x16x32_bf16 v[64:67], v[240:243], v[210:213], v[64:67]
	s_mov_b32 m0, s51
	s_add_u32 s66, vcc_lo, s80
	s_addc_u32 s67, vcc_hi, s81
	s_barrier
	ds_read_b128 v[182:185], v150 offset:49152
	ds_read_b128 v[186:189], v150 offset:50176
	ds_read_b128 v[190:193], v150 offset:51200
	ds_read_b128 v[194:197], v150 offset:52224
	ds_read_b128 v[198:201], v150 offset:53248
	ds_read_b128 v[202:205], v150 offset:54272
	ds_read_b128 v[206:209], v150 offset:55296
	ds_read_b128 v[210:213], v150 offset:56320
	global_load_lds_dwordx4 v134, s[66:67]
	s_mov_b32 m0, s62
	s_nop 0
	global_load_lds_dwordx4 v130, s[66:67]
	s_barrier
	s_waitcnt lgkmcnt(0)
	s_waitcnt lgkmcnt(0)
	v_mfma_f32_16x16x32_bf16 v[60:63], v[152:155], v[182:185], v[60:63]
	v_mfma_f32_16x16x32_bf16 v[52:55], v[174:177], v[182:185], v[52:55]
	v_mfma_f32_16x16x32_bf16 v[44:47], v[152:155], v[190:193], v[44:47]
	v_mfma_f32_16x16x32_bf16 v[36:39], v[174:177], v[190:193], v[36:39]
	v_mfma_f32_16x16x32_bf16 v[28:31], v[152:155], v[198:201], v[28:31]
	v_mfma_f32_16x16x32_bf16 v[20:23], v[174:177], v[198:201], v[20:23]
	v_mfma_f32_16x16x32_bf16 v[12:15], v[152:155], v[206:209], v[12:15]
	v_mfma_f32_16x16x32_bf16 v[4:7], v[174:177], v[206:209], v[4:7]
	v_mfma_f32_16x16x32_bf16 v[60:63], v[156:159], v[186:189], v[60:63]
	v_mfma_f32_16x16x32_bf16 v[52:55], v[178:181], v[186:189], v[52:55]
	v_mfma_f32_16x16x32_bf16 v[44:47], v[156:159], v[194:197], v[44:47]
	v_mfma_f32_16x16x32_bf16 v[36:39], v[178:181], v[194:197], v[36:39]
	v_mfma_f32_16x16x32_bf16 v[28:31], v[156:159], v[202:205], v[28:31]
	v_mfma_f32_16x16x32_bf16 v[20:23], v[178:181], v[202:205], v[20:23]
	v_mfma_f32_16x16x32_bf16 v[12:15], v[156:159], v[210:213], v[12:15]
	v_mfma_f32_16x16x32_bf16 v[4:7], v[178:181], v[210:213], v[4:7]
	s_barrier
	s_add_u32 s44, s44, 0x40080
	s_addc_u32 s45, s45, 0
	s_add_i32 s73, s74, s7
	s_mov_b32 m0, s73
	s_nop 0
	global_load_lds_dwordx4 v132, s[44:45]
	s_add_i32 m0, s73, 0x2000
	s_nop 0
	global_load_lds_dwordx4 v128, s[44:45]
	s_waitcnt vmcnt(6)
	s_barrier
	v_mfma_f32_16x16x32_bf16 v[56:59], v[226:229], v[182:185], v[56:59]
	v_mfma_f32_16x16x32_bf16 v[48:51], v[236:239], v[182:185], v[48:51]
	v_mfma_f32_16x16x32_bf16 v[40:43], v[226:229], v[190:193], v[40:43]
	v_mfma_f32_16x16x32_bf16 v[32:35], v[236:239], v[190:193], v[32:35]
	v_mfma_f32_16x16x32_bf16 v[24:27], v[226:229], v[198:201], v[24:27]
	v_mfma_f32_16x16x32_bf16 v[16:19], v[236:239], v[198:201], v[16:19]
	v_mfma_f32_16x16x32_bf16 v[8:11], v[226:229], v[206:209], v[8:11]
	v_mfma_f32_16x16x32_bf16 v[0:3], v[236:239], v[206:209], v[0:3]
	v_mfma_f32_16x16x32_bf16 v[56:59], v[232:235], v[186:189], v[56:59]
	v_mfma_f32_16x16x32_bf16 v[48:51], v[240:243], v[186:189], v[48:51]
	v_mfma_f32_16x16x32_bf16 v[40:43], v[232:235], v[194:197], v[40:43]
	v_mfma_f32_16x16x32_bf16 v[32:35], v[240:243], v[194:197], v[32:35]
	v_mfma_f32_16x16x32_bf16 v[24:27], v[232:235], v[202:205], v[24:27]
	v_mfma_f32_16x16x32_bf16 v[16:19], v[240:243], v[202:205], v[16:19]
	v_mfma_f32_16x16x32_bf16 v[8:11], v[232:235], v[210:213], v[8:11]
	v_mfma_f32_16x16x32_bf16 v[0:3], v[240:243], v[210:213], v[0:3]
	s_add_i32 s72, s72, 2
	s_add_u32 s42, s42, 0x100
	s_addc_u32 s43, s43, 0
	s_add_u32 s71, s71, 0x100
	s_addc_u32 s52, s52, 0
	s_cmp_gt_u32 s72, 13
	s_barrier
	s_cbranch_scc0 .LBB0_208
	s_cmp_lt_u32 s101, 0x100
	s_cbranch_scc0 .Lxa_0
	s_barrier

; #define PG8_STAGE(bufoff, gbase, voff) do { _Pragma("unroll") for (int _i = 0; _i < 2; ++_i) \
;     __builtin_amdgcn_global_load_lds((const unsigned*)((const char*)(gbase) + (voff)[_i]), (LAS unsigned*)(lds + (bufoff) + ldsw + _i * 8192), 16, 0, 0); } while (0)
; #define PG8_LDA(dst, b, h) do { _Pragma("unroll") for (int m = 0; m < 4; ++m) _Pragma("unroll") for (int k = 0; k < 2; ++k) dst[m][k] = *(const LAS bf16x8*)(lds + PG8_SA(b, h) + aoff + m * 2048 + k * 1024); } while (0)
; #define PG8_LDB(dst, b, h) do { _Pragma("unroll") for (int n = 0; n < 2; ++n) _Pragma("unroll") for (int k = 0; k < 2; ++k) dst[n][k] = *(const LAS bf16x8*)(lds + PG8_SB(b, h) + boff + n * 2048 + k * 1024); } while (0)
; #define PG8_MMA(ai, bj, At, Bt) do { __builtin_amdgcn_s_setprio(1); _Pragma("unroll") for (int m = 0; m < 4; ++m) _Pragma("unroll") for (int n = 0; n < 2; ++n) _Pragma("unroll") for (int k = 0; k < 2; ++k) \
;     acc[ai][bj][m][n] = __builtin_amdgcn_mfma_f32_16x16x32_bf16(Bt[n][k], At[m][k], acc[ai][bj][m][n], 0, 0, 0); __builtin_amdgcn_s_setprio(0); } while (0)
; #define PG8_WAIT_L(n) asm volatile("s_waitcnt lgkmcnt(" #n ")" ::: "memory")
; #define PG8_BAR __builtin_amdgcn_s_barrier()
; #define PG8_SCHED __builtin_amdgcn_sched_barrier(0)
; template <class Epi, class Sched>
; __device__ __forceinline__ void gemm_phase(LAS unsigned char* lds, const Gemm g, const Sched& S, const Epi& E) {
;     ...
;       const bool last = (t == nt - 2);
;       const char* a1 = cA + (size_t)(t + 1) * kstep;
;       const char* a2 = last ? nA : cA + (size_t)(t + 2) * kstep; const char* b2 = last ? nB : cB + (size_t)(t + 2) * kstep;
;       const char* a3 = a2 + kstep; const char* b3 = b2 + kstep;
;       if (last && has_next) S.a_ready(nxt);
;       PG8_LDB(B0, 0, 0); PG8_SCHED; PG8_LDA(At, 0, 0); PG8_STAGE(PG8_SA(1, 1), a1 + hstep, voffA);
;       PG8_WAIT_L(8); PG8_BAR; PG8_WAIT_L(0); PG8_MMA(0, 0, At, B0); PG8_BAR; PG8_SCHED;
;       PG8_LDB(B1, 0, 1); PG8_STAGE(PG8_SB(0, 0), b2, voffB);
;       PG8_BAR; PG8_WAIT_L(0); PG8_MMA(0, 1, At, B1); PG8_BAR;
;       PG8_LDA(At, 0, 1); PG8_STAGE(PG8_SA(0, 0), a2, voffA);
;       PG8_BAR; PG8_WAIT_L(0); PG8_MMA(1, 0, At, B0); PG8_BAR; PG8_SCHED;
.Lxs_e1:
.LBB0_281:
	s_add_u32 s42, s34, 0x100
	s_addc_u32 s43, s35, 0
	s_add_i32 s72, 0, 0x10000
	v_add_u32_e32 v140, s72, v202
	ds_read_b128 v[128:131], v140
	ds_read_b128 v[132:135], v140 offset:1024
	ds_read_b128 v[136:139], v140 offset:2048
	ds_read_b128 v[140:143], v140 offset:3072
	s_cmp_eq_u32 s52, 40
	s_cselect_b32 vcc_hi, s23, s43
	s_cselect_b32 vcc_lo, s22, s42
	s_cselect_b32 s45, s37, s49
	s_cselect_b32 s44, s36, s48
	s_add_i32 m0, s51, 0xc000
	ds_read_b128 v[144:147], v203
	ds_read_b128 v[148:151], v203 offset:1024
	ds_read_b128 v[152:155], v203 offset:2048
	ds_read_b128 v[186:189], v203 offset:3072
	ds_read_b128 v[190:193], v203 offset:4096
	ds_read_b128 v[194:197], v203 offset:5120
	ds_read_b128 v[198:201], v203 offset:6144
	ds_read_b128 v[204:207], v203 offset:7168
	global_load_lds_dwordx4 v182, s[34:35]
	s_add_i32 m0, s51, 0xe000
	s_nop 0
	global_load_lds_dwordx4 v184, s[34:35]
	s_waitcnt lgkmcnt(8)
	s_barrier
	s_waitcnt lgkmcnt(0)
	s_waitcnt lgkmcnt(0)
	v_mfma_f32_16x16x32_bf16 v[124:127], v[128:131], v[144:147], v[124:127]
	v_mfma_f32_16x16x32_bf16 v[120:123], v[136:139], v[144:147], v[120:123]
	v_mfma_f32_16x16x32_bf16 v[108:111], v[128:131], v[152:155], v[108:111]
	v_mfma_f32_16x16x32_bf16 v[104:107], v[136:139], v[152:155], v[104:107]
	v_mfma_f32_16x16x32_bf16 v[92:95], v[128:131], v[190:193], v[92:95]
	v_mfma_f32_16x16x32_bf16 v[88:91], v[136:139], v[190:193], v[88:91]
	v_mfma_f32_16x16x32_bf16 v[76:79], v[128:131], v[198:201], v[76:79]
	v_mfma_f32_16x16x32_bf16 v[72:75], v[136:139], v[198:201], v[72:75]
	v_mfma_f32_16x16x32_bf16 v[124:127], v[132:135], v[148:151], v[124:127]
	v_mfma_f32_16x16x32_bf16 v[120:123], v[140:143], v[148:151], v[120:123]
	v_mfma_f32_16x16x32_bf16 v[108:111], v[132:135], v[186:189], v[108:111]
	v_mfma_f32_16x16x32_bf16 v[104:107], v[140:143], v[186:189], v[104:107]
	v_mfma_f32_16x16x32_bf16 v[92:95], v[132:135], v[194:197], v[92:95]
	v_mfma_f32_16x16x32_bf16 v[88:91], v[140:143], v[194:197], v[88:91]
	v_mfma_f32_16x16x32_bf16 v[76:79], v[132:135], v[204:207], v[76:79]
	v_mfma_f32_16x16x32_bf16 v[72:75], v[140:143], v[204:207], v[72:75]
	s_barrier
	s_add_i32 s73, 0, 0x14000
	s_add_i32 s34, s72, s7
	v_add_u32_e32 v160, s73, v202
	s_mov_b32 m0, s34
	ds_read_b128 v[208:211], v160
	ds_read_b128 v[226:229], v160 offset:1024
	ds_read_b128 v[232:235], v160 offset:2048
	ds_read_b128 v[236:239], v160 offset:3072
	global_load_lds_dwordx4 v174, s[44:45]
	s_add_i32 m0, s34, 0x2000
	s_nop 0
	global_load_lds_dwordx4 v156, s[44:45]
	s_barrier
	s_waitcnt lgkmcnt(0)
	s_waitcnt lgkmcnt(0)
	v_mfma_f32_16x16x32_bf16 v[116:119], v[208:211], v[144:147], v[116:119]
	v_mfma_f32_16x16x32_bf16 v[112:115], v[232:235], v[144:147], v[112:115]
	v_mfma_f32_16x16x32_bf16 v[100:103], v[208:211], v[152:155], v[100:103]
	v_mfma_f32_16x16x32_bf16 v[96:99], v[232:235], v[152:155], v[96:99]
	v_mfma_f32_16x16x32_bf16 v[84:87], v[208:211], v[190:193], v[84:87]
	v_mfma_f32_16x16x32_bf16 v[80:83], v[232:235], v[190:193], v[80:83]
	v_mfma_f32_16x16x32_bf16 v[68:71], v[208:211], v[198:201], v[68:71]
	v_mfma_f32_16x16x32_bf16 v[64:67], v[232:235], v[198:201], v[64:67]
	v_mfma_f32_16x16x32_bf16 v[116:119], v[226:229], v[148:151], v[116:119]
	v_mfma_f32_16x16x32_bf16 v[112:115], v[236:239], v[148:151], v[112:115]
	v_mfma_f32_16x16x32_bf16 v[100:103], v[226:229], v[186:189], v[100:103]
	v_mfma_f32_16x16x32_bf16 v[96:99], v[236:239], v[186:189], v[96:99]
	v_mfma_f32_16x16x32_bf16 v[84:87], v[226:229], v[194:197], v[84:87]
	v_mfma_f32_16x16x32_bf16 v[80:83], v[236:239], v[194:197], v[80:83]
	v_mfma_f32_16x16x32_bf16 v[68:71], v[226:229], v[204:207], v[68:71]
	v_mfma_f32_16x16x32_bf16 v[64:67], v[236:239], v[204:207], v[64:67]
	s_mov_b32 m0, s51
	s_barrier
	ds_read_b128 v[144:147], v203 offset:16384
	ds_read_b128 v[148:151], v203 offset:17408
	ds_read_b128 v[152:155], v203 offset:18432
	ds_read_b128 v[186:189], v203 offset:19456
	ds_read_b128 v[190:193], v203 offset:20480
	ds_read_b128 v[194:197], v203 offset:21504
	ds_read_b128 v[198:201], v203 offset:22528
	ds_read_b128 v[204:207], v203 offset:23552
	global_load_lds_dwordx4 v176, vcc
	s_mov_b32 m0, s62
	s_nop 0
	global_load_lds_dwordx4 v158, vcc
	s_barrier
	s_waitcnt lgkmcnt(0)
	s_waitcnt lgkmcnt(0)
	v_mfma_f32_16x16x32_bf16 v[60:63], v[128:131], v[144:147], v[60:63]
	v_mfma_f32_16x16x32_bf16 v[56:59], v[136:139], v[144:147], v[56:59]
	v_mfma_f32_16x16x32_bf16 v[44:47], v[128:131], v[152:155], v[44:47]
	v_mfma_f32_16x16x32_bf16 v[40:43], v[136:139], v[152:155], v[40:43]
	v_mfma_f32_16x16x32_bf16 v[28:31], v[128:131], v[190:193], v[28:31]
	v_mfma_f32_16x16x32_bf16 v[24:27], v[136:139], v[190:193], v[24:27]
	v_mfma_f32_16x16x32_bf16 v[12:15], v[128:131], v[198:201], v[12:15]
	v_mfma_f32_16x16x32_bf16 v[8:11], v[136:139], v[198:201], v[8:11]
	v_mfma_f32_16x16x32_bf16 v[60:63], v[132:135], v[148:151], v[60:63]
	v_mfma_f32_16x16x32_bf16 v[56:59], v[140:143], v[148:151], v[56:59]
	v_mfma_f32_16x16x32_bf16 v[44:47], v[132:135], v[186:189], v[44:47]
	v_mfma_f32_16x16x32_bf16 v[40:43], v[140:143], v[186:189], v[40:43]
	v_mfma_f32_16x16x32_bf16 v[28:31], v[132:135], v[194:197], v[28:31]
	v_mfma_f32_16x16x32_bf16 v[24:27], v[140:143], v[194:197], v[24:27]
	v_mfma_f32_16x16x32_bf16 v[12:15], v[132:135], v[204:207], v[12:15]
	v_mfma_f32_16x16x32_bf16 v[8:11], v[140:143], v[204:207], v[8:11]
	s_barrier
	s_add_u32 s34, s44, 0xb0000
	s_addc_u32 s35, s45, 0
	s_add_i32 s72, s73, s7
	s_mov_b32 m0, s72
	s_nop 0
	global_load_lds_dwordx4 v174, s[34:35]
	s_add_i32 m0, s72, 0x2000
	s_nop 0
	global_load_lds_dwordx4 v156, s[34:35]
	s_waitcnt vmcnt(6)
	s_barrier
; #define PG8_STAGE(bufoff, gbase, voff) do { _Pragma("unroll") for (int _i = 0; _i < 2; ++_i) \
;     __builtin_amdgcn_global_load_lds((const unsigned*)((const char*)(gbase) + (voff)[_i]), (LAS unsigned*)(lds + (bufoff) + ldsw + _i * 8192), 16, 0, 0); } while (0)
; #define PG8_LDA(dst, b, h) do { _Pragma("unroll") for (int m = 0; m < 4; ++m) _Pragma("unroll") for (int k = 0; k < 2; ++k) dst[m][k] = *(const LAS bf16x8*)(lds + PG8_SA(b, h) + aoff + m * 2048 + k * 1024); } while (0)
; #define PG8_LDB(dst, b, h) do { _Pragma("unroll") for (int n = 0; n < 2; ++n) _Pragma("unroll") for (int k = 0; k < 2; ++k) dst[n][k] = *(const LAS bf16x8*)(lds + PG8_SB(b, h) + boff + n * 2048 + k * 1024); } while (0)
; #define PG8_MMA(ai, bj, At, Bt) do { __builtin_amdgcn_s_setprio(1); _Pragma("unroll") for (int m = 0; m < 4; ++m) _Pragma("unroll") for (int n = 0; n < 2; ++n) _Pragma("unroll") for (int k = 0; k < 2; ++k) \
;     acc[ai][bj][m][n] = __builtin_amdgcn_mfma_f32_16x16x32_bf16(Bt[n][k], At[m][k], acc[ai][bj][m][n], 0, 0, 0); __builtin_amdgcn_s_setprio(0); } while (0)
; #define PG8_WAIT_V(n) asm volatile("s_waitcnt vmcnt(" #n ")" ::: "memory")
; #define PG8_WAIT_L(n) asm volatile("s_waitcnt lgkmcnt(" #n ")" ::: "memory")
; #define PG8_BAR __builtin_amdgcn_s_barrier()
; #define PG8_SCHED __builtin_amdgcn_sched_barrier(0)
; template <class Epi, class Sched>
; __device__ __forceinline__ void gemm_phase(LAS unsigned char* lds, const Gemm g, const Sched& S, const Epi& E) {
;     ...
;       PG8_STAGE(PG8_SB(0, 1), b2 + hstep, voffB);
;       PG8_WAIT_V(6); PG8_BAR; PG8_MMA(1, 1, At, B1); PG8_BAR;
;       PG8_LDB(B0, 1, 0); PG8_SCHED; PG8_LDA(At, 1, 0); PG8_STAGE(PG8_SA(0, 1), a2 + hstep, voffA);
;       PG8_WAIT_L(8); PG8_BAR; PG8_WAIT_L(0); PG8_MMA(0, 0, At, B0); PG8_BAR; PG8_SCHED;
;       PG8_LDB(B1, 1, 1); PG8_STAGE(PG8_SB(1, 0), b3, voffB);
	v_mfma_f32_16x16x32_bf16 v[52:55], v[208:211], v[144:147], v[52:55]
	v_mfma_f32_16x16x32_bf16 v[48:51], v[232:235], v[144:147], v[48:51]
	v_mfma_f32_16x16x32_bf16 v[36:39], v[208:211], v[152:155], v[36:39]
	v_mfma_f32_16x16x32_bf16 v[32:35], v[232:235], v[152:155], v[32:35]
	v_mfma_f32_16x16x32_bf16 v[20:23], v[208:211], v[190:193], v[20:23]
	v_mfma_f32_16x16x32_bf16 v[16:19], v[232:235], v[190:193], v[16:19]
	v_mfma_f32_16x16x32_bf16 v[4:7], v[208:211], v[198:201], v[4:7]
	v_mfma_f32_16x16x32_bf16 v[0:3], v[232:235], v[198:201], v[0:3]
	v_mfma_f32_16x16x32_bf16 v[52:55], v[226:229], v[148:151], v[52:55]
	v_mfma_f32_16x16x32_bf16 v[48:51], v[236:239], v[148:151], v[48:51]
	v_mfma_f32_16x16x32_bf16 v[36:39], v[226:229], v[186:189], v[36:39]
	v_mfma_f32_16x16x32_bf16 v[32:35], v[236:239], v[186:189], v[32:35]
	v_mfma_f32_16x16x32_bf16 v[20:23], v[226:229], v[194:197], v[20:23]
	v_mfma_f32_16x16x32_bf16 v[16:19], v[236:239], v[194:197], v[16:19]
	v_mfma_f32_16x16x32_bf16 v[4:7], v[226:229], v[204:207], v[4:7]
	v_mfma_f32_16x16x32_bf16 v[0:3], v[236:239], v[204:207], v[0:3]
	s_add_i32 s72, 0, 0x18000
	v_add_u32_e32 v140, s72, v202
	s_barrier
	ds_read_b128 v[128:131], v140
	ds_read_b128 v[132:135], v140 offset:1024
	ds_read_b128 v[136:139], v140 offset:2048
	ds_read_b128 v[140:143], v140 offset:3072
	s_add_u32 s34, vcc_lo, 0xb0000
	s_addc_u32 s35, vcc_hi, 0
	s_mov_b32 m0, s63
	ds_read_b128 v[144:147], v203 offset:32768
	ds_read_b128 v[148:151], v203 offset:33792
	ds_read_b128 v[152:155], v203 offset:34816
	ds_read_b128 v[186:189], v203 offset:35840
	ds_read_b128 v[190:193], v203 offset:36864
	ds_read_b128 v[194:197], v203 offset:37888
	ds_read_b128 v[198:201], v203 offset:38912
	ds_read_b128 v[204:207], v203 offset:39936
	global_load_lds_dwordx4 v176, s[34:35]
	s_mov_b32 m0, s64
	s_nop 0
	global_load_lds_dwordx4 v158, s[34:35]
	s_waitcnt lgkmcnt(8)
	s_barrier
	s_waitcnt lgkmcnt(0)
	s_waitcnt lgkmcnt(0)
	v_mfma_f32_16x16x32_bf16 v[124:127], v[128:131], v[144:147], v[124:127]
	v_mfma_f32_16x16x32_bf16 v[120:123], v[136:139], v[144:147], v[120:123]
	v_mfma_f32_16x16x32_bf16 v[108:111], v[128:131], v[152:155], v[108:111]
	v_mfma_f32_16x16x32_bf16 v[104:107], v[136:139], v[152:155], v[104:107]
	v_mfma_f32_16x16x32_bf16 v[92:95], v[128:131], v[190:193], v[92:95]
	v_mfma_f32_16x16x32_bf16 v[88:91], v[136:139], v[190:193], v[88:91]
	v_mfma_f32_16x16x32_bf16 v[76:79], v[128:131], v[198:201], v[76:79]
	v_mfma_f32_16x16x32_bf16 v[72:75], v[136:139], v[198:201], v[72:75]
	v_mfma_f32_16x16x32_bf16 v[124:127], v[132:135], v[148:151], v[124:127]
	v_mfma_f32_16x16x32_bf16 v[120:123], v[140:143], v[148:151], v[120:123]
	v_mfma_f32_16x16x32_bf16 v[108:111], v[132:135], v[186:189], v[108:111]
	v_mfma_f32_16x16x32_bf16 v[104:107], v[140:143], v[186:189], v[104:107]
	v_mfma_f32_16x16x32_bf16 v[92:95], v[132:135], v[194:197], v[92:95]
	v_mfma_f32_16x16x32_bf16 v[88:91], v[140:143], v[194:197], v[88:91]
	v_mfma_f32_16x16x32_bf16 v[76:79], v[132:135], v[204:207], v[76:79]
	v_mfma_f32_16x16x32_bf16 v[72:75], v[140:143], v[204:207], v[72:75]
	s_barrier
	s_add_i32 s73, 0, 0x1c000
	s_add_i32 s34, s72, s7
	v_add_u32_e32 v160, s73, v202
	s_add_u32 s66, s44, s80
	s_addc_u32 s67, s45, s81
	s_mov_b32 m0, s34
	ds_read_b128 v[208:211], v160
	ds_read_b128 v[226:229], v160 offset:1024
	ds_read_b128 v[232:235], v160 offset:2048
	ds_read_b128 v[236:239], v160 offset:3072
	global_load_lds_dwordx4 v174, s[66:67]
	s_add_i32 m0, s34, 0x2000
	s_nop 0
	global_load_lds_dwordx4 v156, s[66:67]
	s_barrier
; #define PG8_STAGE(bufoff, gbase, voff) do { _Pragma("unroll") for (int _i = 0; _i < 2; ++_i) \
;     __builtin_amdgcn_global_load_lds((const unsigned*)((const char*)(gbase) + (voff)[_i]), (LAS unsigned*)(lds + (bufoff) + ldsw + _i * 8192), 16, 0, 0); } while (0)
; #define PG8_LDA(dst, b, h) do { _Pragma("unroll") for (int m = 0; m < 4; ++m) _Pragma("unroll") for (int k = 0; k < 2; ++k) dst[m][k] = *(const LAS bf16x8*)(lds + PG8_SA(b, h) + aoff + m * 2048 + k * 1024); } while (0)
; #define PG8_MMA(ai, bj, At, Bt) do { __builtin_amdgcn_s_setprio(1); _Pragma("unroll") for (int m = 0; m < 4; ++m) _Pragma("unroll") for (int n = 0; n < 2; ++n) _Pragma("unroll") for (int k = 0; k < 2; ++k) \
;     acc[ai][bj][m][n] = __builtin_amdgcn_mfma_f32_16x16x32_bf16(Bt[n][k], At[m][k], acc[ai][bj][m][n], 0, 0, 0); __builtin_amdgcn_s_setprio(0); } while (0)
; #define PG8_WAIT_V(n) asm volatile("s_waitcnt vmcnt(" #n ")" ::: "memory")
; #define PG8_WAIT_L(n) asm volatile("s_waitcnt lgkmcnt(" #n ")" ::: "memory")
; #define PG8_BAR __builtin_amdgcn_s_barrier()
; #define PG8_SCHED __builtin_amdgcn_sched_barrier(0)
; template <class Epi, class Sched>
; __device__ __forceinline__ void gemm_phase(LAS unsigned char* lds, const Gemm g, const Sched& S, const Epi& E) {
;     ...
;       PG8_BAR; PG8_WAIT_L(0); PG8_MMA(0, 1, At, B1); PG8_BAR;
;       PG8_LDA(At, 1, 1); PG8_STAGE(PG8_SA(1, 0), a3, voffA);
;       PG8_BAR; PG8_WAIT_L(0); PG8_MMA(1, 0, At, B0); PG8_BAR; PG8_SCHED;
;       PG8_STAGE(PG8_SB(1, 1), b3 + hstep, voffB);
;       PG8_WAIT_V(6); PG8_BAR; PG8_MMA(1, 1, At, B1); PG8_BAR;
;     }
	s_waitcnt lgkmcnt(0)
	s_waitcnt lgkmcnt(0)
	v_mfma_f32_16x16x32_bf16 v[116:119], v[208:211], v[144:147], v[116:119]
	v_mfma_f32_16x16x32_bf16 v[112:115], v[232:235], v[144:147], v[112:115]
	v_mfma_f32_16x16x32_bf16 v[100:103], v[208:211], v[152:155], v[100:103]
	v_mfma_f32_16x16x32_bf16 v[96:99], v[232:235], v[152:155], v[96:99]
	v_mfma_f32_16x16x32_bf16 v[84:87], v[208:211], v[190:193], v[84:87]
	v_mfma_f32_16x16x32_bf16 v[80:83], v[232:235], v[190:193], v[80:83]
	v_mfma_f32_16x16x32_bf16 v[68:71], v[208:211], v[198:201], v[68:71]
	v_mfma_f32_16x16x32_bf16 v[64:67], v[232:235], v[198:201], v[64:67]
	v_mfma_f32_16x16x32_bf16 v[116:119], v[226:229], v[148:151], v[116:119]
	v_mfma_f32_16x16x32_bf16 v[112:115], v[236:239], v[148:151], v[112:115]
	v_mfma_f32_16x16x32_bf16 v[100:103], v[226:229], v[186:189], v[100:103]
	v_mfma_f32_16x16x32_bf16 v[96:99], v[236:239], v[186:189], v[96:99]
	v_mfma_f32_16x16x32_bf16 v[84:87], v[226:229], v[194:197], v[84:87]
	v_mfma_f32_16x16x32_bf16 v[80:83], v[236:239], v[194:197], v[80:83]
	v_mfma_f32_16x16x32_bf16 v[68:71], v[226:229], v[204:207], v[68:71]
	v_mfma_f32_16x16x32_bf16 v[64:67], v[236:239], v[204:207], v[64:67]
	s_mov_b32 m0, s65
	s_add_u32 s74, vcc_lo, s80
	s_addc_u32 s75, vcc_hi, s81
	s_barrier
	ds_read_b128 v[144:147], v203 offset:49152
	ds_read_b128 v[148:151], v203 offset:50176
	ds_read_b128 v[152:155], v203 offset:51200
	ds_read_b128 v[186:189], v203 offset:52224
	ds_read_b128 v[190:193], v203 offset:53248
	ds_read_b128 v[194:197], v203 offset:54272
	ds_read_b128 v[198:201], v203 offset:55296
	ds_read_b128 v[204:207], v203 offset:56320
	global_load_lds_dwordx4 v176, s[74:75]
	s_mov_b32 m0, s70
	s_nop 0
	global_load_lds_dwordx4 v158, s[74:75]
	s_barrier
	s_waitcnt lgkmcnt(0)
	s_waitcnt lgkmcnt(0)
	v_mfma_f32_16x16x32_bf16 v[60:63], v[128:131], v[144:147], v[60:63]
	v_mfma_f32_16x16x32_bf16 v[56:59], v[136:139], v[144:147], v[56:59]
	v_mfma_f32_16x16x32_bf16 v[44:47], v[128:131], v[152:155], v[44:47]
	v_mfma_f32_16x16x32_bf16 v[40:43], v[136:139], v[152:155], v[40:43]
	v_mfma_f32_16x16x32_bf16 v[28:31], v[128:131], v[190:193], v[28:31]
	v_mfma_f32_16x16x32_bf16 v[24:27], v[136:139], v[190:193], v[24:27]
	v_mfma_f32_16x16x32_bf16 v[12:15], v[128:131], v[198:201], v[12:15]
	v_mfma_f32_16x16x32_bf16 v[8:11], v[136:139], v[198:201], v[8:11]
	v_mfma_f32_16x16x32_bf16 v[60:63], v[132:135], v[148:151], v[60:63]
	v_mfma_f32_16x16x32_bf16 v[56:59], v[140:143], v[148:151], v[56:59]
	v_mfma_f32_16x16x32_bf16 v[44:47], v[132:135], v[186:189], v[44:47]
	v_mfma_f32_16x16x32_bf16 v[40:43], v[140:143], v[186:189], v[40:43]
	v_mfma_f32_16x16x32_bf16 v[28:31], v[132:135], v[194:197], v[28:31]
	v_mfma_f32_16x16x32_bf16 v[24:27], v[140:143], v[194:197], v[24:27]
	v_mfma_f32_16x16x32_bf16 v[12:15], v[132:135], v[204:207], v[12:15]
	v_mfma_f32_16x16x32_bf16 v[8:11], v[140:143], v[204:207], v[8:11]
	s_barrier
	s_add_u32 s34, s44, 0xb0080
	s_addc_u32 s35, s45, 0
	s_add_i32 s44, s73, s7
	s_mov_b32 m0, s44
	s_nop 0
	global_load_lds_dwordx4 v174, s[34:35]
	s_add_i32 m0, s44, 0x2000
	s_nop 0
	global_load_lds_dwordx4 v156, s[34:35]
	s_waitcnt vmcnt(6)
	s_barrier
	v_mfma_f32_16x16x32_bf16 v[52:55], v[208:211], v[144:147], v[52:55]
	v_mfma_f32_16x16x32_bf16 v[48:51], v[232:235], v[144:147], v[48:51]
	v_mfma_f32_16x16x32_bf16 v[36:39], v[208:211], v[152:155], v[36:39]
	v_mfma_f32_16x16x32_bf16 v[32:35], v[232:235], v[152:155], v[32:35]
	v_mfma_f32_16x16x32_bf16 v[20:23], v[208:211], v[190:193], v[20:23]
	v_mfma_f32_16x16x32_bf16 v[16:19], v[232:235], v[190:193], v[16:19]
	v_mfma_f32_16x16x32_bf16 v[4:7], v[208:211], v[198:201], v[4:7]
	v_mfma_f32_16x16x32_bf16 v[0:3], v[232:235], v[198:201], v[0:3]
	v_mfma_f32_16x16x32_bf16 v[52:55], v[226:229], v[148:151], v[52:55]
	v_mfma_f32_16x16x32_bf16 v[48:51], v[236:239], v[148:151], v[48:51]
	v_mfma_f32_16x16x32_bf16 v[36:39], v[226:229], v[186:189], v[36:39]
	v_mfma_f32_16x16x32_bf16 v[32:35], v[236:239], v[186:189], v[32:35]
	v_mfma_f32_16x16x32_bf16 v[20:23], v[226:229], v[194:197], v[20:23]
	v_mfma_f32_16x16x32_bf16 v[16:19], v[236:239], v[194:197], v[16:19]
	v_mfma_f32_16x16x32_bf16 v[4:7], v[226:229], v[204:207], v[4:7]
	v_mfma_f32_16x16x32_bf16 v[0:3], v[236:239], v[204:207], v[0:3]
	s_add_i32 s52, s52, 2
	s_add_u32 s48, s48, 0x100
	s_addc_u32 s49, s49, 0
	s_cmp_gt_u32 s52, 41
	s_mov_b64 s[34:35], s[42:43]
	s_barrier
	s_cbranch_scc0 .LBB0_281
	s_cmp_lt_u32 s101, 0x100
	s_cbranch_scc0 .Lxa_1
	s_barrier

; #define PG8_STAGE(bufoff, gbase, voff) do { _Pragma("unroll") for (int _i = 0; _i < 2; ++_i) \
;     __builtin_amdgcn_global_load_lds((const unsigned*)((const char*)(gbase) + (voff)[_i]), (LAS unsigned*)(lds + (bufoff) + ldsw + _i * 8192), 16, 0, 0); } while (0)
; #define PG8_LDA(dst, b, h) do { _Pragma("unroll") for (int m = 0; m < 4; ++m) _Pragma("unroll") for (int k = 0; k < 2; ++k) dst[m][k] = *(const LAS bf16x8*)(lds + PG8_SA(b, h) + aoff + m * 2048 + k * 1024); } while (0)
; #define PG8_LDB(dst, b, h) do { _Pragma("unroll") for (int n = 0; n < 2; ++n) _Pragma("unroll") for (int k = 0; k < 2; ++k) dst[n][k] = *(const LAS bf16x8*)(lds + PG8_SB(b, h) + boff + n * 2048 + k * 1024); } while (0)
; #define PG8_MMA(ai, bj, At, Bt) do { __builtin_amdgcn_s_setprio(1); _Pragma("unroll") for (int m = 0; m < 4; ++m) _Pragma("unroll") for (int n = 0; n < 2; ++n) _Pragma("unroll") for (int k = 0; k < 2; ++k) \
;     acc[ai][bj][m][n] = __builtin_amdgcn_mfma_f32_16x16x32_bf16(Bt[n][k], At[m][k], acc[ai][bj][m][n], 0, 0, 0); __builtin_amdgcn_s_setprio(0); } while (0)
; #define PG8_WAIT_L(n) asm volatile("s_waitcnt lgkmcnt(" #n ")" ::: "memory")
; #define PG8_BAR __builtin_amdgcn_s_barrier()
; #define PG8_SCHED __builtin_amdgcn_sched_barrier(0)
; template <class Epi, class Sched>
; __device__ __forceinline__ void gemm_phase(LAS unsigned char* lds, const Gemm g, const Sched& S, const Epi& E) {
;     ...
;       const bool last = (t == nt - 2);
;       const char* a1 = cA + (size_t)(t + 1) * kstep;
;       const char* a2 = last ? nA : cA + (size_t)(t + 2) * kstep; const char* b2 = last ? nB : cB + (size_t)(t + 2) * kstep;
;       const char* a3 = a2 + kstep; const char* b3 = b2 + kstep;
;       if (last && has_next) S.a_ready(nxt);
;       PG8_LDB(B0, 0, 0); PG8_SCHED; PG8_LDA(At, 0, 0); PG8_STAGE(PG8_SA(1, 1), a1 + hstep, voffA);
;       PG8_WAIT_L(8); PG8_BAR; PG8_WAIT_L(0); PG8_MMA(0, 0, At, B0); PG8_BAR; PG8_SCHED;
;       PG8_LDB(B1, 0, 1); PG8_STAGE(PG8_SB(0, 0), b2, voffB);
;       PG8_BAR; PG8_WAIT_L(0); PG8_MMA(0, 1, At, B1); PG8_BAR;
;       PG8_LDA(At, 0, 1); PG8_STAGE(PG8_SA(0, 0), a2, voffA);
;       PG8_BAR; PG8_WAIT_L(0); PG8_MMA(1, 0, At, B0); PG8_BAR; PG8_SCHED;
.Lxs_e2:
.LBB0_367:
	s_add_u32 s44, s34, 0xfffc0080
	s_addc_u32 s45, s35, -1
	s_add_i32 s73, 0, 0x10000
	v_add_u32_e32 v140, s73, v183
	ds_read_b128 v[128:131], v140
	ds_read_b128 v[132:135], v140 offset:1024
	ds_read_b128 v[136:139], v140 offset:2048
	ds_read_b128 v[140:143], v140 offset:3072
	s_cmp_eq_u32 s72, 12
	s_cselect_b32 vcc_hi, s37, s45
	s_cselect_b32 vcc_lo, s70, s44
	s_cselect_b32 s45, s23, s52
	s_cselect_b32 s44, s71, s6
	s_add_i32 m0, s12, 0xc000
	ds_read_b128 v[174:177], v185
	ds_read_b128 v[178:181], v185 offset:1024
	ds_read_b128 v[186:189], v185 offset:2048
	ds_read_b128 v[190:193], v185 offset:3072
	ds_read_b128 v[194:197], v185 offset:4096
	ds_read_b128 v[198:201], v185 offset:5120
	ds_read_b128 v[202:205], v185 offset:6144
	ds_read_b128 v[206:209], v185 offset:7168
	global_load_lds_dwordx4 v154, s[34:35]
	s_add_i32 m0, s12, 0xe000
	s_nop 0
	global_load_lds_dwordx4 v156, s[34:35]
	s_waitcnt lgkmcnt(8)
	s_barrier
	s_waitcnt lgkmcnt(0)
	s_waitcnt lgkmcnt(0)
	v_mfma_f32_16x16x32_bf16 v[124:127], v[128:131], v[174:177], v[124:127]
	v_mfma_f32_16x16x32_bf16 v[120:123], v[136:139], v[174:177], v[120:123]
	v_mfma_f32_16x16x32_bf16 v[116:119], v[128:131], v[186:189], v[116:119]
	v_mfma_f32_16x16x32_bf16 v[108:111], v[136:139], v[186:189], v[108:111]
	v_mfma_f32_16x16x32_bf16 v[96:99], v[128:131], v[194:197], v[96:99]
	v_mfma_f32_16x16x32_bf16 v[88:91], v[136:139], v[194:197], v[88:91]
	v_mfma_f32_16x16x32_bf16 v[84:87], v[128:131], v[202:205], v[84:87]
	v_mfma_f32_16x16x32_bf16 v[76:79], v[136:139], v[202:205], v[76:79]
	v_mfma_f32_16x16x32_bf16 v[124:127], v[132:135], v[178:181], v[124:127]
	v_mfma_f32_16x16x32_bf16 v[120:123], v[140:143], v[178:181], v[120:123]
	v_mfma_f32_16x16x32_bf16 v[116:119], v[132:135], v[190:193], v[116:119]
	v_mfma_f32_16x16x32_bf16 v[108:111], v[140:143], v[190:193], v[108:111]
	v_mfma_f32_16x16x32_bf16 v[96:99], v[132:135], v[198:201], v[96:99]
	v_mfma_f32_16x16x32_bf16 v[88:91], v[140:143], v[198:201], v[88:91]
	v_mfma_f32_16x16x32_bf16 v[84:87], v[132:135], v[206:209], v[84:87]
	v_mfma_f32_16x16x32_bf16 v[76:79], v[140:143], v[206:209], v[76:79]
	s_barrier
	s_add_i32 s76, 0, 0x14000
	s_add_i32 s73, s73, s7
	v_add_u32_e32 v159, s76, v183
	s_mov_b32 m0, s73
	ds_read_b128 v[210:213], v159
	ds_read_b128 v[226:229], v159 offset:1024
	ds_read_b128 v[232:235], v159 offset:2048
	ds_read_b128 v[236:239], v159 offset:3072
	global_load_lds_dwordx4 v148, s[44:45]
	s_add_i32 m0, s73, 0x2000
	s_nop 0
	global_load_lds_dwordx4 v144, s[44:45]
	s_barrier
	s_waitcnt lgkmcnt(0)
	s_waitcnt lgkmcnt(0)
	v_mfma_f32_16x16x32_bf16 v[112:115], v[210:213], v[174:177], v[112:115]
	v_mfma_f32_16x16x32_bf16 v[104:107], v[232:235], v[174:177], v[104:107]
	v_mfma_f32_16x16x32_bf16 v[100:103], v[210:213], v[186:189], v[100:103]
	v_mfma_f32_16x16x32_bf16 v[92:95], v[232:235], v[186:189], v[92:95]
	v_mfma_f32_16x16x32_bf16 v[80:83], v[210:213], v[194:197], v[80:83]
	v_mfma_f32_16x16x32_bf16 v[72:75], v[232:235], v[194:197], v[72:75]
	v_mfma_f32_16x16x32_bf16 v[68:71], v[210:213], v[202:205], v[68:71]
	v_mfma_f32_16x16x32_bf16 v[64:67], v[232:235], v[202:205], v[64:67]
	v_mfma_f32_16x16x32_bf16 v[112:115], v[226:229], v[178:181], v[112:115]
	v_mfma_f32_16x16x32_bf16 v[104:107], v[236:239], v[178:181], v[104:107]
	v_mfma_f32_16x16x32_bf16 v[100:103], v[226:229], v[190:193], v[100:103]
	v_mfma_f32_16x16x32_bf16 v[92:95], v[236:239], v[190:193], v[92:95]
	v_mfma_f32_16x16x32_bf16 v[80:83], v[226:229], v[198:201], v[80:83]
	v_mfma_f32_16x16x32_bf16 v[72:75], v[236:239], v[198:201], v[72:75]
	v_mfma_f32_16x16x32_bf16 v[68:71], v[226:229], v[206:209], v[68:71]
	v_mfma_f32_16x16x32_bf16 v[64:67], v[236:239], v[206:209], v[64:67]
	s_mov_b32 m0, s12
	s_barrier
	ds_read_b128 v[174:177], v185 offset:16384
	ds_read_b128 v[178:181], v185 offset:17408
	ds_read_b128 v[186:189], v185 offset:18432
	ds_read_b128 v[190:193], v185 offset:19456
	ds_read_b128 v[194:197], v185 offset:20480
	ds_read_b128 v[198:201], v185 offset:21504
	ds_read_b128 v[202:205], v185 offset:22528
	ds_read_b128 v[206:209], v185 offset:23552
	global_load_lds_dwordx4 v150, vcc
	s_mov_b32 m0, s13
	s_nop 0
	global_load_lds_dwordx4 v146, vcc
	s_barrier
	s_waitcnt lgkmcnt(0)
	s_waitcnt lgkmcnt(0)
	v_mfma_f32_16x16x32_bf16 v[60:63], v[128:131], v[174:177], v[60:63]
	v_mfma_f32_16x16x32_bf16 v[56:59], v[136:139], v[174:177], v[56:59]
	v_mfma_f32_16x16x32_bf16 v[52:55], v[128:131], v[186:189], v[52:55]
	v_mfma_f32_16x16x32_bf16 v[44:47], v[136:139], v[186:189], v[44:47]
	v_mfma_f32_16x16x32_bf16 v[32:35], v[128:131], v[194:197], v[32:35]
	v_mfma_f32_16x16x32_bf16 v[24:27], v[136:139], v[194:197], v[24:27]
	v_mfma_f32_16x16x32_bf16 v[20:23], v[128:131], v[202:205], v[20:23]
	v_mfma_f32_16x16x32_bf16 v[12:15], v[136:139], v[202:205], v[12:15]
	v_mfma_f32_16x16x32_bf16 v[60:63], v[132:135], v[178:181], v[60:63]
	v_mfma_f32_16x16x32_bf16 v[56:59], v[140:143], v[178:181], v[56:59]
	v_mfma_f32_16x16x32_bf16 v[52:55], v[132:135], v[190:193], v[52:55]
	v_mfma_f32_16x16x32_bf16 v[44:47], v[140:143], v[190:193], v[44:47]
	v_mfma_f32_16x16x32_bf16 v[32:35], v[132:135], v[198:201], v[32:35]
	v_mfma_f32_16x16x32_bf16 v[24:27], v[140:143], v[198:201], v[24:27]
	v_mfma_f32_16x16x32_bf16 v[20:23], v[132:135], v[206:209], v[20:23]
	v_mfma_f32_16x16x32_bf16 v[12:15], v[140:143], v[206:209], v[12:15]
	s_barrier
	s_add_u32 s74, s44, 0x40000
	s_addc_u32 s75, s45, 0
	s_add_i32 s73, s76, s7
	s_mov_b32 m0, s73
	s_nop 0
	global_load_lds_dwordx4 v148, s[74:75]
	s_add_i32 m0, s73, 0x2000
	s_nop 0
	global_load_lds_dwordx4 v144, s[74:75]
	s_waitcnt vmcnt(6)
	s_barrier
; #define PG8_STAGE(bufoff, gbase, voff) do { _Pragma("unroll") for (int _i = 0; _i < 2; ++_i) \
;     __builtin_amdgcn_global_load_lds((const unsigned*)((const char*)(gbase) + (voff)[_i]), (LAS unsigned*)(lds + (bufoff) + ldsw + _i * 8192), 16, 0, 0); } while (0)
; #define PG8_LDA(dst, b, h) do { _Pragma("unroll") for (int m = 0; m < 4; ++m) _Pragma("unroll") for (int k = 0; k < 2; ++k) dst[m][k] = *(const LAS bf16x8*)(lds + PG8_SA(b, h) + aoff + m * 2048 + k * 1024); } while (0)
; #define PG8_LDB(dst, b, h) do { _Pragma("unroll") for (int n = 0; n < 2; ++n) _Pragma("unroll") for (int k = 0; k < 2; ++k) dst[n][k] = *(const LAS bf16x8*)(lds + PG8_SB(b, h) + boff + n * 2048 + k * 1024); } while (0)
; #define PG8_MMA(ai, bj, At, Bt) do { __builtin_amdgcn_s_setprio(1); _Pragma("unroll") for (int m = 0; m < 4; ++m) _Pragma("unroll") for (int n = 0; n < 2; ++n) _Pragma("unroll") for (int k = 0; k < 2; ++k) \
;     acc[ai][bj][m][n] = __builtin_amdgcn_mfma_f32_16x16x32_bf16(Bt[n][k], At[m][k], acc[ai][bj][m][n], 0, 0, 0); __builtin_amdgcn_s_setprio(0); } while (0)
; #define PG8_WAIT_V(n) asm volatile("s_waitcnt vmcnt(" #n ")" ::: "memory")
; #define PG8_WAIT_L(n) asm volatile("s_waitcnt lgkmcnt(" #n ")" ::: "memory")
; #define PG8_BAR __builtin_amdgcn_s_barrier()
; #define PG8_SCHED __builtin_amdgcn_sched_barrier(0)
; template <class Epi, class Sched>
; __device__ __forceinline__ void gemm_phase(LAS unsigned char* lds, const Gemm g, const Sched& S, const Epi& E) {
;     ...
;       PG8_WAIT_V(6); PG8_BAR; PG8_MMA(1, 1, At, B1); PG8_BAR;
;       PG8_LDB(B0, 1, 0); PG8_SCHED; PG8_LDA(At, 1, 0); PG8_STAGE(PG8_SA(0, 1), a2 + hstep, voffA);
;       PG8_WAIT_L(8); PG8_BAR; PG8_WAIT_L(0); PG8_MMA(0, 0, At, B0); PG8_BAR; PG8_SCHED;
;       PG8_LDB(B1, 1, 1); PG8_STAGE(PG8_SB(1, 0), b3, voffB);
	v_mfma_f32_16x16x32_bf16 v[48:51], v[210:213], v[174:177], v[48:51]
	v_mfma_f32_16x16x32_bf16 v[40:43], v[232:235], v[174:177], v[40:43]
	v_mfma_f32_16x16x32_bf16 v[36:39], v[210:213], v[186:189], v[36:39]
	v_mfma_f32_16x16x32_bf16 v[28:31], v[232:235], v[186:189], v[28:31]
	v_mfma_f32_16x16x32_bf16 v[16:19], v[210:213], v[194:197], v[16:19]
	v_mfma_f32_16x16x32_bf16 v[8:11], v[232:235], v[194:197], v[8:11]
	v_mfma_f32_16x16x32_bf16 v[4:7], v[210:213], v[202:205], v[4:7]
	v_mfma_f32_16x16x32_bf16 v[0:3], v[232:235], v[202:205], v[0:3]
	v_mfma_f32_16x16x32_bf16 v[48:51], v[226:229], v[178:181], v[48:51]
	v_mfma_f32_16x16x32_bf16 v[40:43], v[236:239], v[178:181], v[40:43]
	v_mfma_f32_16x16x32_bf16 v[36:39], v[226:229], v[190:193], v[36:39]
	v_mfma_f32_16x16x32_bf16 v[28:31], v[236:239], v[190:193], v[28:31]
	v_mfma_f32_16x16x32_bf16 v[16:19], v[226:229], v[198:201], v[16:19]
	v_mfma_f32_16x16x32_bf16 v[8:11], v[236:239], v[198:201], v[8:11]
	v_mfma_f32_16x16x32_bf16 v[4:7], v[226:229], v[206:209], v[4:7]
	v_mfma_f32_16x16x32_bf16 v[0:3], v[236:239], v[206:209], v[0:3]
	s_add_i32 s73, 0, 0x18000
	v_add_u32_e32 v140, s73, v183
	s_barrier
	ds_read_b128 v[128:131], v140
	ds_read_b128 v[132:135], v140 offset:1024
	ds_read_b128 v[136:139], v140 offset:2048
	ds_read_b128 v[140:143], v140 offset:3072
	s_add_u32 s74, vcc_lo, 0x40000
	s_addc_u32 s75, vcc_hi, 0
	s_mov_b32 m0, s20
	ds_read_b128 v[174:177], v185 offset:32768
	ds_read_b128 v[178:181], v185 offset:33792
	ds_read_b128 v[186:189], v185 offset:34816
	ds_read_b128 v[190:193], v185 offset:35840
	ds_read_b128 v[194:197], v185 offset:36864
	ds_read_b128 v[198:201], v185 offset:37888
	ds_read_b128 v[202:205], v185 offset:38912
	ds_read_b128 v[206:209], v185 offset:39936
	global_load_lds_dwordx4 v150, s[74:75]
	s_mov_b32 m0, s48
	s_nop 0
	global_load_lds_dwordx4 v146, s[74:75]
	s_waitcnt lgkmcnt(8)
	s_barrier
	s_waitcnt lgkmcnt(0)
	s_waitcnt lgkmcnt(0)
	v_mfma_f32_16x16x32_bf16 v[124:127], v[128:131], v[174:177], v[124:127]
	v_mfma_f32_16x16x32_bf16 v[120:123], v[136:139], v[174:177], v[120:123]
	v_mfma_f32_16x16x32_bf16 v[116:119], v[128:131], v[186:189], v[116:119]
	v_mfma_f32_16x16x32_bf16 v[108:111], v[136:139], v[186:189], v[108:111]
	v_mfma_f32_16x16x32_bf16 v[96:99], v[128:131], v[194:197], v[96:99]
	v_mfma_f32_16x16x32_bf16 v[88:91], v[136:139], v[194:197], v[88:91]
	v_mfma_f32_16x16x32_bf16 v[84:87], v[128:131], v[202:205], v[84:87]
	v_mfma_f32_16x16x32_bf16 v[76:79], v[136:139], v[202:205], v[76:79]
	v_mfma_f32_16x16x32_bf16 v[124:127], v[132:135], v[178:181], v[124:127]
	v_mfma_f32_16x16x32_bf16 v[120:123], v[140:143], v[178:181], v[120:123]
	v_mfma_f32_16x16x32_bf16 v[116:119], v[132:135], v[190:193], v[116:119]
	v_mfma_f32_16x16x32_bf16 v[108:111], v[140:143], v[190:193], v[108:111]
	v_mfma_f32_16x16x32_bf16 v[96:99], v[132:135], v[198:201], v[96:99]
	v_mfma_f32_16x16x32_bf16 v[88:91], v[140:143], v[198:201], v[88:91]
	v_mfma_f32_16x16x32_bf16 v[84:87], v[132:135], v[206:209], v[84:87]
	v_mfma_f32_16x16x32_bf16 v[76:79], v[140:143], v[206:209], v[76:79]
	s_barrier
	s_add_i32 s74, 0, 0x1c000
	s_add_i32 s73, s73, s7
	v_add_u32_e32 v159, s74, v183
	s_add_u32 s60, s44, s80
	s_addc_u32 s61, s45, s81
	s_mov_b32 m0, s73
	ds_read_b128 v[210:213], v159
	ds_read_b128 v[226:229], v159 offset:1024
	ds_read_b128 v[232:235], v159 offset:2048
	ds_read_b128 v[236:239], v159 offset:3072
	global_load_lds_dwordx4 v148, s[60:61]
	s_add_i32 m0, s73, 0x2000
	s_nop 0
	global_load_lds_dwordx4 v144, s[60:61]
	s_barrier
; #define PG8_STAGE(bufoff, gbase, voff) do { _Pragma("unroll") for (int _i = 0; _i < 2; ++_i) \
;     __builtin_amdgcn_global_load_lds((const unsigned*)((const char*)(gbase) + (voff)[_i]), (LAS unsigned*)(lds + (bufoff) + ldsw + _i * 8192), 16, 0, 0); } while (0)
; #define PG8_LDA(dst, b, h) do { _Pragma("unroll") for (int m = 0; m < 4; ++m) _Pragma("unroll") for (int k = 0; k < 2; ++k) dst[m][k] = *(const LAS bf16x8*)(lds + PG8_SA(b, h) + aoff + m * 2048 + k * 1024); } while (0)
; #define PG8_MMA(ai, bj, At, Bt) do { __builtin_amdgcn_s_setprio(1); _Pragma("unroll") for (int m = 0; m < 4; ++m) _Pragma("unroll") for (int n = 0; n < 2; ++n) _Pragma("unroll") for (int k = 0; k < 2; ++k) \
;     acc[ai][bj][m][n] = __builtin_amdgcn_mfma_f32_16x16x32_bf16(Bt[n][k], At[m][k], acc[ai][bj][m][n], 0, 0, 0); __builtin_amdgcn_s_setprio(0); } while (0)
; #define PG8_WAIT_V(n) asm volatile("s_waitcnt vmcnt(" #n ")" ::: "memory")
; #define PG8_WAIT_L(n) asm volatile("s_waitcnt lgkmcnt(" #n ")" ::: "memory")
; #define PG8_BAR __builtin_amdgcn_s_barrier()
; #define PG8_SCHED __builtin_amdgcn_sched_barrier(0)
; template <class Epi, class Sched>
; __device__ __forceinline__ void gemm_phase(LAS unsigned char* lds, const Gemm g, const Sched& S, const Epi& E) {
;     ...
;       PG8_BAR; PG8_WAIT_L(0); PG8_MMA(0, 1, At, B1); PG8_BAR;
;       PG8_LDA(At, 1, 1); PG8_STAGE(PG8_SA(1, 0), a3, voffA);
;       PG8_BAR; PG8_WAIT_L(0); PG8_MMA(1, 0, At, B0); PG8_BAR; PG8_SCHED;
;       PG8_STAGE(PG8_SB(1, 1), b3 + hstep, voffB);
;       PG8_WAIT_V(6); PG8_BAR; PG8_MMA(1, 1, At, B1); PG8_BAR;
;     }
	s_waitcnt lgkmcnt(0)
	s_waitcnt lgkmcnt(0)
	v_mfma_f32_16x16x32_bf16 v[112:115], v[210:213], v[174:177], v[112:115]
	v_mfma_f32_16x16x32_bf16 v[104:107], v[232:235], v[174:177], v[104:107]
	v_mfma_f32_16x16x32_bf16 v[100:103], v[210:213], v[186:189], v[100:103]
	v_mfma_f32_16x16x32_bf16 v[92:95], v[232:235], v[186:189], v[92:95]
	v_mfma_f32_16x16x32_bf16 v[80:83], v[210:213], v[194:197], v[80:83]
	v_mfma_f32_16x16x32_bf16 v[72:75], v[232:235], v[194:197], v[72:75]
	v_mfma_f32_16x16x32_bf16 v[68:71], v[210:213], v[202:205], v[68:71]
	v_mfma_f32_16x16x32_bf16 v[64:67], v[232:235], v[202:205], v[64:67]
	v_mfma_f32_16x16x32_bf16 v[112:115], v[226:229], v[178:181], v[112:115]
	v_mfma_f32_16x16x32_bf16 v[104:107], v[236:239], v[178:181], v[104:107]
	v_mfma_f32_16x16x32_bf16 v[100:103], v[226:229], v[190:193], v[100:103]
	v_mfma_f32_16x16x32_bf16 v[92:95], v[236:239], v[190:193], v[92:95]
	v_mfma_f32_16x16x32_bf16 v[80:83], v[226:229], v[198:201], v[80:83]
	v_mfma_f32_16x16x32_bf16 v[72:75], v[236:239], v[198:201], v[72:75]
	v_mfma_f32_16x16x32_bf16 v[68:71], v[226:229], v[206:209], v[68:71]
	v_mfma_f32_16x16x32_bf16 v[64:67], v[236:239], v[206:209], v[64:67]
	s_mov_b32 m0, s49
	s_add_u32 s98, vcc_lo, s80
	s_addc_u32 s99, vcc_hi, s81
	s_barrier
	ds_read_b128 v[174:177], v185 offset:49152
	ds_read_b128 v[178:181], v185 offset:50176
	ds_read_b128 v[186:189], v185 offset:51200
	ds_read_b128 v[190:193], v185 offset:52224
	ds_read_b128 v[194:197], v185 offset:53248
	ds_read_b128 v[198:201], v185 offset:54272
	ds_read_b128 v[202:205], v185 offset:55296
	ds_read_b128 v[206:209], v185 offset:56320
	global_load_lds_dwordx4 v150, s[98:99]
	s_mov_b32 m0, s51
	s_nop 0
	global_load_lds_dwordx4 v146, s[98:99]
	s_barrier
	s_waitcnt lgkmcnt(0)
	s_waitcnt lgkmcnt(0)
	v_mfma_f32_16x16x32_bf16 v[60:63], v[128:131], v[174:177], v[60:63]
	v_mfma_f32_16x16x32_bf16 v[56:59], v[136:139], v[174:177], v[56:59]
	v_mfma_f32_16x16x32_bf16 v[52:55], v[128:131], v[186:189], v[52:55]
	v_mfma_f32_16x16x32_bf16 v[44:47], v[136:139], v[186:189], v[44:47]
	v_mfma_f32_16x16x32_bf16 v[32:35], v[128:131], v[194:197], v[32:35]
	v_mfma_f32_16x16x32_bf16 v[24:27], v[136:139], v[194:197], v[24:27]
	v_mfma_f32_16x16x32_bf16 v[20:23], v[128:131], v[202:205], v[20:23]
	v_mfma_f32_16x16x32_bf16 v[12:15], v[136:139], v[202:205], v[12:15]
	v_mfma_f32_16x16x32_bf16 v[60:63], v[132:135], v[178:181], v[60:63]
	v_mfma_f32_16x16x32_bf16 v[56:59], v[140:143], v[178:181], v[56:59]
	v_mfma_f32_16x16x32_bf16 v[52:55], v[132:135], v[190:193], v[52:55]
	v_mfma_f32_16x16x32_bf16 v[44:47], v[140:143], v[190:193], v[44:47]
	v_mfma_f32_16x16x32_bf16 v[32:35], v[132:135], v[198:201], v[32:35]
	v_mfma_f32_16x16x32_bf16 v[24:27], v[140:143], v[198:201], v[24:27]
	v_mfma_f32_16x16x32_bf16 v[20:23], v[132:135], v[206:209], v[20:23]
	v_mfma_f32_16x16x32_bf16 v[12:15], v[140:143], v[206:209], v[12:15]
	s_barrier
	s_add_u32 s44, s44, 0x40080
	s_addc_u32 s45, s45, 0
	s_add_i32 s73, s74, s7
	s_mov_b32 m0, s73
	s_nop 0
	global_load_lds_dwordx4 v148, s[44:45]
	s_add_i32 m0, s73, 0x2000
	s_nop 0
	global_load_lds_dwordx4 v144, s[44:45]
	s_waitcnt vmcnt(6)
	s_barrier
	v_mfma_f32_16x16x32_bf16 v[48:51], v[210:213], v[174:177], v[48:51]
	v_mfma_f32_16x16x32_bf16 v[40:43], v[232:235], v[174:177], v[40:43]
	v_mfma_f32_16x16x32_bf16 v[36:39], v[210:213], v[186:189], v[36:39]
	v_mfma_f32_16x16x32_bf16 v[28:31], v[232:235], v[186:189], v[28:31]
	v_mfma_f32_16x16x32_bf16 v[16:19], v[210:213], v[194:197], v[16:19]
	v_mfma_f32_16x16x32_bf16 v[8:11], v[232:235], v[194:197], v[8:11]
	v_mfma_f32_16x16x32_bf16 v[4:7], v[210:213], v[202:205], v[4:7]
	v_mfma_f32_16x16x32_bf16 v[0:3], v[232:235], v[202:205], v[0:3]
	v_mfma_f32_16x16x32_bf16 v[48:51], v[226:229], v[178:181], v[48:51]
	v_mfma_f32_16x16x32_bf16 v[40:43], v[236:239], v[178:181], v[40:43]
	v_mfma_f32_16x16x32_bf16 v[36:39], v[226:229], v[190:193], v[36:39]
	v_mfma_f32_16x16x32_bf16 v[28:31], v[236:239], v[190:193], v[28:31]
	v_mfma_f32_16x16x32_bf16 v[16:19], v[226:229], v[198:201], v[16:19]
	v_mfma_f32_16x16x32_bf16 v[8:11], v[236:239], v[198:201], v[8:11]
	v_mfma_f32_16x16x32_bf16 v[4:7], v[226:229], v[206:209], v[4:7]
	v_mfma_f32_16x16x32_bf16 v[0:3], v[236:239], v[206:209], v[0:3]
	s_add_i32 s72, s72, 2
	s_add_u32 s34, s34, 0x100
	s_addc_u32 s35, s35, 0
	s_add_u32 s6, s6, 0x100
	s_addc_u32 s52, s52, 0
	s_cmp_gt_u32 s72, 13
	s_barrier
	s_cbranch_scc0 .LBB0_367
	s_cmp_lt_u32 s101, 0x100
	s_cbranch_scc0 .Lxa_2
	s_barrier

; #define PG8_STAGE(bufoff, gbase, voff) do { _Pragma("unroll") for (int _i = 0; _i < 2; ++_i) \
;     __builtin_amdgcn_global_load_lds((const unsigned*)((const char*)(gbase) + (voff)[_i]), (LAS unsigned*)(lds + (bufoff) + ldsw + _i * 8192), 16, 0, 0); } while (0)
; #define PG8_LDA(dst, b, h) do { _Pragma("unroll") for (int m = 0; m < 4; ++m) _Pragma("unroll") for (int k = 0; k < 2; ++k) dst[m][k] = *(const LAS bf16x8*)(lds + PG8_SA(b, h) + aoff + m * 2048 + k * 1024); } while (0)
; #define PG8_LDB(dst, b, h) do { _Pragma("unroll") for (int n = 0; n < 2; ++n) _Pragma("unroll") for (int k = 0; k < 2; ++k) dst[n][k] = *(const LAS bf16x8*)(lds + PG8_SB(b, h) + boff + n * 2048 + k * 1024); } while (0)
; #define PG8_MMA(ai, bj, At, Bt) do { __builtin_amdgcn_s_setprio(1); _Pragma("unroll") for (int m = 0; m < 4; ++m) _Pragma("unroll") for (int n = 0; n < 2; ++n) _Pragma("unroll") for (int k = 0; k < 2; ++k) \
;     acc[ai][bj][m][n] = __builtin_amdgcn_mfma_f32_16x16x32_bf16(Bt[n][k], At[m][k], acc[ai][bj][m][n], 0, 0, 0); __builtin_amdgcn_s_setprio(0); } while (0)
; #define PG8_WAIT_L(n) asm volatile("s_waitcnt lgkmcnt(" #n ")" ::: "memory")
; #define PG8_BAR __builtin_amdgcn_s_barrier()
; #define PG8_SCHED __builtin_amdgcn_sched_barrier(0)
; template <class Epi, class Sched>
; __device__ __forceinline__ void gemm_phase(LAS unsigned char* lds, const Gemm g, const Sched& S, const Epi& E) {
;     ...
;       const bool last = (t == nt - 2);
;       const char* a1 = cA + (size_t)(t + 1) * kstep;
;       const char* a2 = last ? nA : cA + (size_t)(t + 2) * kstep; const char* b2 = last ? nB : cB + (size_t)(t + 2) * kstep;
;       const char* a3 = a2 + kstep; const char* b3 = b2 + kstep;
;       if (last && has_next) S.a_ready(nxt);
;       PG8_LDB(B0, 0, 0); PG8_SCHED; PG8_LDA(At, 0, 0); PG8_STAGE(PG8_SA(1, 1), a1 + hstep, voffA);
;       PG8_WAIT_L(8); PG8_BAR; PG8_WAIT_L(0); PG8_MMA(0, 0, At, B0); PG8_BAR; PG8_SCHED;
;       PG8_LDB(B1, 0, 1); PG8_STAGE(PG8_SB(0, 0), b2, voffB);
;       PG8_BAR; PG8_WAIT_L(0); PG8_MMA(0, 1, At, B1); PG8_BAR;
;       PG8_LDA(At, 0, 1); PG8_STAGE(PG8_SA(0, 0), a2, voffA);
;       PG8_BAR; PG8_WAIT_L(0); PG8_MMA(1, 0, At, B0); PG8_BAR; PG8_SCHED;
.Lxs_e3:
.LBB0_707:
	s_add_u32 s48, s34, 0xfffc0080
	s_addc_u32 s49, s35, -1
	s_add_i32 s73, 0, 0x10000
	v_add_u32_e32 v140, s73, v201
	ds_read_b128 v[120:123], v140
	ds_read_b128 v[124:127], v140 offset:1024
	ds_read_b128 v[136:139], v140 offset:2048
	ds_read_b128 v[140:143], v140 offset:3072
	s_cmp_eq_u32 s72, 12
	s_cselect_b32 s49, s20, s49
	s_cselect_b32 s48, s45, s48
	s_cselect_b32 vcc_hi, s43, s52
	s_cselect_b32 vcc_lo, s68, s69
	s_add_i32 m0, s65, 0xc000
	ds_read_b128 v[144:147], v203
	ds_read_b128 v[148:151], v203 offset:1024
	ds_read_b128 v[152:155], v203 offset:2048
	ds_read_b128 v[186:189], v203 offset:3072
	ds_read_b128 v[190:193], v203 offset:4096
	ds_read_b128 v[194:197], v203 offset:5120
	ds_read_b128 v[204:207], v203 offset:6144
	ds_read_b128 v[208:211], v203 offset:7168
	global_load_lds_dwordx4 v182, s[34:35]
	s_add_i32 m0, s65, 0xe000
	s_nop 0
	global_load_lds_dwordx4 v184, s[34:35]
	s_waitcnt lgkmcnt(8)
	s_barrier
	s_waitcnt lgkmcnt(0)
	s_waitcnt lgkmcnt(0)
	v_mfma_f32_16x16x32_bf16 v[132:135], v[120:123], v[144:147], v[132:135]
	v_mfma_f32_16x16x32_bf16 v[128:131], v[136:139], v[144:147], v[128:131]
	v_mfma_f32_16x16x32_bf16 v[108:111], v[120:123], v[152:155], v[108:111]
	v_mfma_f32_16x16x32_bf16 v[104:107], v[136:139], v[152:155], v[104:107]
	v_mfma_f32_16x16x32_bf16 v[92:95], v[120:123], v[190:193], v[92:95]
	v_mfma_f32_16x16x32_bf16 v[88:91], v[136:139], v[190:193], v[88:91]
	v_mfma_f32_16x16x32_bf16 v[76:79], v[120:123], v[204:207], v[76:79]
	v_mfma_f32_16x16x32_bf16 v[72:75], v[136:139], v[204:207], v[72:75]
	v_mfma_f32_16x16x32_bf16 v[132:135], v[124:127], v[148:151], v[132:135]
	v_mfma_f32_16x16x32_bf16 v[128:131], v[140:143], v[148:151], v[128:131]
	v_mfma_f32_16x16x32_bf16 v[108:111], v[124:127], v[186:189], v[108:111]
	v_mfma_f32_16x16x32_bf16 v[104:107], v[140:143], v[186:189], v[104:107]
	v_mfma_f32_16x16x32_bf16 v[92:95], v[124:127], v[194:197], v[92:95]
	v_mfma_f32_16x16x32_bf16 v[88:91], v[140:143], v[194:197], v[88:91]
	v_mfma_f32_16x16x32_bf16 v[76:79], v[124:127], v[208:211], v[76:79]
	v_mfma_f32_16x16x32_bf16 v[72:75], v[140:143], v[208:211], v[72:75]
	s_barrier
	s_add_i32 s76, 0, 0x14000
	s_add_i32 s73, s73, s64
	v_add_u32_e32 v160, s76, v201
	s_mov_b32 m0, s73
	ds_read_b128 v[226:229], v160
	ds_read_b128 v[232:235], v160 offset:1024
	ds_read_b128 v[236:239], v160 offset:2048
	ds_read_b128 v[240:243], v160 offset:3072
	global_load_lds_dwordx4 v174, vcc
	s_add_i32 m0, s73, 0x2000
	s_nop 0
	global_load_lds_dwordx4 v156, vcc
	s_barrier
	s_waitcnt lgkmcnt(0)
	s_waitcnt lgkmcnt(0)
	v_mfma_f32_16x16x32_bf16 v[116:119], v[226:229], v[144:147], v[116:119]
	v_mfma_f32_16x16x32_bf16 v[112:115], v[236:239], v[144:147], v[112:115]
	v_mfma_f32_16x16x32_bf16 v[100:103], v[226:229], v[152:155], v[100:103]
	v_mfma_f32_16x16x32_bf16 v[96:99], v[236:239], v[152:155], v[96:99]
	v_mfma_f32_16x16x32_bf16 v[84:87], v[226:229], v[190:193], v[84:87]
	v_mfma_f32_16x16x32_bf16 v[80:83], v[236:239], v[190:193], v[80:83]
	v_mfma_f32_16x16x32_bf16 v[68:71], v[226:229], v[204:207], v[68:71]
	v_mfma_f32_16x16x32_bf16 v[64:67], v[236:239], v[204:207], v[64:67]
	v_mfma_f32_16x16x32_bf16 v[116:119], v[232:235], v[148:151], v[116:119]
	v_mfma_f32_16x16x32_bf16 v[112:115], v[240:243], v[148:151], v[112:115]
	v_mfma_f32_16x16x32_bf16 v[100:103], v[232:235], v[186:189], v[100:103]
	v_mfma_f32_16x16x32_bf16 v[96:99], v[240:243], v[186:189], v[96:99]
	v_mfma_f32_16x16x32_bf16 v[84:87], v[232:235], v[194:197], v[84:87]
	v_mfma_f32_16x16x32_bf16 v[80:83], v[240:243], v[194:197], v[80:83]
	v_mfma_f32_16x16x32_bf16 v[68:71], v[232:235], v[208:211], v[68:71]
	v_mfma_f32_16x16x32_bf16 v[64:67], v[240:243], v[208:211], v[64:67]
	s_mov_b32 m0, s65
	v_lshl_add_u64 v[222:223], s[48:49], 0, v[176:177]
	s_barrier
	ds_read_b128 v[144:147], v203 offset:16384
	ds_read_b128 v[148:151], v203 offset:17408
	ds_read_b128 v[152:155], v203 offset:18432
	ds_read_b128 v[186:189], v203 offset:19456
	ds_read_b128 v[190:193], v203 offset:20480
	ds_read_b128 v[194:197], v203 offset:21504
	ds_read_b128 v[204:207], v203 offset:22528
	ds_read_b128 v[208:211], v203 offset:23552
	global_load_lds_dwordx4 v176, s[48:49]
	v_lshl_add_u64 v[244:245], s[48:49], 0, v[158:159]
	s_mov_b32 m0, s51
	s_nop 0
	global_load_lds_dwordx4 v158, s[48:49]
	s_barrier
	s_waitcnt lgkmcnt(0)
	s_waitcnt lgkmcnt(0)
	v_mfma_f32_16x16x32_bf16 v[60:63], v[120:123], v[144:147], v[60:63]
	v_mfma_f32_16x16x32_bf16 v[56:59], v[136:139], v[144:147], v[56:59]
	v_mfma_f32_16x16x32_bf16 v[44:47], v[120:123], v[152:155], v[44:47]
	v_mfma_f32_16x16x32_bf16 v[40:43], v[136:139], v[152:155], v[40:43]
	v_mfma_f32_16x16x32_bf16 v[28:31], v[120:123], v[190:193], v[28:31]
	v_mfma_f32_16x16x32_bf16 v[24:27], v[136:139], v[190:193], v[24:27]
	v_mfma_f32_16x16x32_bf16 v[12:15], v[120:123], v[204:207], v[12:15]
	v_mfma_f32_16x16x32_bf16 v[8:11], v[136:139], v[204:207], v[8:11]
	v_mfma_f32_16x16x32_bf16 v[60:63], v[124:127], v[148:151], v[60:63]
	v_mfma_f32_16x16x32_bf16 v[56:59], v[140:143], v[148:151], v[56:59]
	v_mfma_f32_16x16x32_bf16 v[44:47], v[124:127], v[186:189], v[44:47]
	v_mfma_f32_16x16x32_bf16 v[40:43], v[140:143], v[186:189], v[40:43]
	v_mfma_f32_16x16x32_bf16 v[28:31], v[124:127], v[194:197], v[28:31]
	v_mfma_f32_16x16x32_bf16 v[24:27], v[140:143], v[194:197], v[24:27]
	v_mfma_f32_16x16x32_bf16 v[12:15], v[124:127], v[208:211], v[12:15]
	v_mfma_f32_16x16x32_bf16 v[8:11], v[140:143], v[208:211], v[8:11]
	s_barrier
	s_add_u32 s74, vcc_lo, 0x40000
	s_addc_u32 s75, vcc_hi, 0
	s_add_i32 s73, s76, s64
	s_mov_b32 m0, s73
	s_nop 0
	global_load_lds_dwordx4 v174, s[74:75]
	s_add_i32 m0, s73, 0x2000
	s_nop 0
	global_load_lds_dwordx4 v156, s[74:75]
	s_waitcnt vmcnt(6)
	s_barrier
; #define PG8_STAGE(bufoff, gbase, voff) do { _Pragma("unroll") for (int _i = 0; _i < 2; ++_i) \
;     __builtin_amdgcn_global_load_lds((const unsigned*)((const char*)(gbase) + (voff)[_i]), (LAS unsigned*)(lds + (bufoff) + ldsw + _i * 8192), 16, 0, 0); } while (0)
; #define PG8_LDA(dst, b, h) do { _Pragma("unroll") for (int m = 0; m < 4; ++m) _Pragma("unroll") for (int k = 0; k < 2; ++k) dst[m][k] = *(const LAS bf16x8*)(lds + PG8_SA(b, h) + aoff + m * 2048 + k * 1024); } while (0)
; #define PG8_LDB(dst, b, h) do { _Pragma("unroll") for (int n = 0; n < 2; ++n) _Pragma("unroll") for (int k = 0; k < 2; ++k) dst[n][k] = *(const LAS bf16x8*)(lds + PG8_SB(b, h) + boff + n * 2048 + k * 1024); } while (0)
; #define PG8_MMA(ai, bj, At, Bt) do { __builtin_amdgcn_s_setprio(1); _Pragma("unroll") for (int m = 0; m < 4; ++m) _Pragma("unroll") for (int n = 0; n < 2; ++n) _Pragma("unroll") for (int k = 0; k < 2; ++k) \
;     acc[ai][bj][m][n] = __builtin_amdgcn_mfma_f32_16x16x32_bf16(Bt[n][k], At[m][k], acc[ai][bj][m][n], 0, 0, 0); __builtin_amdgcn_s_setprio(0); } while (0)
; #define PG8_WAIT_V(n) asm volatile("s_waitcnt vmcnt(" #n ")" ::: "memory")
; #define PG8_WAIT_L(n) asm volatile("s_waitcnt lgkmcnt(" #n ")" ::: "memory")
; #define PG8_BAR __builtin_amdgcn_s_barrier()
; #define PG8_SCHED __builtin_amdgcn_sched_barrier(0)
; template <class Epi, class Sched>
; __device__ __forceinline__ void gemm_phase(LAS unsigned char* lds, const Gemm g, const Sched& S, const Epi& E) {
;     ...
;       PG8_WAIT_V(6); PG8_BAR; PG8_MMA(1, 1, At, B1); PG8_BAR;
;       PG8_LDB(B0, 1, 0); PG8_SCHED; PG8_LDA(At, 1, 0); PG8_STAGE(PG8_SA(0, 1), a2 + hstep, voffA);
;       PG8_WAIT_L(8); PG8_BAR; PG8_WAIT_L(0); PG8_MMA(0, 0, At, B0); PG8_BAR; PG8_SCHED;
;       PG8_LDB(B1, 1, 1); PG8_STAGE(PG8_SB(1, 0), b3, voffB);
	v_mfma_f32_16x16x32_bf16 v[52:55], v[226:229], v[144:147], v[52:55]
	v_mfma_f32_16x16x32_bf16 v[48:51], v[236:239], v[144:147], v[48:51]
	v_mfma_f32_16x16x32_bf16 v[36:39], v[226:229], v[152:155], v[36:39]
	v_mfma_f32_16x16x32_bf16 v[32:35], v[236:239], v[152:155], v[32:35]
	v_mfma_f32_16x16x32_bf16 v[20:23], v[226:229], v[190:193], v[20:23]
	v_mfma_f32_16x16x32_bf16 v[16:19], v[236:239], v[190:193], v[16:19]
	v_mfma_f32_16x16x32_bf16 v[4:7], v[226:229], v[204:207], v[4:7]
	v_mfma_f32_16x16x32_bf16 v[0:3], v[236:239], v[204:207], v[0:3]
	v_mfma_f32_16x16x32_bf16 v[52:55], v[232:235], v[148:151], v[52:55]
	v_mfma_f32_16x16x32_bf16 v[48:51], v[240:243], v[148:151], v[48:51]
	v_mfma_f32_16x16x32_bf16 v[36:39], v[232:235], v[186:189], v[36:39]
	v_mfma_f32_16x16x32_bf16 v[32:35], v[240:243], v[186:189], v[32:35]
	v_mfma_f32_16x16x32_bf16 v[20:23], v[232:235], v[194:197], v[20:23]
	v_mfma_f32_16x16x32_bf16 v[16:19], v[240:243], v[194:197], v[16:19]
	v_mfma_f32_16x16x32_bf16 v[4:7], v[232:235], v[208:211], v[4:7]
	v_mfma_f32_16x16x32_bf16 v[0:3], v[240:243], v[208:211], v[0:3]
	s_add_i32 s73, 0, 0x18000
	v_add_u32_e32 v140, s73, v201
	s_barrier
	ds_read_b128 v[120:123], v140
	ds_read_b128 v[124:127], v140 offset:1024
	ds_read_b128 v[136:139], v140 offset:2048
	ds_read_b128 v[140:143], v140 offset:3072
	s_add_u32 s48, s48, 0x40000
	s_addc_u32 s49, s49, 0
	s_mov_b32 m0, s62
	ds_read_b128 v[144:147], v203 offset:32768
	ds_read_b128 v[148:151], v203 offset:33792
	ds_read_b128 v[152:155], v203 offset:34816
	ds_read_b128 v[186:189], v203 offset:35840
	ds_read_b128 v[190:193], v203 offset:36864
	ds_read_b128 v[194:197], v203 offset:37888
	ds_read_b128 v[204:207], v203 offset:38912
	ds_read_b128 v[208:211], v203 offset:39936
	global_load_lds_dwordx4 v176, s[48:49]
	s_mov_b32 m0, s63
	s_nop 0
	global_load_lds_dwordx4 v158, s[48:49]
	s_waitcnt lgkmcnt(8)
	s_barrier
	s_waitcnt lgkmcnt(0)
	s_waitcnt lgkmcnt(0)
	v_mfma_f32_16x16x32_bf16 v[132:135], v[120:123], v[144:147], v[132:135]
	v_mfma_f32_16x16x32_bf16 v[128:131], v[136:139], v[144:147], v[128:131]
	v_mfma_f32_16x16x32_bf16 v[108:111], v[120:123], v[152:155], v[108:111]
	v_mfma_f32_16x16x32_bf16 v[104:107], v[136:139], v[152:155], v[104:107]
	v_mfma_f32_16x16x32_bf16 v[92:95], v[120:123], v[190:193], v[92:95]
	v_mfma_f32_16x16x32_bf16 v[88:91], v[136:139], v[190:193], v[88:91]
	v_mfma_f32_16x16x32_bf16 v[76:79], v[120:123], v[204:207], v[76:79]
	v_mfma_f32_16x16x32_bf16 v[72:75], v[136:139], v[204:207], v[72:75]
	v_mfma_f32_16x16x32_bf16 v[132:135], v[124:127], v[148:151], v[132:135]
	v_mfma_f32_16x16x32_bf16 v[128:131], v[140:143], v[148:151], v[128:131]
	v_mfma_f32_16x16x32_bf16 v[108:111], v[124:127], v[186:189], v[108:111]
	v_mfma_f32_16x16x32_bf16 v[104:107], v[140:143], v[186:189], v[104:107]
	v_mfma_f32_16x16x32_bf16 v[92:95], v[124:127], v[194:197], v[92:95]
	v_mfma_f32_16x16x32_bf16 v[88:91], v[140:143], v[194:197], v[88:91]
	v_mfma_f32_16x16x32_bf16 v[76:79], v[124:127], v[208:211], v[76:79]
	v_mfma_f32_16x16x32_bf16 v[72:75], v[140:143], v[208:211], v[72:75]
	s_barrier
	s_add_i32 s74, 0, 0x1c000
	s_add_i32 s48, s73, s64
	v_add_u32_e32 v160, s74, v201
	s_add_u32 s98, vcc_lo, s80
	s_addc_u32 s99, vcc_hi, s81
	s_mov_b32 m0, s48
	ds_read_b128 v[226:229], v160
	ds_read_b128 v[232:235], v160 offset:1024
	ds_read_b128 v[236:239], v160 offset:2048
	ds_read_b128 v[240:243], v160 offset:3072
	global_load_lds_dwordx4 v174, s[98:99]
	v_lshl_add_u64 v[198:199], v[212:213], 0, s[80:81]
	s_add_i32 m0, s48, 0x2000
	s_nop 0
	global_load_lds_dwordx4 v156, s[98:99]
	s_barrier
; #define PG8_STAGE(bufoff, gbase, voff) do { _Pragma("unroll") for (int _i = 0; _i < 2; ++_i) \
;     __builtin_amdgcn_global_load_lds((const unsigned*)((const char*)(gbase) + (voff)[_i]), (LAS unsigned*)(lds + (bufoff) + ldsw + _i * 8192), 16, 0, 0); } while (0)
; #define PG8_LDA(dst, b, h) do { _Pragma("unroll") for (int m = 0; m < 4; ++m) _Pragma("unroll") for (int k = 0; k < 2; ++k) dst[m][k] = *(const LAS bf16x8*)(lds + PG8_SA(b, h) + aoff + m * 2048 + k * 1024); } while (0)
; #define PG8_MMA(ai, bj, At, Bt) do { __builtin_amdgcn_s_setprio(1); _Pragma("unroll") for (int m = 0; m < 4; ++m) _Pragma("unroll") for (int n = 0; n < 2; ++n) _Pragma("unroll") for (int k = 0; k < 2; ++k) \
;     acc[ai][bj][m][n] = __builtin_amdgcn_mfma_f32_16x16x32_bf16(Bt[n][k], At[m][k], acc[ai][bj][m][n], 0, 0, 0); __builtin_amdgcn_s_setprio(0); } while (0)
; #define PG8_WAIT_V(n) asm volatile("s_waitcnt vmcnt(" #n ")" ::: "memory")
; #define PG8_WAIT_L(n) asm volatile("s_waitcnt lgkmcnt(" #n ")" ::: "memory")
; #define PG8_BAR __builtin_amdgcn_s_barrier()
; #define PG8_SCHED __builtin_amdgcn_sched_barrier(0)
; template <class Epi, class Sched>
; __device__ __forceinline__ void gemm_phase(LAS unsigned char* lds, const Gemm g, const Sched& S, const Epi& E) {
;     ...
;       PG8_BAR; PG8_WAIT_L(0); PG8_MMA(0, 1, At, B1); PG8_BAR;
;       PG8_LDA(At, 1, 1); PG8_STAGE(PG8_SA(1, 0), a3, voffA);
;       PG8_BAR; PG8_WAIT_L(0); PG8_MMA(1, 0, At, B0); PG8_BAR; PG8_SCHED;
;       PG8_STAGE(PG8_SB(1, 1), b3 + hstep, voffB);
;       PG8_WAIT_V(6); PG8_BAR; PG8_MMA(1, 1, At, B1); PG8_BAR;
;     }
	s_waitcnt lgkmcnt(0)
	s_waitcnt lgkmcnt(0)
	v_mfma_f32_16x16x32_bf16 v[116:119], v[226:229], v[144:147], v[116:119]
	v_mfma_f32_16x16x32_bf16 v[112:115], v[236:239], v[144:147], v[112:115]
	v_mfma_f32_16x16x32_bf16 v[100:103], v[226:229], v[152:155], v[100:103]
	v_mfma_f32_16x16x32_bf16 v[96:99], v[236:239], v[152:155], v[96:99]
	v_mfma_f32_16x16x32_bf16 v[84:87], v[226:229], v[190:193], v[84:87]
	v_mfma_f32_16x16x32_bf16 v[80:83], v[236:239], v[190:193], v[80:83]
	v_mfma_f32_16x16x32_bf16 v[68:71], v[226:229], v[204:207], v[68:71]
	v_mfma_f32_16x16x32_bf16 v[64:67], v[236:239], v[204:207], v[64:67]
	v_mfma_f32_16x16x32_bf16 v[116:119], v[232:235], v[148:151], v[116:119]
	v_mfma_f32_16x16x32_bf16 v[112:115], v[240:243], v[148:151], v[112:115]
	v_mfma_f32_16x16x32_bf16 v[100:103], v[232:235], v[186:189], v[100:103]
	v_mfma_f32_16x16x32_bf16 v[96:99], v[240:243], v[186:189], v[96:99]
	v_mfma_f32_16x16x32_bf16 v[84:87], v[232:235], v[194:197], v[84:87]
	v_mfma_f32_16x16x32_bf16 v[80:83], v[240:243], v[194:197], v[80:83]
	v_mfma_f32_16x16x32_bf16 v[68:71], v[232:235], v[208:211], v[68:71]
	v_mfma_f32_16x16x32_bf16 v[64:67], v[240:243], v[208:211], v[64:67]
	s_mov_b32 m0, s70
	v_lshl_add_u64 v[198:199], v[222:223], 0, s[80:81]
	s_barrier
	ds_read_b128 v[144:147], v203 offset:49152
	ds_read_b128 v[148:151], v203 offset:50176
	ds_read_b128 v[152:155], v203 offset:51200
	ds_read_b128 v[186:189], v203 offset:52224
	ds_read_b128 v[190:193], v203 offset:53248
	ds_read_b128 v[194:197], v203 offset:54272
	ds_read_b128 v[204:207], v203 offset:55296
	ds_read_b128 v[208:211], v203 offset:56320
	global_load_lds_dwordx4 v[198:199], off
	v_lshl_add_u64 v[198:199], v[244:245], 0, s[80:81]
	s_mov_b32 m0, s71
	s_nop 0
	global_load_lds_dwordx4 v[198:199], off
	s_barrier
	s_waitcnt lgkmcnt(0)
	s_waitcnt lgkmcnt(0)
	v_mfma_f32_16x16x32_bf16 v[60:63], v[120:123], v[144:147], v[60:63]
	v_mfma_f32_16x16x32_bf16 v[56:59], v[136:139], v[144:147], v[56:59]
	v_mfma_f32_16x16x32_bf16 v[44:47], v[120:123], v[152:155], v[44:47]
	v_mfma_f32_16x16x32_bf16 v[40:43], v[136:139], v[152:155], v[40:43]
	v_mfma_f32_16x16x32_bf16 v[28:31], v[120:123], v[190:193], v[28:31]
	v_mfma_f32_16x16x32_bf16 v[24:27], v[136:139], v[190:193], v[24:27]
	v_mfma_f32_16x16x32_bf16 v[12:15], v[120:123], v[204:207], v[12:15]
	v_mfma_f32_16x16x32_bf16 v[8:11], v[136:139], v[204:207], v[8:11]
	v_mfma_f32_16x16x32_bf16 v[60:63], v[124:127], v[148:151], v[60:63]
	v_mfma_f32_16x16x32_bf16 v[56:59], v[140:143], v[148:151], v[56:59]
	v_mfma_f32_16x16x32_bf16 v[44:47], v[124:127], v[186:189], v[44:47]
	v_mfma_f32_16x16x32_bf16 v[40:43], v[140:143], v[186:189], v[40:43]
	v_mfma_f32_16x16x32_bf16 v[28:31], v[124:127], v[194:197], v[28:31]
	v_mfma_f32_16x16x32_bf16 v[24:27], v[140:143], v[194:197], v[24:27]
	v_mfma_f32_16x16x32_bf16 v[12:15], v[124:127], v[208:211], v[12:15]
	v_mfma_f32_16x16x32_bf16 v[8:11], v[140:143], v[208:211], v[8:11]
	s_barrier
	s_add_u32 s48, vcc_lo, 0x40080
	s_addc_u32 s49, vcc_hi, 0
	s_add_i32 s73, s74, s64
	s_mov_b32 m0, s73
	s_nop 0
	global_load_lds_dwordx4 v174, s[48:49]
	s_add_i32 m0, s73, 0x2000
	s_nop 0
	global_load_lds_dwordx4 v156, s[48:49]
	s_waitcnt vmcnt(6)
	s_barrier
	v_mfma_f32_16x16x32_bf16 v[52:55], v[226:229], v[144:147], v[52:55]
	v_mfma_f32_16x16x32_bf16 v[48:51], v[236:239], v[144:147], v[48:51]
	v_mfma_f32_16x16x32_bf16 v[36:39], v[226:229], v[152:155], v[36:39]
	v_mfma_f32_16x16x32_bf16 v[32:35], v[236:239], v[152:155], v[32:35]
	v_mfma_f32_16x16x32_bf16 v[20:23], v[226:229], v[190:193], v[20:23]
	v_mfma_f32_16x16x32_bf16 v[16:19], v[236:239], v[190:193], v[16:19]
	v_mfma_f32_16x16x32_bf16 v[4:7], v[226:229], v[204:207], v[4:7]
	v_mfma_f32_16x16x32_bf16 v[0:3], v[236:239], v[204:207], v[0:3]
	v_mfma_f32_16x16x32_bf16 v[52:55], v[232:235], v[148:151], v[52:55]
	v_mfma_f32_16x16x32_bf16 v[48:51], v[240:243], v[148:151], v[48:51]
	v_mfma_f32_16x16x32_bf16 v[36:39], v[232:235], v[186:189], v[36:39]
	v_mfma_f32_16x16x32_bf16 v[32:35], v[240:243], v[186:189], v[32:35]
	v_mfma_f32_16x16x32_bf16 v[20:23], v[232:235], v[194:197], v[20:23]
	v_mfma_f32_16x16x32_bf16 v[16:19], v[240:243], v[194:197], v[16:19]
	v_mfma_f32_16x16x32_bf16 v[4:7], v[232:235], v[208:211], v[4:7]
	v_mfma_f32_16x16x32_bf16 v[0:3], v[240:243], v[208:211], v[0:3]
	s_add_i32 s72, s72, 2
	s_add_u32 s34, s34, 0x100
	s_addc_u32 s35, s35, 0
	s_add_u32 s69, s69, 0x100
	s_addc_u32 s52, s52, 0
	s_cmp_gt_u32 s72, 13
	s_barrier
	s_cbranch_scc0 .LBB0_707
	s_cmp_lt_u32 s101, 0x100
	s_cbranch_scc0 .Lxa_3
	s_barrier

; #define PG8_STAGE(bufoff, gbase, voff) do { _Pragma("unroll") for (int _i = 0; _i < 2; ++_i) \
;     __builtin_amdgcn_global_load_lds((const unsigned*)((const char*)(gbase) + (voff)[_i]), (LAS unsigned*)(lds + (bufoff) + ldsw + _i * 8192), 16, 0, 0); } while (0)
; #define PG8_LDA(dst, b, h) do { _Pragma("unroll") for (int m = 0; m < 4; ++m) _Pragma("unroll") for (int k = 0; k < 2; ++k) dst[m][k] = *(const LAS bf16x8*)(lds + PG8_SA(b, h) + aoff + m * 2048 + k * 1024); } while (0)
; #define PG8_LDB(dst, b, h) do { _Pragma("unroll") for (int n = 0; n < 2; ++n) _Pragma("unroll") for (int k = 0; k < 2; ++k) dst[n][k] = *(const LAS bf16x8*)(lds + PG8_SB(b, h) + boff + n * 2048 + k * 1024); } while (0)
; #define PG8_MMA(ai, bj, At, Bt) do { __builtin_amdgcn_s_setprio(1); _Pragma("unroll") for (int m = 0; m < 4; ++m) _Pragma("unroll") for (int n = 0; n < 2; ++n) _Pragma("unroll") for (int k = 0; k < 2; ++k) \
;     acc[ai][bj][m][n] = __builtin_amdgcn_mfma_f32_16x16x32_bf16(Bt[n][k], At[m][k], acc[ai][bj][m][n], 0, 0, 0); __builtin_amdgcn_s_setprio(0); } while (0)
; #define PG8_WAIT_L(n) asm volatile("s_waitcnt lgkmcnt(" #n ")" ::: "memory")
; #define PG8_BAR __builtin_amdgcn_s_barrier()
; #define PG8_SCHED __builtin_amdgcn_sched_barrier(0)
; template <class Epi, class Sched>
; __device__ __forceinline__ void gemm_phase(LAS unsigned char* lds, const Gemm g, const Sched& S, const Epi& E) {
;     ...
;       const bool last = (t == nt - 2);
;       const char* a1 = cA + (size_t)(t + 1) * kstep;
;       const char* a2 = last ? nA : cA + (size_t)(t + 2) * kstep; const char* b2 = last ? nB : cB + (size_t)(t + 2) * kstep;
;       const char* a3 = a2 + kstep; const char* b3 = b2 + kstep;
;       if (last && has_next) S.a_ready(nxt);
;       PG8_LDB(B0, 0, 0); PG8_SCHED; PG8_LDA(At, 0, 0); PG8_STAGE(PG8_SA(1, 1), a1 + hstep, voffA);
;       PG8_WAIT_L(8); PG8_BAR; PG8_WAIT_L(0); PG8_MMA(0, 0, At, B0); PG8_BAR; PG8_SCHED;
;       PG8_LDB(B1, 0, 1); PG8_STAGE(PG8_SB(0, 0), b2, voffB);
;       PG8_BAR; PG8_WAIT_L(0); PG8_MMA(0, 1, At, B1); PG8_BAR;
;       PG8_LDA(At, 0, 1); PG8_STAGE(PG8_SA(0, 0), a2, voffA);
;       PG8_BAR; PG8_WAIT_L(0); PG8_MMA(1, 0, At, B0); PG8_BAR; PG8_SCHED;
.Lxs_e4:
.LBB0_778:
	s_add_u32 s44, s34, 0xfffe0080
	s_addc_u32 s45, s35, -1
	s_add_i32 s73, 0, 0x10000
	v_add_u32_e32 v150, s73, v177
	ds_read_b128 v[138:141], v150
	ds_read_b128 v[142:145], v150 offset:1024
	ds_read_b128 v[146:149], v150 offset:2048
	ds_read_b128 v[150:153], v150 offset:3072
	s_cmp_eq_u32 s72, 4
	s_cselect_b32 s49, s37, s45
	s_cselect_b32 s48, s69, s44
	s_cselect_b32 s45, s23, s52
	s_cselect_b32 s44, s70, s71
	s_add_i32 m0, s12, 0xc000
	ds_read_b128 v[154:157], v179
	ds_read_b128 v[180:183], v179 offset:1024
	ds_read_b128 v[184:187], v179 offset:2048
	ds_read_b128 v[188:191], v179 offset:3072
	ds_read_b128 v[192:195], v179 offset:4096
	ds_read_b128 v[196:199], v179 offset:5120
	ds_read_b128 v[200:203], v179 offset:6144
	ds_read_b128 v[204:207], v179 offset:7168
	global_load_lds_dwordx4 v134, s[34:35]
	s_add_i32 m0, s12, 0xe000
	s_nop 0
	global_load_lds_dwordx4 v136, s[34:35]
	s_waitcnt lgkmcnt(8)
	s_barrier
	s_waitcnt lgkmcnt(0)
	s_waitcnt lgkmcnt(0)
	v_mfma_f32_16x16x32_bf16 v[124:127], v[138:141], v[154:157], v[124:127]
	v_mfma_f32_16x16x32_bf16 v[120:123], v[146:149], v[154:157], v[120:123]
	v_mfma_f32_16x16x32_bf16 v[108:111], v[138:141], v[184:187], v[108:111]
	v_mfma_f32_16x16x32_bf16 v[104:107], v[146:149], v[184:187], v[104:107]
	v_mfma_f32_16x16x32_bf16 v[92:95], v[138:141], v[192:195], v[92:95]
	v_mfma_f32_16x16x32_bf16 v[88:91], v[146:149], v[192:195], v[88:91]
	v_mfma_f32_16x16x32_bf16 v[76:79], v[138:141], v[200:203], v[76:79]
	v_mfma_f32_16x16x32_bf16 v[72:75], v[146:149], v[200:203], v[72:75]
	v_mfma_f32_16x16x32_bf16 v[124:127], v[142:145], v[180:183], v[124:127]
	v_mfma_f32_16x16x32_bf16 v[120:123], v[150:153], v[180:183], v[120:123]
	v_mfma_f32_16x16x32_bf16 v[108:111], v[142:145], v[188:191], v[108:111]
	v_mfma_f32_16x16x32_bf16 v[104:107], v[150:153], v[188:191], v[104:107]
	v_mfma_f32_16x16x32_bf16 v[92:95], v[142:145], v[196:199], v[92:95]
	v_mfma_f32_16x16x32_bf16 v[88:91], v[150:153], v[196:199], v[88:91]
	v_mfma_f32_16x16x32_bf16 v[76:79], v[142:145], v[204:207], v[76:79]
	v_mfma_f32_16x16x32_bf16 v[72:75], v[150:153], v[204:207], v[72:75]
	s_barrier
	s_add_i32 s76, 0, 0x14000
	v_add_u32_e32 v158, s76, v177
	s_add_i32 s73, s73, s7
	ds_read_b128 v[208:211], v158
	ds_read_b128 v[226:229], v158 offset:1024
	ds_read_b128 v[232:235], v158 offset:2048
	ds_read_b128 v[236:239], v158 offset:3072
	v_lshl_add_u64 v[158:159], s[44:45], 0, v[160:161]
	s_mov_b32 m0, s73
	v_lshl_add_u64 v[174:175], s[44:45], 0, v[128:129]
	global_load_lds_dwordx4 v[158:159], off
	s_add_i32 m0, s73, 0x2000
	s_nop 0
	global_load_lds_dwordx4 v[174:175], off
	s_barrier
	s_waitcnt lgkmcnt(0)
	s_waitcnt lgkmcnt(0)
	v_mfma_f32_16x16x32_bf16 v[116:119], v[208:211], v[154:157], v[116:119]
	v_mfma_f32_16x16x32_bf16 v[112:115], v[232:235], v[154:157], v[112:115]
	v_mfma_f32_16x16x32_bf16 v[100:103], v[208:211], v[184:187], v[100:103]
	v_mfma_f32_16x16x32_bf16 v[96:99], v[232:235], v[184:187], v[96:99]
	v_mfma_f32_16x16x32_bf16 v[84:87], v[208:211], v[192:195], v[84:87]
	v_mfma_f32_16x16x32_bf16 v[80:83], v[232:235], v[192:195], v[80:83]
	v_mfma_f32_16x16x32_bf16 v[68:71], v[208:211], v[200:203], v[68:71]
	v_mfma_f32_16x16x32_bf16 v[64:67], v[232:235], v[200:203], v[64:67]
	v_mfma_f32_16x16x32_bf16 v[116:119], v[226:229], v[180:183], v[116:119]
	v_mfma_f32_16x16x32_bf16 v[112:115], v[236:239], v[180:183], v[112:115]
	v_mfma_f32_16x16x32_bf16 v[100:103], v[226:229], v[188:191], v[100:103]
	v_mfma_f32_16x16x32_bf16 v[96:99], v[236:239], v[188:191], v[96:99]
	v_mfma_f32_16x16x32_bf16 v[84:87], v[226:229], v[196:199], v[84:87]
	v_mfma_f32_16x16x32_bf16 v[80:83], v[236:239], v[196:199], v[80:83]
	v_mfma_f32_16x16x32_bf16 v[68:71], v[226:229], v[204:207], v[68:71]
	v_mfma_f32_16x16x32_bf16 v[64:67], v[236:239], v[204:207], v[64:67]
	s_mov_b32 m0, s12
	v_lshl_add_u64 v[212:213], s[48:49], 0, v[132:133]
	s_barrier
	ds_read_b128 v[154:157], v179 offset:16384
	ds_read_b128 v[180:183], v179 offset:17408
	ds_read_b128 v[184:187], v179 offset:18432
	ds_read_b128 v[188:191], v179 offset:19456
	ds_read_b128 v[192:195], v179 offset:20480
	ds_read_b128 v[196:199], v179 offset:21504
	ds_read_b128 v[200:203], v179 offset:22528
	ds_read_b128 v[204:207], v179 offset:23552
	global_load_lds_dwordx4 v132, s[48:49]
	v_lshl_add_u64 v[222:223], s[48:49], 0, v[130:131]
	s_mov_b32 m0, s13
	s_nop 0
	global_load_lds_dwordx4 v130, s[48:49]
	s_barrier
	s_waitcnt lgkmcnt(0)
	s_waitcnt lgkmcnt(0)
	v_mfma_f32_16x16x32_bf16 v[60:63], v[138:141], v[154:157], v[60:63]
	v_mfma_f32_16x16x32_bf16 v[56:59], v[146:149], v[154:157], v[56:59]
	v_mfma_f32_16x16x32_bf16 v[44:47], v[138:141], v[184:187], v[44:47]
	v_mfma_f32_16x16x32_bf16 v[40:43], v[146:149], v[184:187], v[40:43]
	v_mfma_f32_16x16x32_bf16 v[28:31], v[138:141], v[192:195], v[28:31]
	v_mfma_f32_16x16x32_bf16 v[24:27], v[146:149], v[192:195], v[24:27]
	v_mfma_f32_16x16x32_bf16 v[12:15], v[138:141], v[200:203], v[12:15]
	v_mfma_f32_16x16x32_bf16 v[8:11], v[146:149], v[200:203], v[8:11]
	v_mfma_f32_16x16x32_bf16 v[60:63], v[142:145], v[180:183], v[60:63]
	v_mfma_f32_16x16x32_bf16 v[56:59], v[150:153], v[180:183], v[56:59]
	v_mfma_f32_16x16x32_bf16 v[44:47], v[142:145], v[188:191], v[44:47]
	v_mfma_f32_16x16x32_bf16 v[40:43], v[150:153], v[188:191], v[40:43]
	v_mfma_f32_16x16x32_bf16 v[28:31], v[142:145], v[196:199], v[28:31]
	v_mfma_f32_16x16x32_bf16 v[24:27], v[150:153], v[196:199], v[24:27]
	v_mfma_f32_16x16x32_bf16 v[12:15], v[142:145], v[204:207], v[12:15]
	v_mfma_f32_16x16x32_bf16 v[8:11], v[150:153], v[204:207], v[8:11]
	s_barrier
; #define PG8_STAGE(bufoff, gbase, voff) do { _Pragma("unroll") for (int _i = 0; _i < 2; ++_i) \
;     __builtin_amdgcn_global_load_lds((const unsigned*)((const char*)(gbase) + (voff)[_i]), (LAS unsigned*)(lds + (bufoff) + ldsw + _i * 8192), 16, 0, 0); } while (0)
; #define PG8_LDA(dst, b, h) do { _Pragma("unroll") for (int m = 0; m < 4; ++m) _Pragma("unroll") for (int k = 0; k < 2; ++k) dst[m][k] = *(const LAS bf16x8*)(lds + PG8_SA(b, h) + aoff + m * 2048 + k * 1024); } while (0)
; #define PG8_LDB(dst, b, h) do { _Pragma("unroll") for (int n = 0; n < 2; ++n) _Pragma("unroll") for (int k = 0; k < 2; ++k) dst[n][k] = *(const LAS bf16x8*)(lds + PG8_SB(b, h) + boff + n * 2048 + k * 1024); } while (0)
; #define PG8_MMA(ai, bj, At, Bt) do { __builtin_amdgcn_s_setprio(1); _Pragma("unroll") for (int m = 0; m < 4; ++m) _Pragma("unroll") for (int n = 0; n < 2; ++n) _Pragma("unroll") for (int k = 0; k < 2; ++k) \
;     acc[ai][bj][m][n] = __builtin_amdgcn_mfma_f32_16x16x32_bf16(Bt[n][k], At[m][k], acc[ai][bj][m][n], 0, 0, 0); __builtin_amdgcn_s_setprio(0); } while (0)
; #define PG8_WAIT_V(n) asm volatile("s_waitcnt vmcnt(" #n ")" ::: "memory")
; #define PG8_WAIT_L(n) asm volatile("s_waitcnt lgkmcnt(" #n ")" ::: "memory")
; #define PG8_BAR __builtin_amdgcn_s_barrier()
; #define PG8_SCHED __builtin_amdgcn_sched_barrier(0)
; template <class Epi, class Sched>
; __device__ __forceinline__ void gemm_phase(LAS unsigned char* lds, const Gemm g, const Sched& S, const Epi& E) {
;     ...
;       PG8_STAGE(PG8_SB(0, 1), b2 + hstep, voffB);
;       PG8_WAIT_V(6); PG8_BAR; PG8_MMA(1, 1, At, B1); PG8_BAR;
;       PG8_LDB(B0, 1, 0); PG8_SCHED; PG8_LDA(At, 1, 0); PG8_STAGE(PG8_SA(0, 1), a2 + hstep, voffA);
;       PG8_WAIT_L(8); PG8_BAR; PG8_WAIT_L(0); PG8_MMA(0, 0, At, B0); PG8_BAR; PG8_SCHED;
;       PG8_LDB(B1, 1, 1); PG8_STAGE(PG8_SB(1, 0), b3, voffB);
	s_add_u32 s74, s44, 0x20000
	s_addc_u32 s75, s45, 0
	s_add_i32 s73, s76, s7
	s_mov_b32 m0, s73
	s_nop 0
	global_load_lds_dwordx4 v160, s[74:75]
	s_add_i32 m0, s73, 0x2000
	s_nop 0
	global_load_lds_dwordx4 v128, s[74:75]
	s_waitcnt vmcnt(6)
	s_barrier
	v_mfma_f32_16x16x32_bf16 v[52:55], v[208:211], v[154:157], v[52:55]
	v_mfma_f32_16x16x32_bf16 v[48:51], v[232:235], v[154:157], v[48:51]
	v_mfma_f32_16x16x32_bf16 v[36:39], v[208:211], v[184:187], v[36:39]
	v_mfma_f32_16x16x32_bf16 v[32:35], v[232:235], v[184:187], v[32:35]
	v_mfma_f32_16x16x32_bf16 v[20:23], v[208:211], v[192:195], v[20:23]
	v_mfma_f32_16x16x32_bf16 v[16:19], v[232:235], v[192:195], v[16:19]
	v_mfma_f32_16x16x32_bf16 v[4:7], v[208:211], v[200:203], v[4:7]
	v_mfma_f32_16x16x32_bf16 v[0:3], v[232:235], v[200:203], v[0:3]
	v_mfma_f32_16x16x32_bf16 v[52:55], v[226:229], v[180:183], v[52:55]
	v_mfma_f32_16x16x32_bf16 v[48:51], v[236:239], v[180:183], v[48:51]
	v_mfma_f32_16x16x32_bf16 v[36:39], v[226:229], v[188:191], v[36:39]
	v_mfma_f32_16x16x32_bf16 v[32:35], v[236:239], v[188:191], v[32:35]
	v_mfma_f32_16x16x32_bf16 v[20:23], v[226:229], v[196:199], v[20:23]
	v_mfma_f32_16x16x32_bf16 v[16:19], v[236:239], v[196:199], v[16:19]
	v_mfma_f32_16x16x32_bf16 v[4:7], v[226:229], v[204:207], v[4:7]
	v_mfma_f32_16x16x32_bf16 v[0:3], v[236:239], v[204:207], v[0:3]
	s_add_i32 s73, 0, 0x18000
	v_add_u32_e32 v150, s73, v177
	s_barrier
	ds_read_b128 v[138:141], v150
	ds_read_b128 v[142:145], v150 offset:1024
	ds_read_b128 v[146:149], v150 offset:2048
	ds_read_b128 v[150:153], v150 offset:3072
	s_add_u32 s48, s48, 0x20000
	s_addc_u32 s49, s49, 0
	s_mov_b32 m0, s20
	ds_read_b128 v[154:157], v179 offset:32768
	ds_read_b128 v[180:183], v179 offset:33792
	ds_read_b128 v[184:187], v179 offset:34816
	ds_read_b128 v[188:191], v179 offset:35840
	ds_read_b128 v[192:195], v179 offset:36864
	ds_read_b128 v[196:199], v179 offset:37888
	ds_read_b128 v[200:203], v179 offset:38912
	ds_read_b128 v[204:207], v179 offset:39936
	global_load_lds_dwordx4 v132, s[48:49]
	s_mov_b32 m0, s51
	s_nop 0
	global_load_lds_dwordx4 v130, s[48:49]
	s_waitcnt lgkmcnt(8)
	s_barrier
	s_waitcnt lgkmcnt(0)
	s_waitcnt lgkmcnt(0)
	v_mfma_f32_16x16x32_bf16 v[124:127], v[138:141], v[154:157], v[124:127]
	v_mfma_f32_16x16x32_bf16 v[120:123], v[146:149], v[154:157], v[120:123]
	v_mfma_f32_16x16x32_bf16 v[108:111], v[138:141], v[184:187], v[108:111]
	v_mfma_f32_16x16x32_bf16 v[104:107], v[146:149], v[184:187], v[104:107]
	v_mfma_f32_16x16x32_bf16 v[92:95], v[138:141], v[192:195], v[92:95]
	v_mfma_f32_16x16x32_bf16 v[88:91], v[146:149], v[192:195], v[88:91]
	v_mfma_f32_16x16x32_bf16 v[76:79], v[138:141], v[200:203], v[76:79]
	v_mfma_f32_16x16x32_bf16 v[72:75], v[146:149], v[200:203], v[72:75]
	v_mfma_f32_16x16x32_bf16 v[124:127], v[142:145], v[180:183], v[124:127]
	v_mfma_f32_16x16x32_bf16 v[120:123], v[150:153], v[180:183], v[120:123]
	v_mfma_f32_16x16x32_bf16 v[108:111], v[142:145], v[188:191], v[108:111]
	v_mfma_f32_16x16x32_bf16 v[104:107], v[150:153], v[188:191], v[104:107]
	v_mfma_f32_16x16x32_bf16 v[92:95], v[142:145], v[196:199], v[92:95]
	v_mfma_f32_16x16x32_bf16 v[88:91], v[150:153], v[196:199], v[88:91]
	v_mfma_f32_16x16x32_bf16 v[76:79], v[142:145], v[204:207], v[76:79]
	v_mfma_f32_16x16x32_bf16 v[72:75], v[150:153], v[204:207], v[72:75]
	s_barrier
	s_add_i32 s48, 0, 0x1c000
	s_add_i32 s49, s73, s7
	v_add_u32_e32 v225, s48, v177
	s_add_u32 s98, s44, s80
	s_addc_u32 s99, s45, s81
	s_mov_b32 m0, s49
	ds_read_b128 v[208:211], v225
	ds_read_b128 v[226:229], v225 offset:1024
	ds_read_b128 v[232:235], v225 offset:2048
	ds_read_b128 v[236:239], v225 offset:3072
	global_load_lds_dwordx4 v160, s[98:99]
	v_lshl_add_u64 v[158:159], v[174:175], 0, s[80:81]
	s_add_i32 m0, s49, 0x2000
	s_nop 0
	global_load_lds_dwordx4 v128, s[98:99]
	s_barrier
; #define PG8_STAGE(bufoff, gbase, voff) do { _Pragma("unroll") for (int _i = 0; _i < 2; ++_i) \
;     __builtin_amdgcn_global_load_lds((const unsigned*)((const char*)(gbase) + (voff)[_i]), (LAS unsigned*)(lds + (bufoff) + ldsw + _i * 8192), 16, 0, 0); } while (0)
; #define PG8_LDA(dst, b, h) do { _Pragma("unroll") for (int m = 0; m < 4; ++m) _Pragma("unroll") for (int k = 0; k < 2; ++k) dst[m][k] = *(const LAS bf16x8*)(lds + PG8_SA(b, h) + aoff + m * 2048 + k * 1024); } while (0)
; #define PG8_MMA(ai, bj, At, Bt) do { __builtin_amdgcn_s_setprio(1); _Pragma("unroll") for (int m = 0; m < 4; ++m) _Pragma("unroll") for (int n = 0; n < 2; ++n) _Pragma("unroll") for (int k = 0; k < 2; ++k) \
;     acc[ai][bj][m][n] = __builtin_amdgcn_mfma_f32_16x16x32_bf16(Bt[n][k], At[m][k], acc[ai][bj][m][n], 0, 0, 0); __builtin_amdgcn_s_setprio(0); } while (0)
; #define PG8_WAIT_V(n) asm volatile("s_waitcnt vmcnt(" #n ")" ::: "memory")
; #define PG8_WAIT_L(n) asm volatile("s_waitcnt lgkmcnt(" #n ")" ::: "memory")
; #define PG8_BAR __builtin_amdgcn_s_barrier()
; #define PG8_SCHED __builtin_amdgcn_sched_barrier(0)
; template <class Epi, class Sched>
; __device__ __forceinline__ void gemm_phase(LAS unsigned char* lds, const Gemm g, const Sched& S, const Epi& E) {
;     ...
;       PG8_BAR; PG8_WAIT_L(0); PG8_MMA(0, 1, At, B1); PG8_BAR;
;       PG8_LDA(At, 1, 1); PG8_STAGE(PG8_SA(1, 0), a3, voffA);
;       PG8_BAR; PG8_WAIT_L(0); PG8_MMA(1, 0, At, B0); PG8_BAR; PG8_SCHED;
;       PG8_STAGE(PG8_SB(1, 1), b3 + hstep, voffB);
;       PG8_WAIT_V(6); PG8_BAR; PG8_MMA(1, 1, At, B1); PG8_BAR;
;     }
	s_waitcnt lgkmcnt(0)
	s_waitcnt lgkmcnt(0)
	v_mfma_f32_16x16x32_bf16 v[116:119], v[208:211], v[154:157], v[116:119]
	v_mfma_f32_16x16x32_bf16 v[112:115], v[232:235], v[154:157], v[112:115]
	v_mfma_f32_16x16x32_bf16 v[100:103], v[208:211], v[184:187], v[100:103]
	v_mfma_f32_16x16x32_bf16 v[96:99], v[232:235], v[184:187], v[96:99]
	v_mfma_f32_16x16x32_bf16 v[84:87], v[208:211], v[192:195], v[84:87]
	v_mfma_f32_16x16x32_bf16 v[80:83], v[232:235], v[192:195], v[80:83]
	v_mfma_f32_16x16x32_bf16 v[68:71], v[208:211], v[200:203], v[68:71]
	v_mfma_f32_16x16x32_bf16 v[64:67], v[232:235], v[200:203], v[64:67]
	v_mfma_f32_16x16x32_bf16 v[116:119], v[226:229], v[180:183], v[116:119]
	v_mfma_f32_16x16x32_bf16 v[112:115], v[236:239], v[180:183], v[112:115]
	v_mfma_f32_16x16x32_bf16 v[100:103], v[226:229], v[188:191], v[100:103]
	v_mfma_f32_16x16x32_bf16 v[96:99], v[236:239], v[188:191], v[96:99]
	v_mfma_f32_16x16x32_bf16 v[84:87], v[226:229], v[196:199], v[84:87]
	v_mfma_f32_16x16x32_bf16 v[80:83], v[236:239], v[196:199], v[80:83]
	v_mfma_f32_16x16x32_bf16 v[68:71], v[226:229], v[204:207], v[68:71]
	v_mfma_f32_16x16x32_bf16 v[64:67], v[236:239], v[204:207], v[64:67]
	s_mov_b32 m0, s62
	v_lshl_add_u64 v[158:159], v[212:213], 0, s[80:81]
	s_barrier
	ds_read_b128 v[154:157], v179 offset:49152
	ds_read_b128 v[180:183], v179 offset:50176
	ds_read_b128 v[184:187], v179 offset:51200
	ds_read_b128 v[188:191], v179 offset:52224
	ds_read_b128 v[192:195], v179 offset:53248
	ds_read_b128 v[196:199], v179 offset:54272
	ds_read_b128 v[200:203], v179 offset:55296
	ds_read_b128 v[204:207], v179 offset:56320
	global_load_lds_dwordx4 v[158:159], off
	v_lshl_add_u64 v[158:159], v[222:223], 0, s[80:81]
	s_mov_b32 m0, s63
	s_nop 0
	global_load_lds_dwordx4 v[158:159], off
	s_barrier
	s_waitcnt lgkmcnt(0)
	s_waitcnt lgkmcnt(0)
	v_mfma_f32_16x16x32_bf16 v[60:63], v[138:141], v[154:157], v[60:63]
	v_mfma_f32_16x16x32_bf16 v[56:59], v[146:149], v[154:157], v[56:59]
	v_mfma_f32_16x16x32_bf16 v[44:47], v[138:141], v[184:187], v[44:47]
	v_mfma_f32_16x16x32_bf16 v[40:43], v[146:149], v[184:187], v[40:43]
	v_mfma_f32_16x16x32_bf16 v[28:31], v[138:141], v[192:195], v[28:31]
	v_mfma_f32_16x16x32_bf16 v[24:27], v[146:149], v[192:195], v[24:27]
	v_mfma_f32_16x16x32_bf16 v[12:15], v[138:141], v[200:203], v[12:15]
	v_mfma_f32_16x16x32_bf16 v[8:11], v[146:149], v[200:203], v[8:11]
	v_mfma_f32_16x16x32_bf16 v[60:63], v[142:145], v[180:183], v[60:63]
	v_mfma_f32_16x16x32_bf16 v[56:59], v[150:153], v[180:183], v[56:59]
	v_mfma_f32_16x16x32_bf16 v[44:47], v[142:145], v[188:191], v[44:47]
	v_mfma_f32_16x16x32_bf16 v[40:43], v[150:153], v[188:191], v[40:43]
	v_mfma_f32_16x16x32_bf16 v[28:31], v[142:145], v[196:199], v[28:31]
	v_mfma_f32_16x16x32_bf16 v[24:27], v[150:153], v[196:199], v[24:27]
	v_mfma_f32_16x16x32_bf16 v[12:15], v[142:145], v[204:207], v[12:15]
	v_mfma_f32_16x16x32_bf16 v[8:11], v[150:153], v[204:207], v[8:11]
	s_barrier
	s_add_u32 s44, s44, 0x20080
	s_addc_u32 s45, s45, 0
	s_add_i32 s48, s48, s7
	s_mov_b32 m0, s48
	s_nop 0
	global_load_lds_dwordx4 v160, s[44:45]
	s_add_i32 m0, s48, 0x2000
	s_nop 0
	global_load_lds_dwordx4 v128, s[44:45]
	s_waitcnt vmcnt(6)
	s_barrier
	v_mfma_f32_16x16x32_bf16 v[52:55], v[208:211], v[154:157], v[52:55]
	v_mfma_f32_16x16x32_bf16 v[48:51], v[232:235], v[154:157], v[48:51]
	v_mfma_f32_16x16x32_bf16 v[36:39], v[208:211], v[184:187], v[36:39]
	v_mfma_f32_16x16x32_bf16 v[32:35], v[232:235], v[184:187], v[32:35]
	v_mfma_f32_16x16x32_bf16 v[20:23], v[208:211], v[192:195], v[20:23]
	v_mfma_f32_16x16x32_bf16 v[16:19], v[232:235], v[192:195], v[16:19]
	v_mfma_f32_16x16x32_bf16 v[4:7], v[208:211], v[200:203], v[4:7]
	v_mfma_f32_16x16x32_bf16 v[0:3], v[232:235], v[200:203], v[0:3]
	v_mfma_f32_16x16x32_bf16 v[52:55], v[226:229], v[180:183], v[52:55]
	v_mfma_f32_16x16x32_bf16 v[48:51], v[236:239], v[180:183], v[48:51]
	v_mfma_f32_16x16x32_bf16 v[36:39], v[226:229], v[188:191], v[36:39]
	v_mfma_f32_16x16x32_bf16 v[32:35], v[236:239], v[188:191], v[32:35]
	v_mfma_f32_16x16x32_bf16 v[20:23], v[226:229], v[196:199], v[20:23]
	v_mfma_f32_16x16x32_bf16 v[16:19], v[236:239], v[196:199], v[16:19]
	v_mfma_f32_16x16x32_bf16 v[4:7], v[226:229], v[204:207], v[4:7]
	v_mfma_f32_16x16x32_bf16 v[0:3], v[236:239], v[204:207], v[0:3]
	s_add_i32 s72, s72, 2
	s_add_u32 s34, s34, 0x100
	s_addc_u32 s35, s35, 0
	s_add_u32 s71, s71, 0x100
	s_addc_u32 s52, s52, 0
	s_cmp_gt_u32 s72, 5
	s_barrier
	s_cbranch_scc0 .LBB0_778
	s_cmp_lt_u32 s101, 0x100
	s_cbranch_scc0 .Lxa_4
	s_barrier

; #define PG8_STAGE(bufoff, gbase, voff) do { _Pragma("unroll") for (int _i = 0; _i < 2; ++_i) \
;     __builtin_amdgcn_global_load_lds((const unsigned*)((const char*)(gbase) + (voff)[_i]), (LAS unsigned*)(lds + (bufoff) + ldsw + _i * 8192), 16, 0, 0); } while (0)
; #define PG8_LDA(dst, b, h) do { _Pragma("unroll") for (int m = 0; m < 4; ++m) _Pragma("unroll") for (int k = 0; k < 2; ++k) dst[m][k] = *(const LAS bf16x8*)(lds + PG8_SA(b, h) + aoff + m * 2048 + k * 1024); } while (0)
; #define PG8_LDB(dst, b, h) do { _Pragma("unroll") for (int n = 0; n < 2; ++n) _Pragma("unroll") for (int k = 0; k < 2; ++k) dst[n][k] = *(const LAS bf16x8*)(lds + PG8_SB(b, h) + boff + n * 2048 + k * 1024); } while (0)
; #define PG8_MMA(ai, bj, At, Bt) do { __builtin_amdgcn_s_setprio(1); _Pragma("unroll") for (int m = 0; m < 4; ++m) _Pragma("unroll") for (int n = 0; n < 2; ++n) _Pragma("unroll") for (int k = 0; k < 2; ++k) \
;     acc[ai][bj][m][n] = __builtin_amdgcn_mfma_f32_16x16x32_bf16(Bt[n][k], At[m][k], acc[ai][bj][m][n], 0, 0, 0); __builtin_amdgcn_s_setprio(0); } while (0)
; #define PG8_WAIT_L(n) asm volatile("s_waitcnt lgkmcnt(" #n ")" ::: "memory")
; #define PG8_BAR __builtin_amdgcn_s_barrier()
; #define PG8_SCHED __builtin_amdgcn_sched_barrier(0)
; template <class Epi, class Sched>
; __device__ __forceinline__ void gemm_phase(LAS unsigned char* lds, const Gemm g, const Sched& S, const Epi& E) {
;     ...
;       const bool last = (t == nt - 2);
;       const char* a1 = cA + (size_t)(t + 1) * kstep;
;       const char* a2 = last ? nA : cA + (size_t)(t + 2) * kstep; const char* b2 = last ? nB : cB + (size_t)(t + 2) * kstep;
;       const char* a3 = a2 + kstep; const char* b3 = b2 + kstep;
;       if (last && has_next) S.a_ready(nxt);
;       PG8_LDB(B0, 0, 0); PG8_SCHED; PG8_LDA(At, 0, 0); PG8_STAGE(PG8_SA(1, 1), a1 + hstep, voffA);
;       PG8_WAIT_L(8); PG8_BAR; PG8_WAIT_L(0); PG8_MMA(0, 0, At, B0); PG8_BAR; PG8_SCHED;
;       PG8_LDB(B1, 0, 1); PG8_STAGE(PG8_SB(0, 0), b2, voffB);
;       PG8_BAR; PG8_WAIT_L(0); PG8_MMA(0, 1, At, B1); PG8_BAR;
;       PG8_LDA(At, 0, 1); PG8_STAGE(PG8_SA(0, 0), a2, voffA);
;       PG8_BAR; PG8_WAIT_L(0); PG8_MMA(1, 0, At, B0); PG8_BAR; PG8_SCHED;
.Lxs_e5:
.LBB0_794:
	s_add_u32 s44, s34, 0xfffc0080
	s_addc_u32 s45, s35, -1
	s_add_i32 s73, 0, 0x10000
	v_add_u32_e32 v140, s73, v226
	ds_read_b128 v[128:131], v140
	ds_read_b128 v[132:135], v140 offset:1024
	ds_read_b128 v[136:139], v140 offset:2048
	ds_read_b128 v[140:143], v140 offset:3072
	s_cmp_eq_u32 s72, 12
	s_cselect_b32 s49, s37, s45
	s_cselect_b32 s48, s69, s44
	s_cselect_b32 s45, s23, s52
	s_cselect_b32 s44, s70, s71
	s_add_i32 m0, s12, 0xc000
	ds_read_b128 v[144:147], v228
	ds_read_b128 v[148:151], v228 offset:1024
	ds_read_b128 v[152:155], v228 offset:2048
	ds_read_b128 v[156:159], v228 offset:3072
	ds_read_b128 v[184:187], v228 offset:4096
	ds_read_b128 v[188:191], v228 offset:5120
	ds_read_b128 v[192:195], v228 offset:6144
	ds_read_b128 v[196:199], v228 offset:7168
	global_load_lds_dwordx4 v180, s[34:35]
	s_add_i32 m0, s12, 0xe000
	s_nop 0
	global_load_lds_dwordx4 v182, s[34:35]
	s_waitcnt lgkmcnt(8)
	s_barrier
	s_waitcnt lgkmcnt(0)
	s_waitcnt lgkmcnt(0)
	v_mfma_f32_16x16x32_bf16 v[124:127], v[128:131], v[144:147], v[124:127]
	v_mfma_f32_16x16x32_bf16 v[120:123], v[136:139], v[144:147], v[120:123]
	v_mfma_f32_16x16x32_bf16 v[108:111], v[128:131], v[152:155], v[108:111]
	v_mfma_f32_16x16x32_bf16 v[104:107], v[136:139], v[152:155], v[104:107]
	v_mfma_f32_16x16x32_bf16 v[92:95], v[128:131], v[184:187], v[92:95]
	v_mfma_f32_16x16x32_bf16 v[88:91], v[136:139], v[184:187], v[88:91]
	v_mfma_f32_16x16x32_bf16 v[76:79], v[128:131], v[192:195], v[76:79]
	v_mfma_f32_16x16x32_bf16 v[72:75], v[136:139], v[192:195], v[72:75]
	v_mfma_f32_16x16x32_bf16 v[124:127], v[132:135], v[148:151], v[124:127]
	v_mfma_f32_16x16x32_bf16 v[120:123], v[140:143], v[148:151], v[120:123]
	v_mfma_f32_16x16x32_bf16 v[108:111], v[132:135], v[156:159], v[108:111]
	v_mfma_f32_16x16x32_bf16 v[104:107], v[140:143], v[156:159], v[104:107]
	v_mfma_f32_16x16x32_bf16 v[92:95], v[132:135], v[188:191], v[92:95]
	v_mfma_f32_16x16x32_bf16 v[88:91], v[140:143], v[188:191], v[88:91]
	v_mfma_f32_16x16x32_bf16 v[76:79], v[132:135], v[196:199], v[76:79]
	v_mfma_f32_16x16x32_bf16 v[72:75], v[140:143], v[196:199], v[72:75]
	s_barrier
	s_add_i32 s76, 0, 0x14000
	v_add_u32_e32 v212, s76, v226
	s_add_i32 s73, s73, s7
	ds_read_b128 v[200:203], v212
	ds_read_b128 v[204:207], v212 offset:1024
	ds_read_b128 v[208:211], v212 offset:2048
	ds_read_b128 v[232:235], v212 offset:3072
	v_lshl_add_u64 v[212:213], s[44:45], 0, v[160:161]
	s_mov_b32 m0, s73
	v_lshl_add_u64 v[222:223], s[44:45], 0, v[174:175]
	global_load_lds_dwordx4 v[212:213], off
	s_add_i32 m0, s73, 0x2000
	s_nop 0
	global_load_lds_dwordx4 v[222:223], off
	s_barrier
	s_waitcnt lgkmcnt(0)
	s_waitcnt lgkmcnt(0)
	v_mfma_f32_16x16x32_bf16 v[116:119], v[200:203], v[144:147], v[116:119]
	v_mfma_f32_16x16x32_bf16 v[112:115], v[208:211], v[144:147], v[112:115]
	v_mfma_f32_16x16x32_bf16 v[100:103], v[200:203], v[152:155], v[100:103]
	v_mfma_f32_16x16x32_bf16 v[96:99], v[208:211], v[152:155], v[96:99]
	v_mfma_f32_16x16x32_bf16 v[84:87], v[200:203], v[184:187], v[84:87]
	v_mfma_f32_16x16x32_bf16 v[80:83], v[208:211], v[184:187], v[80:83]
	v_mfma_f32_16x16x32_bf16 v[68:71], v[200:203], v[192:195], v[68:71]
	v_mfma_f32_16x16x32_bf16 v[64:67], v[208:211], v[192:195], v[64:67]
	v_mfma_f32_16x16x32_bf16 v[116:119], v[204:207], v[148:151], v[116:119]
	v_mfma_f32_16x16x32_bf16 v[112:115], v[232:235], v[148:151], v[112:115]
	v_mfma_f32_16x16x32_bf16 v[100:103], v[204:207], v[156:159], v[100:103]
	v_mfma_f32_16x16x32_bf16 v[96:99], v[232:235], v[156:159], v[96:99]
	v_mfma_f32_16x16x32_bf16 v[84:87], v[204:207], v[188:191], v[84:87]
	v_mfma_f32_16x16x32_bf16 v[80:83], v[232:235], v[188:191], v[80:83]
	v_mfma_f32_16x16x32_bf16 v[68:71], v[204:207], v[196:199], v[68:71]
	v_mfma_f32_16x16x32_bf16 v[64:67], v[232:235], v[196:199], v[64:67]
	s_mov_b32 m0, s12
	v_lshl_add_u64 v[236:237], s[48:49], 0, v[178:179]
	s_barrier
	ds_read_b128 v[144:147], v228 offset:16384
	ds_read_b128 v[148:151], v228 offset:17408
	ds_read_b128 v[152:155], v228 offset:18432
	ds_read_b128 v[156:159], v228 offset:19456
	ds_read_b128 v[184:187], v228 offset:20480
	ds_read_b128 v[188:191], v228 offset:21504
	ds_read_b128 v[192:195], v228 offset:22528
	ds_read_b128 v[196:199], v228 offset:23552
	global_load_lds_dwordx4 v178, s[48:49]
	v_lshl_add_u64 v[238:239], s[48:49], 0, v[176:177]
	s_mov_b32 m0, s13
	s_nop 0
	global_load_lds_dwordx4 v176, s[48:49]
	s_barrier
	s_waitcnt lgkmcnt(0)
	s_waitcnt lgkmcnt(0)
	v_mfma_f32_16x16x32_bf16 v[60:63], v[128:131], v[144:147], v[60:63]
	v_mfma_f32_16x16x32_bf16 v[56:59], v[136:139], v[144:147], v[56:59]
	v_mfma_f32_16x16x32_bf16 v[44:47], v[128:131], v[152:155], v[44:47]
	v_mfma_f32_16x16x32_bf16 v[40:43], v[136:139], v[152:155], v[40:43]
	v_mfma_f32_16x16x32_bf16 v[28:31], v[128:131], v[184:187], v[28:31]
	v_mfma_f32_16x16x32_bf16 v[24:27], v[136:139], v[184:187], v[24:27]
	v_mfma_f32_16x16x32_bf16 v[12:15], v[128:131], v[192:195], v[12:15]
	v_mfma_f32_16x16x32_bf16 v[8:11], v[136:139], v[192:195], v[8:11]
	v_mfma_f32_16x16x32_bf16 v[60:63], v[132:135], v[148:151], v[60:63]
	v_mfma_f32_16x16x32_bf16 v[56:59], v[140:143], v[148:151], v[56:59]
	v_mfma_f32_16x16x32_bf16 v[44:47], v[132:135], v[156:159], v[44:47]
	v_mfma_f32_16x16x32_bf16 v[40:43], v[140:143], v[156:159], v[40:43]
	v_mfma_f32_16x16x32_bf16 v[28:31], v[132:135], v[188:191], v[28:31]
	v_mfma_f32_16x16x32_bf16 v[24:27], v[140:143], v[188:191], v[24:27]
	v_mfma_f32_16x16x32_bf16 v[12:15], v[132:135], v[196:199], v[12:15]
	v_mfma_f32_16x16x32_bf16 v[8:11], v[140:143], v[196:199], v[8:11]
	s_barrier
; #define PG8_STAGE(bufoff, gbase, voff) do { _Pragma("unroll") for (int _i = 0; _i < 2; ++_i) \
;     __builtin_amdgcn_global_load_lds((const unsigned*)((const char*)(gbase) + (voff)[_i]), (LAS unsigned*)(lds + (bufoff) + ldsw + _i * 8192), 16, 0, 0); } while (0)
; #define PG8_LDA(dst, b, h) do { _Pragma("unroll") for (int m = 0; m < 4; ++m) _Pragma("unroll") for (int k = 0; k < 2; ++k) dst[m][k] = *(const LAS bf16x8*)(lds + PG8_SA(b, h) + aoff + m * 2048 + k * 1024); } while (0)
; #define PG8_LDB(dst, b, h) do { _Pragma("unroll") for (int n = 0; n < 2; ++n) _Pragma("unroll") for (int k = 0; k < 2; ++k) dst[n][k] = *(const LAS bf16x8*)(lds + PG8_SB(b, h) + boff + n * 2048 + k * 1024); } while (0)
; #define PG8_MMA(ai, bj, At, Bt) do { __builtin_amdgcn_s_setprio(1); _Pragma("unroll") for (int m = 0; m < 4; ++m) _Pragma("unroll") for (int n = 0; n < 2; ++n) _Pragma("unroll") for (int k = 0; k < 2; ++k) \
;     acc[ai][bj][m][n] = __builtin_amdgcn_mfma_f32_16x16x32_bf16(Bt[n][k], At[m][k], acc[ai][bj][m][n], 0, 0, 0); __builtin_amdgcn_s_setprio(0); } while (0)
; #define PG8_WAIT_V(n) asm volatile("s_waitcnt vmcnt(" #n ")" ::: "memory")
; #define PG8_WAIT_L(n) asm volatile("s_waitcnt lgkmcnt(" #n ")" ::: "memory")
; #define PG8_BAR __builtin_amdgcn_s_barrier()
; #define PG8_SCHED __builtin_amdgcn_sched_barrier(0)
; template <class Epi, class Sched>
; __device__ __forceinline__ void gemm_phase(LAS unsigned char* lds, const Gemm g, const Sched& S, const Epi& E) {
;     ...
;       PG8_STAGE(PG8_SB(0, 1), b2 + hstep, voffB);
;       PG8_WAIT_V(6); PG8_BAR; PG8_MMA(1, 1, At, B1); PG8_BAR;
;       PG8_LDB(B0, 1, 0); PG8_SCHED; PG8_LDA(At, 1, 0); PG8_STAGE(PG8_SA(0, 1), a2 + hstep, voffA);
;       PG8_WAIT_L(8); PG8_BAR; PG8_WAIT_L(0); PG8_MMA(0, 0, At, B0); PG8_BAR; PG8_SCHED;
;       PG8_LDB(B1, 1, 1); PG8_STAGE(PG8_SB(1, 0), b3, voffB);
	s_add_u32 s74, s44, 0x40000
	s_addc_u32 s75, s45, 0
	s_add_i32 s73, s76, s7
	s_mov_b32 m0, s73
	s_nop 0
	global_load_lds_dwordx4 v160, s[74:75]
	s_add_i32 m0, s73, 0x2000
	s_nop 0
	global_load_lds_dwordx4 v174, s[74:75]
	s_waitcnt vmcnt(6)
	s_barrier
	v_mfma_f32_16x16x32_bf16 v[52:55], v[200:203], v[144:147], v[52:55]
	v_mfma_f32_16x16x32_bf16 v[48:51], v[208:211], v[144:147], v[48:51]
	v_mfma_f32_16x16x32_bf16 v[36:39], v[200:203], v[152:155], v[36:39]
	v_mfma_f32_16x16x32_bf16 v[32:35], v[208:211], v[152:155], v[32:35]
	v_mfma_f32_16x16x32_bf16 v[20:23], v[200:203], v[184:187], v[20:23]
	v_mfma_f32_16x16x32_bf16 v[16:19], v[208:211], v[184:187], v[16:19]
	v_mfma_f32_16x16x32_bf16 v[4:7], v[200:203], v[192:195], v[4:7]
	v_mfma_f32_16x16x32_bf16 v[0:3], v[208:211], v[192:195], v[0:3]
	v_mfma_f32_16x16x32_bf16 v[52:55], v[204:207], v[148:151], v[52:55]
	v_mfma_f32_16x16x32_bf16 v[48:51], v[232:235], v[148:151], v[48:51]
	v_mfma_f32_16x16x32_bf16 v[36:39], v[204:207], v[156:159], v[36:39]
	v_mfma_f32_16x16x32_bf16 v[32:35], v[232:235], v[156:159], v[32:35]
	v_mfma_f32_16x16x32_bf16 v[20:23], v[204:207], v[188:191], v[20:23]
	v_mfma_f32_16x16x32_bf16 v[16:19], v[232:235], v[188:191], v[16:19]
	v_mfma_f32_16x16x32_bf16 v[4:7], v[204:207], v[196:199], v[4:7]
	v_mfma_f32_16x16x32_bf16 v[0:3], v[232:235], v[196:199], v[0:3]
	s_add_i32 s73, 0, 0x18000
	v_add_u32_e32 v140, s73, v226
	s_barrier
	ds_read_b128 v[128:131], v140
	ds_read_b128 v[132:135], v140 offset:1024
	ds_read_b128 v[136:139], v140 offset:2048
	ds_read_b128 v[140:143], v140 offset:3072
	s_add_u32 s48, s48, 0x40000
	s_addc_u32 s49, s49, 0
	s_mov_b32 m0, s20
	ds_read_b128 v[144:147], v228 offset:32768
	ds_read_b128 v[148:151], v228 offset:33792
	ds_read_b128 v[152:155], v228 offset:34816
	ds_read_b128 v[156:159], v228 offset:35840
	ds_read_b128 v[184:187], v228 offset:36864
	ds_read_b128 v[188:191], v228 offset:37888
	ds_read_b128 v[192:195], v228 offset:38912
	ds_read_b128 v[196:199], v228 offset:39936
	global_load_lds_dwordx4 v178, s[48:49]
	s_mov_b32 m0, s51
	s_nop 0
	global_load_lds_dwordx4 v176, s[48:49]
	s_waitcnt lgkmcnt(8)
	s_barrier
	s_waitcnt lgkmcnt(0)
	s_waitcnt lgkmcnt(0)
	v_mfma_f32_16x16x32_bf16 v[124:127], v[128:131], v[144:147], v[124:127]
	v_mfma_f32_16x16x32_bf16 v[120:123], v[136:139], v[144:147], v[120:123]
	v_mfma_f32_16x16x32_bf16 v[108:111], v[128:131], v[152:155], v[108:111]
	v_mfma_f32_16x16x32_bf16 v[104:107], v[136:139], v[152:155], v[104:107]
	v_mfma_f32_16x16x32_bf16 v[92:95], v[128:131], v[184:187], v[92:95]
	v_mfma_f32_16x16x32_bf16 v[88:91], v[136:139], v[184:187], v[88:91]
	v_mfma_f32_16x16x32_bf16 v[76:79], v[128:131], v[192:195], v[76:79]
	v_mfma_f32_16x16x32_bf16 v[72:75], v[136:139], v[192:195], v[72:75]
	v_mfma_f32_16x16x32_bf16 v[124:127], v[132:135], v[148:151], v[124:127]
	v_mfma_f32_16x16x32_bf16 v[120:123], v[140:143], v[148:151], v[120:123]
	v_mfma_f32_16x16x32_bf16 v[108:111], v[132:135], v[156:159], v[108:111]
	v_mfma_f32_16x16x32_bf16 v[104:107], v[140:143], v[156:159], v[104:107]
	v_mfma_f32_16x16x32_bf16 v[92:95], v[132:135], v[188:191], v[92:95]
	v_mfma_f32_16x16x32_bf16 v[88:91], v[140:143], v[188:191], v[88:91]
	v_mfma_f32_16x16x32_bf16 v[76:79], v[132:135], v[196:199], v[76:79]
	v_mfma_f32_16x16x32_bf16 v[72:75], v[140:143], v[196:199], v[72:75]
	s_barrier
	s_add_i32 s48, 0, 0x1c000
	s_add_i32 s49, s73, s7
	v_add_u32_e32 v229, s48, v226
	s_add_u32 s98, s44, s80
	s_addc_u32 s99, s45, s81
	s_mov_b32 m0, s49
	ds_read_b128 v[200:203], v229
	ds_read_b128 v[204:207], v229 offset:1024
	ds_read_b128 v[208:211], v229 offset:2048
	ds_read_b128 v[232:235], v229 offset:3072
	global_load_lds_dwordx4 v160, s[98:99]
	v_lshl_add_u64 v[212:213], v[222:223], 0, s[80:81]
	s_add_i32 m0, s49, 0x2000
	s_nop 0
	global_load_lds_dwordx4 v174, s[98:99]
	s_barrier
; #define PG8_STAGE(bufoff, gbase, voff) do { _Pragma("unroll") for (int _i = 0; _i < 2; ++_i) \
;     __builtin_amdgcn_global_load_lds((const unsigned*)((const char*)(gbase) + (voff)[_i]), (LAS unsigned*)(lds + (bufoff) + ldsw + _i * 8192), 16, 0, 0); } while (0)
; #define PG8_LDA(dst, b, h) do { _Pragma("unroll") for (int m = 0; m < 4; ++m) _Pragma("unroll") for (int k = 0; k < 2; ++k) dst[m][k] = *(const LAS bf16x8*)(lds + PG8_SA(b, h) + aoff + m * 2048 + k * 1024); } while (0)
; #define PG8_MMA(ai, bj, At, Bt) do { __builtin_amdgcn_s_setprio(1); _Pragma("unroll") for (int m = 0; m < 4; ++m) _Pragma("unroll") for (int n = 0; n < 2; ++n) _Pragma("unroll") for (int k = 0; k < 2; ++k) \
;     acc[ai][bj][m][n] = __builtin_amdgcn_mfma_f32_16x16x32_bf16(Bt[n][k], At[m][k], acc[ai][bj][m][n], 0, 0, 0); __builtin_amdgcn_s_setprio(0); } while (0)
; #define PG8_WAIT_V(n) asm volatile("s_waitcnt vmcnt(" #n ")" ::: "memory")
; #define PG8_WAIT_L(n) asm volatile("s_waitcnt lgkmcnt(" #n ")" ::: "memory")
; #define PG8_BAR __builtin_amdgcn_s_barrier()
; #define PG8_SCHED __builtin_amdgcn_sched_barrier(0)
; template <class Epi, class Sched>
; __device__ __forceinline__ void gemm_phase(LAS unsigned char* lds, const Gemm g, const Sched& S, const Epi& E) {
;     ...
;       PG8_BAR; PG8_WAIT_L(0); PG8_MMA(0, 1, At, B1); PG8_BAR;
;       PG8_LDA(At, 1, 1); PG8_STAGE(PG8_SA(1, 0), a3, voffA);
;       PG8_BAR; PG8_WAIT_L(0); PG8_MMA(1, 0, At, B0); PG8_BAR; PG8_SCHED;
;       PG8_STAGE(PG8_SB(1, 1), b3 + hstep, voffB);
;       PG8_WAIT_V(6); PG8_BAR; PG8_MMA(1, 1, At, B1); PG8_BAR;
	s_waitcnt lgkmcnt(0)
	s_waitcnt lgkmcnt(0)
	v_mfma_f32_16x16x32_bf16 v[116:119], v[200:203], v[144:147], v[116:119]
	v_mfma_f32_16x16x32_bf16 v[112:115], v[208:211], v[144:147], v[112:115]
	v_mfma_f32_16x16x32_bf16 v[100:103], v[200:203], v[152:155], v[100:103]
	v_mfma_f32_16x16x32_bf16 v[96:99], v[208:211], v[152:155], v[96:99]
	v_mfma_f32_16x16x32_bf16 v[84:87], v[200:203], v[184:187], v[84:87]
	v_mfma_f32_16x16x32_bf16 v[80:83], v[208:211], v[184:187], v[80:83]
	v_mfma_f32_16x16x32_bf16 v[68:71], v[200:203], v[192:195], v[68:71]
	v_mfma_f32_16x16x32_bf16 v[64:67], v[208:211], v[192:195], v[64:67]
	v_mfma_f32_16x16x32_bf16 v[116:119], v[204:207], v[148:151], v[116:119]
	v_mfma_f32_16x16x32_bf16 v[112:115], v[232:235], v[148:151], v[112:115]
	v_mfma_f32_16x16x32_bf16 v[100:103], v[204:207], v[156:159], v[100:103]
	v_mfma_f32_16x16x32_bf16 v[96:99], v[232:235], v[156:159], v[96:99]
	v_mfma_f32_16x16x32_bf16 v[84:87], v[204:207], v[188:191], v[84:87]
	v_mfma_f32_16x16x32_bf16 v[80:83], v[232:235], v[188:191], v[80:83]
	v_mfma_f32_16x16x32_bf16 v[68:71], v[204:207], v[196:199], v[68:71]
	v_mfma_f32_16x16x32_bf16 v[64:67], v[232:235], v[196:199], v[64:67]
	s_mov_b32 m0, s62
	v_lshl_add_u64 v[212:213], v[236:237], 0, s[80:81]
	s_barrier
	ds_read_b128 v[144:147], v228 offset:49152
	ds_read_b128 v[148:151], v228 offset:50176
	ds_read_b128 v[152:155], v228 offset:51200
	ds_read_b128 v[156:159], v228 offset:52224
	ds_read_b128 v[184:187], v228 offset:53248
	ds_read_b128 v[188:191], v228 offset:54272
	ds_read_b128 v[192:195], v228 offset:55296
	ds_read_b128 v[196:199], v228 offset:56320
	global_load_lds_dwordx4 v[212:213], off
	v_lshl_add_u64 v[212:213], v[238:239], 0, s[80:81]
	s_mov_b32 m0, s63
	s_nop 0
	global_load_lds_dwordx4 v[212:213], off
	s_barrier
	s_waitcnt lgkmcnt(0)
	s_waitcnt lgkmcnt(0)
	v_mfma_f32_16x16x32_bf16 v[60:63], v[128:131], v[144:147], v[60:63]
	v_mfma_f32_16x16x32_bf16 v[56:59], v[136:139], v[144:147], v[56:59]
	v_mfma_f32_16x16x32_bf16 v[44:47], v[128:131], v[152:155], v[44:47]
	v_mfma_f32_16x16x32_bf16 v[40:43], v[136:139], v[152:155], v[40:43]
	v_mfma_f32_16x16x32_bf16 v[28:31], v[128:131], v[184:187], v[28:31]
	v_mfma_f32_16x16x32_bf16 v[24:27], v[136:139], v[184:187], v[24:27]
	v_mfma_f32_16x16x32_bf16 v[12:15], v[128:131], v[192:195], v[12:15]
	v_mfma_f32_16x16x32_bf16 v[8:11], v[136:139], v[192:195], v[8:11]
	v_mfma_f32_16x16x32_bf16 v[60:63], v[132:135], v[148:151], v[60:63]
	v_mfma_f32_16x16x32_bf16 v[56:59], v[140:143], v[148:151], v[56:59]
	v_mfma_f32_16x16x32_bf16 v[44:47], v[132:135], v[156:159], v[44:47]
	v_mfma_f32_16x16x32_bf16 v[40:43], v[140:143], v[156:159], v[40:43]
	v_mfma_f32_16x16x32_bf16 v[28:31], v[132:135], v[188:191], v[28:31]
	v_mfma_f32_16x16x32_bf16 v[24:27], v[140:143], v[188:191], v[24:27]
	v_mfma_f32_16x16x32_bf16 v[12:15], v[132:135], v[196:199], v[12:15]
	v_mfma_f32_16x16x32_bf16 v[8:11], v[140:143], v[196:199], v[8:11]
	s_barrier
	s_add_u32 s44, s44, 0x40080
	s_addc_u32 s45, s45, 0
	s_add_i32 s48, s48, s7
	s_mov_b32 m0, s48
	s_nop 0
	global_load_lds_dwordx4 v160, s[44:45]
	s_add_i32 m0, s48, 0x2000
	s_nop 0
	global_load_lds_dwordx4 v174, s[44:45]
	s_waitcnt vmcnt(6)
	s_barrier
	v_mfma_f32_16x16x32_bf16 v[52:55], v[200:203], v[144:147], v[52:55]
	v_mfma_f32_16x16x32_bf16 v[48:51], v[208:211], v[144:147], v[48:51]
	v_mfma_f32_16x16x32_bf16 v[36:39], v[200:203], v[152:155], v[36:39]
	v_mfma_f32_16x16x32_bf16 v[32:35], v[208:211], v[152:155], v[32:35]
	v_mfma_f32_16x16x32_bf16 v[20:23], v[200:203], v[184:187], v[20:23]
	v_mfma_f32_16x16x32_bf16 v[16:19], v[208:211], v[184:187], v[16:19]
	v_mfma_f32_16x16x32_bf16 v[4:7], v[200:203], v[192:195], v[4:7]
	v_mfma_f32_16x16x32_bf16 v[0:3], v[208:211], v[192:195], v[0:3]
	v_mfma_f32_16x16x32_bf16 v[52:55], v[204:207], v[148:151], v[52:55]
	v_mfma_f32_16x16x32_bf16 v[48:51], v[232:235], v[148:151], v[48:51]
	v_mfma_f32_16x16x32_bf16 v[36:39], v[204:207], v[156:159], v[36:39]
	v_mfma_f32_16x16x32_bf16 v[32:35], v[232:235], v[156:159], v[32:35]
	v_mfma_f32_16x16x32_bf16 v[20:23], v[204:207], v[188:191], v[20:23]
	v_mfma_f32_16x16x32_bf16 v[16:19], v[232:235], v[188:191], v[16:19]
	v_mfma_f32_16x16x32_bf16 v[4:7], v[204:207], v[196:199], v[4:7]
	v_mfma_f32_16x16x32_bf16 v[0:3], v[232:235], v[196:199], v[0:3]
	s_add_i32 s72, s72, 2
	s_add_u32 s34, s34, 0x100
	s_addc_u32 s35, s35, 0
	s_add_u32 s71, s71, 0x100
	s_addc_u32 s52, s52, 0
	s_cmp_gt_u32 s72, 13
	s_barrier
	s_cbranch_scc0 .LBB0_794
	s_cmp_lt_u32 s101, 0x100
	s_cbranch_scc0 .Lxa_5
	s_barrier

; #define PG8_STAGE(bufoff, gbase, voff) do { _Pragma("unroll") for (int _i = 0; _i < 2; ++_i) \
;     __builtin_amdgcn_global_load_lds((const unsigned*)((const char*)(gbase) + (voff)[_i]), (LAS unsigned*)(lds + (bufoff) + ldsw + _i * 8192), 16, 0, 0); } while (0)
; #define PG8_LDA(dst, b, h) do { _Pragma("unroll") for (int m = 0; m < 4; ++m) _Pragma("unroll") for (int k = 0; k < 2; ++k) dst[m][k] = *(const LAS bf16x8*)(lds + PG8_SA(b, h) + aoff + m * 2048 + k * 1024); } while (0)
; #define PG8_LDB(dst, b, h) do { _Pragma("unroll") for (int n = 0; n < 2; ++n) _Pragma("unroll") for (int k = 0; k < 2; ++k) dst[n][k] = *(const LAS bf16x8*)(lds + PG8_SB(b, h) + boff + n * 2048 + k * 1024); } while (0)
; #define PG8_MMA(ai, bj, At, Bt) do { __builtin_amdgcn_s_setprio(1); _Pragma("unroll") for (int m = 0; m < 4; ++m) _Pragma("unroll") for (int n = 0; n < 2; ++n) _Pragma("unroll") for (int k = 0; k < 2; ++k) \
;     acc[ai][bj][m][n] = __builtin_amdgcn_mfma_f32_16x16x32_bf16(Bt[n][k], At[m][k], acc[ai][bj][m][n], 0, 0, 0); __builtin_amdgcn_s_setprio(0); } while (0)
; #define PG8_WAIT_V(n) asm volatile("s_waitcnt vmcnt(" #n ")" ::: "memory")
; #define PG8_WAIT_L(n) asm volatile("s_waitcnt lgkmcnt(" #n ")" ::: "memory")
; #define PG8_BAR __builtin_amdgcn_s_barrier()
; template <class Epi, class Sched>
; __device__ __forceinline__ void gemm_phase(LAS unsigned char* lds, const Gemm g, const Sched& S, const Epi& E) {
;     ...
;     for (int t = 0; t < nt; t += 2) {
;       const bool last = (t == nt - 2);
;       const char* a1 = cA + (size_t)(t + 1) * kstep;
;       const char* a2 = last ? nA : cA + (size_t)(t + 2) * kstep; const char* b2 = last ? nB : cB + (size_t)(t + 2) * kstep;
;       const char* a3 = a2 + kstep; const char* b3 = b2 + kstep;
;       if (last && has_next) S.a_ready(nxt);
;       PG8_LDB(B0, 0, 0); PG8_SCHED; PG8_LDA(At, 0, 0); PG8_STAGE(PG8_SA(1, 1), a1 + hstep, voffA);
;       PG8_WAIT_L(8); PG8_BAR; PG8_WAIT_L(0); PG8_MMA(0, 0, At, B0); PG8_BAR; PG8_SCHED;
;       PG8_LDB(B1, 0, 1); PG8_STAGE(PG8_SB(0, 0), b2, voffB);
;       PG8_BAR; PG8_WAIT_L(0); PG8_MMA(0, 1, At, B1); PG8_BAR;
;       PG8_LDA(At, 0, 1); PG8_STAGE(PG8_SA(0, 0), a2, voffA);
;       PG8_BAR; PG8_WAIT_L(0); PG8_MMA(1, 0, At, B0); PG8_BAR; PG8_SCHED;
;       PG8_STAGE(PG8_SB(0, 1), b2 + hstep, voffB);
;       PG8_WAIT_V(6); PG8_BAR; PG8_MMA(1, 1, At, B1); PG8_BAR;
.Lxs_e6:
.LBB0_863:
	s_add_u32 s48, s34, 0xfffc0080
	s_addc_u32 s49, s35, -1
	s_add_i32 s74, 0, 0x10000
	v_add_u32_e32 v140, s74, v202
	ds_read_b128 v[128:131], v140
	ds_read_b128 v[132:135], v140 offset:1024
	ds_read_b128 v[136:139], v140 offset:2048
	ds_read_b128 v[140:143], v140 offset:3072
	s_cmp_eq_u32 s73, 12
	s_cselect_b32 s49, s37, s49
	s_cselect_b32 s48, s68, s48
	s_cselect_b32 vcc_hi, s23, s72
	s_cselect_b32 vcc_lo, s69, s52
	s_add_i32 m0, s51, 0xc000
	ds_read_b128 v[144:147], v203
	ds_read_b128 v[148:151], v203 offset:1024
	ds_read_b128 v[152:155], v203 offset:2048
	ds_read_b128 v[186:189], v203 offset:3072
	ds_read_b128 v[190:193], v203 offset:4096
	ds_read_b128 v[194:197], v203 offset:5120
	ds_read_b128 v[198:201], v203 offset:6144
	ds_read_b128 v[204:207], v203 offset:7168
	global_load_lds_dwordx4 v182, s[34:35]
	s_add_i32 m0, s51, 0xe000
	s_nop 0
	global_load_lds_dwordx4 v184, s[34:35]
	s_waitcnt lgkmcnt(8)
	s_barrier
	s_waitcnt lgkmcnt(0)
	s_waitcnt lgkmcnt(0)
	v_mfma_f32_16x16x32_bf16 v[124:127], v[128:131], v[144:147], v[124:127]
	v_mfma_f32_16x16x32_bf16 v[120:123], v[136:139], v[144:147], v[120:123]
	v_mfma_f32_16x16x32_bf16 v[108:111], v[128:131], v[152:155], v[108:111]
	v_mfma_f32_16x16x32_bf16 v[104:107], v[136:139], v[152:155], v[104:107]
	v_mfma_f32_16x16x32_bf16 v[92:95], v[128:131], v[190:193], v[92:95]
	v_mfma_f32_16x16x32_bf16 v[88:91], v[136:139], v[190:193], v[88:91]
	v_mfma_f32_16x16x32_bf16 v[76:79], v[128:131], v[198:201], v[76:79]
	v_mfma_f32_16x16x32_bf16 v[72:75], v[136:139], v[198:201], v[72:75]
	v_mfma_f32_16x16x32_bf16 v[124:127], v[132:135], v[148:151], v[124:127]
	v_mfma_f32_16x16x32_bf16 v[120:123], v[140:143], v[148:151], v[120:123]
	v_mfma_f32_16x16x32_bf16 v[108:111], v[132:135], v[186:189], v[108:111]
	v_mfma_f32_16x16x32_bf16 v[104:107], v[140:143], v[186:189], v[104:107]
	v_mfma_f32_16x16x32_bf16 v[92:95], v[132:135], v[194:197], v[92:95]
	v_mfma_f32_16x16x32_bf16 v[88:91], v[140:143], v[194:197], v[88:91]
	v_mfma_f32_16x16x32_bf16 v[76:79], v[132:135], v[204:207], v[76:79]
	v_mfma_f32_16x16x32_bf16 v[72:75], v[140:143], v[204:207], v[72:75]
	s_barrier
	s_add_i32 s76, 0, 0x14000
	s_add_i32 s74, s74, s7
	v_add_u32_e32 v160, s76, v202
	s_mov_b32 m0, s74
	ds_read_b128 v[208:211], v160
	ds_read_b128 v[226:229], v160 offset:1024
	ds_read_b128 v[232:235], v160 offset:2048
	ds_read_b128 v[236:239], v160 offset:3072
	global_load_lds_dwordx4 v174, vcc
	s_add_i32 m0, s74, 0x2000
	s_nop 0
	global_load_lds_dwordx4 v156, vcc
	s_barrier
	s_waitcnt lgkmcnt(0)
	s_waitcnt lgkmcnt(0)
	v_mfma_f32_16x16x32_bf16 v[116:119], v[208:211], v[144:147], v[116:119]
	v_mfma_f32_16x16x32_bf16 v[112:115], v[232:235], v[144:147], v[112:115]
	v_mfma_f32_16x16x32_bf16 v[100:103], v[208:211], v[152:155], v[100:103]
	v_mfma_f32_16x16x32_bf16 v[96:99], v[232:235], v[152:155], v[96:99]
	v_mfma_f32_16x16x32_bf16 v[84:87], v[208:211], v[190:193], v[84:87]
	v_mfma_f32_16x16x32_bf16 v[80:83], v[232:235], v[190:193], v[80:83]
	v_mfma_f32_16x16x32_bf16 v[68:71], v[208:211], v[198:201], v[68:71]
	v_mfma_f32_16x16x32_bf16 v[64:67], v[232:235], v[198:201], v[64:67]
	v_mfma_f32_16x16x32_bf16 v[116:119], v[226:229], v[148:151], v[116:119]
	v_mfma_f32_16x16x32_bf16 v[112:115], v[236:239], v[148:151], v[112:115]
	v_mfma_f32_16x16x32_bf16 v[100:103], v[226:229], v[186:189], v[100:103]
	v_mfma_f32_16x16x32_bf16 v[96:99], v[236:239], v[186:189], v[96:99]
	v_mfma_f32_16x16x32_bf16 v[84:87], v[226:229], v[194:197], v[84:87]
	v_mfma_f32_16x16x32_bf16 v[80:83], v[236:239], v[194:197], v[80:83]
	v_mfma_f32_16x16x32_bf16 v[68:71], v[226:229], v[204:207], v[68:71]
	v_mfma_f32_16x16x32_bf16 v[64:67], v[236:239], v[204:207], v[64:67]
	s_mov_b32 m0, s51
	v_lshl_add_u64 v[240:241], s[48:49], 0, v[176:177]
	s_barrier
	ds_read_b128 v[144:147], v203 offset:16384
	ds_read_b128 v[148:151], v203 offset:17408
	ds_read_b128 v[152:155], v203 offset:18432
	ds_read_b128 v[186:189], v203 offset:19456
	ds_read_b128 v[190:193], v203 offset:20480
	ds_read_b128 v[194:197], v203 offset:21504
	ds_read_b128 v[198:201], v203 offset:22528
	ds_read_b128 v[204:207], v203 offset:23552
	global_load_lds_dwordx4 v176, s[48:49]
	v_lshl_add_u64 v[242:243], s[48:49], 0, v[158:159]
	s_mov_b32 m0, s62
	s_nop 0
	global_load_lds_dwordx4 v158, s[48:49]
	s_barrier
	s_waitcnt lgkmcnt(0)
	s_waitcnt lgkmcnt(0)
	v_mfma_f32_16x16x32_bf16 v[60:63], v[128:131], v[144:147], v[60:63]
	v_mfma_f32_16x16x32_bf16 v[56:59], v[136:139], v[144:147], v[56:59]
	v_mfma_f32_16x16x32_bf16 v[44:47], v[128:131], v[152:155], v[44:47]
	v_mfma_f32_16x16x32_bf16 v[40:43], v[136:139], v[152:155], v[40:43]
	v_mfma_f32_16x16x32_bf16 v[28:31], v[128:131], v[190:193], v[28:31]
	v_mfma_f32_16x16x32_bf16 v[24:27], v[136:139], v[190:193], v[24:27]
	v_mfma_f32_16x16x32_bf16 v[12:15], v[128:131], v[198:201], v[12:15]
	v_mfma_f32_16x16x32_bf16 v[8:11], v[136:139], v[198:201], v[8:11]
	v_mfma_f32_16x16x32_bf16 v[60:63], v[132:135], v[148:151], v[60:63]
	v_mfma_f32_16x16x32_bf16 v[56:59], v[140:143], v[148:151], v[56:59]
	v_mfma_f32_16x16x32_bf16 v[44:47], v[132:135], v[186:189], v[44:47]
	v_mfma_f32_16x16x32_bf16 v[40:43], v[140:143], v[186:189], v[40:43]
	v_mfma_f32_16x16x32_bf16 v[28:31], v[132:135], v[194:197], v[28:31]
	v_mfma_f32_16x16x32_bf16 v[24:27], v[140:143], v[194:197], v[24:27]
	v_mfma_f32_16x16x32_bf16 v[12:15], v[132:135], v[204:207], v[12:15]
	v_mfma_f32_16x16x32_bf16 v[8:11], v[140:143], v[204:207], v[8:11]
	s_barrier
	s_add_u32 s74, vcc_lo, 0x40000
	s_addc_u32 s75, vcc_hi, 0
	s_add_i32 s76, s76, s7
	s_mov_b32 m0, s76
	s_nop 0
	global_load_lds_dwordx4 v174, s[74:75]
	s_add_i32 m0, s76, 0x2000
	s_nop 0
	global_load_lds_dwordx4 v156, s[74:75]
	s_waitcnt vmcnt(6)
	s_barrier
; #define PG8_STAGE(bufoff, gbase, voff) do { _Pragma("unroll") for (int _i = 0; _i < 2; ++_i) \
;     __builtin_amdgcn_global_load_lds((const unsigned*)((const char*)(gbase) + (voff)[_i]), (LAS unsigned*)(lds + (bufoff) + ldsw + _i * 8192), 16, 0, 0); } while (0)
; #define PG8_LDA(dst, b, h) do { _Pragma("unroll") for (int m = 0; m < 4; ++m) _Pragma("unroll") for (int k = 0; k < 2; ++k) dst[m][k] = *(const LAS bf16x8*)(lds + PG8_SA(b, h) + aoff + m * 2048 + k * 1024); } while (0)
; #define PG8_LDB(dst, b, h) do { _Pragma("unroll") for (int n = 0; n < 2; ++n) _Pragma("unroll") for (int k = 0; k < 2; ++k) dst[n][k] = *(const LAS bf16x8*)(lds + PG8_SB(b, h) + boff + n * 2048 + k * 1024); } while (0)
; #define PG8_MMA(ai, bj, At, Bt) do { __builtin_amdgcn_s_setprio(1); _Pragma("unroll") for (int m = 0; m < 4; ++m) _Pragma("unroll") for (int n = 0; n < 2; ++n) _Pragma("unroll") for (int k = 0; k < 2; ++k) \
;     acc[ai][bj][m][n] = __builtin_amdgcn_mfma_f32_16x16x32_bf16(Bt[n][k], At[m][k], acc[ai][bj][m][n], 0, 0, 0); __builtin_amdgcn_s_setprio(0); } while (0)
; #define PG8_WAIT_V(n) asm volatile("s_waitcnt vmcnt(" #n ")" ::: "memory")
; #define PG8_WAIT_L(n) asm volatile("s_waitcnt lgkmcnt(" #n ")" ::: "memory")
; #define PG8_BAR __builtin_amdgcn_s_barrier()
; #define PG8_SCHED __builtin_amdgcn_sched_barrier(0)
; template <class Epi, class Sched>
; __device__ __forceinline__ void gemm_phase(LAS unsigned char* lds, const Gemm g, const Sched& S, const Epi& E) {
;     ...
;       PG8_WAIT_V(6); PG8_BAR; PG8_MMA(1, 1, At, B1); PG8_BAR;
;       PG8_LDB(B0, 1, 0); PG8_SCHED; PG8_LDA(At, 1, 0); PG8_STAGE(PG8_SA(0, 1), a2 + hstep, voffA);
;       PG8_WAIT_L(8); PG8_BAR; PG8_WAIT_L(0); PG8_MMA(0, 0, At, B0); PG8_BAR; PG8_SCHED;
;       PG8_LDB(B1, 1, 1); PG8_STAGE(PG8_SB(1, 0), b3, voffB);
	v_mfma_f32_16x16x32_bf16 v[52:55], v[208:211], v[144:147], v[52:55]
	v_mfma_f32_16x16x32_bf16 v[48:51], v[232:235], v[144:147], v[48:51]
	v_mfma_f32_16x16x32_bf16 v[36:39], v[208:211], v[152:155], v[36:39]
	v_mfma_f32_16x16x32_bf16 v[32:35], v[232:235], v[152:155], v[32:35]
	v_mfma_f32_16x16x32_bf16 v[20:23], v[208:211], v[190:193], v[20:23]
	v_mfma_f32_16x16x32_bf16 v[16:19], v[232:235], v[190:193], v[16:19]
	v_mfma_f32_16x16x32_bf16 v[4:7], v[208:211], v[198:201], v[4:7]
	v_mfma_f32_16x16x32_bf16 v[0:3], v[232:235], v[198:201], v[0:3]
	v_mfma_f32_16x16x32_bf16 v[52:55], v[226:229], v[148:151], v[52:55]
	v_mfma_f32_16x16x32_bf16 v[48:51], v[236:239], v[148:151], v[48:51]
	v_mfma_f32_16x16x32_bf16 v[36:39], v[226:229], v[186:189], v[36:39]
	v_mfma_f32_16x16x32_bf16 v[32:35], v[236:239], v[186:189], v[32:35]
	v_mfma_f32_16x16x32_bf16 v[20:23], v[226:229], v[194:197], v[20:23]
	v_mfma_f32_16x16x32_bf16 v[16:19], v[236:239], v[194:197], v[16:19]
	v_mfma_f32_16x16x32_bf16 v[4:7], v[226:229], v[204:207], v[4:7]
	v_mfma_f32_16x16x32_bf16 v[0:3], v[236:239], v[204:207], v[0:3]
	s_add_i32 s74, 0, 0x18000
	v_add_u32_e32 v140, s74, v202
	s_barrier
	ds_read_b128 v[128:131], v140
	ds_read_b128 v[132:135], v140 offset:1024
	ds_read_b128 v[136:139], v140 offset:2048
	ds_read_b128 v[140:143], v140 offset:3072
	s_add_u32 s48, s48, 0x40000
	s_addc_u32 s49, s49, 0
	s_mov_b32 m0, s63
	ds_read_b128 v[144:147], v203 offset:32768
	ds_read_b128 v[148:151], v203 offset:33792
	ds_read_b128 v[152:155], v203 offset:34816
	ds_read_b128 v[186:189], v203 offset:35840
	ds_read_b128 v[190:193], v203 offset:36864
	ds_read_b128 v[194:197], v203 offset:37888
	ds_read_b128 v[198:201], v203 offset:38912
	ds_read_b128 v[204:207], v203 offset:39936
	global_load_lds_dwordx4 v176, s[48:49]
	s_mov_b32 m0, s64
	s_nop 0
	global_load_lds_dwordx4 v158, s[48:49]
	s_waitcnt lgkmcnt(8)
	s_barrier
	s_waitcnt lgkmcnt(0)
	s_waitcnt lgkmcnt(0)
	v_mfma_f32_16x16x32_bf16 v[124:127], v[128:131], v[144:147], v[124:127]
	v_mfma_f32_16x16x32_bf16 v[120:123], v[136:139], v[144:147], v[120:123]
	v_mfma_f32_16x16x32_bf16 v[108:111], v[128:131], v[152:155], v[108:111]
	v_mfma_f32_16x16x32_bf16 v[104:107], v[136:139], v[152:155], v[104:107]
	v_mfma_f32_16x16x32_bf16 v[92:95], v[128:131], v[190:193], v[92:95]
	v_mfma_f32_16x16x32_bf16 v[88:91], v[136:139], v[190:193], v[88:91]
	v_mfma_f32_16x16x32_bf16 v[76:79], v[128:131], v[198:201], v[76:79]
	v_mfma_f32_16x16x32_bf16 v[72:75], v[136:139], v[198:201], v[72:75]
	v_mfma_f32_16x16x32_bf16 v[124:127], v[132:135], v[148:151], v[124:127]
	v_mfma_f32_16x16x32_bf16 v[120:123], v[140:143], v[148:151], v[120:123]
	v_mfma_f32_16x16x32_bf16 v[108:111], v[132:135], v[186:189], v[108:111]
	v_mfma_f32_16x16x32_bf16 v[104:107], v[140:143], v[186:189], v[104:107]
	v_mfma_f32_16x16x32_bf16 v[92:95], v[132:135], v[194:197], v[92:95]
	v_mfma_f32_16x16x32_bf16 v[88:91], v[140:143], v[194:197], v[88:91]
	v_mfma_f32_16x16x32_bf16 v[76:79], v[132:135], v[204:207], v[76:79]
	v_mfma_f32_16x16x32_bf16 v[72:75], v[140:143], v[204:207], v[72:75]
	s_barrier
	s_add_i32 s75, 0, 0x1c000
	s_add_i32 s48, s74, s7
	v_add_u32_e32 v160, s75, v202
	s_add_u32 s98, vcc_lo, s80
	s_addc_u32 s99, vcc_hi, s81
	s_mov_b32 m0, s48
	ds_read_b128 v[208:211], v160
	ds_read_b128 v[226:229], v160 offset:1024
	ds_read_b128 v[232:235], v160 offset:2048
	ds_read_b128 v[236:239], v160 offset:3072
	global_load_lds_dwordx4 v174, s[98:99]
	v_lshl_add_u64 v[212:213], v[222:223], 0, s[80:81]
	s_add_i32 m0, s48, 0x2000
	s_nop 0
	global_load_lds_dwordx4 v156, s[98:99]
	s_barrier
; #define PG8_STAGE(bufoff, gbase, voff) do { _Pragma("unroll") for (int _i = 0; _i < 2; ++_i) \
;     __builtin_amdgcn_global_load_lds((const unsigned*)((const char*)(gbase) + (voff)[_i]), (LAS unsigned*)(lds + (bufoff) + ldsw + _i * 8192), 16, 0, 0); } while (0)
; #define PG8_LDA(dst, b, h) do { _Pragma("unroll") for (int m = 0; m < 4; ++m) _Pragma("unroll") for (int k = 0; k < 2; ++k) dst[m][k] = *(const LAS bf16x8*)(lds + PG8_SA(b, h) + aoff + m * 2048 + k * 1024); } while (0)
; #define PG8_MMA(ai, bj, At, Bt) do { __builtin_amdgcn_s_setprio(1); _Pragma("unroll") for (int m = 0; m < 4; ++m) _Pragma("unroll") for (int n = 0; n < 2; ++n) _Pragma("unroll") for (int k = 0; k < 2; ++k) \
;     acc[ai][bj][m][n] = __builtin_amdgcn_mfma_f32_16x16x32_bf16(Bt[n][k], At[m][k], acc[ai][bj][m][n], 0, 0, 0); __builtin_amdgcn_s_setprio(0); } while (0)
; #define PG8_WAIT_V(n) asm volatile("s_waitcnt vmcnt(" #n ")" ::: "memory")
; #define PG8_WAIT_L(n) asm volatile("s_waitcnt lgkmcnt(" #n ")" ::: "memory")
; #define PG8_BAR __builtin_amdgcn_s_barrier()
; #define PG8_SCHED __builtin_amdgcn_sched_barrier(0)
; template <class Epi, class Sched>
; __device__ __forceinline__ void gemm_phase(LAS unsigned char* lds, const Gemm g, const Sched& S, const Epi& E) {
;     ...
;       PG8_BAR; PG8_WAIT_L(0); PG8_MMA(0, 1, At, B1); PG8_BAR;
;       PG8_LDA(At, 1, 1); PG8_STAGE(PG8_SA(1, 0), a3, voffA);
;       PG8_BAR; PG8_WAIT_L(0); PG8_MMA(1, 0, At, B0); PG8_BAR; PG8_SCHED;
;       PG8_STAGE(PG8_SB(1, 1), b3 + hstep, voffB);
;       PG8_WAIT_V(6); PG8_BAR; PG8_MMA(1, 1, At, B1); PG8_BAR;
	s_waitcnt lgkmcnt(0)
	s_waitcnt lgkmcnt(0)
	v_mfma_f32_16x16x32_bf16 v[116:119], v[208:211], v[144:147], v[116:119]
	v_mfma_f32_16x16x32_bf16 v[112:115], v[232:235], v[144:147], v[112:115]
	v_mfma_f32_16x16x32_bf16 v[100:103], v[208:211], v[152:155], v[100:103]
	v_mfma_f32_16x16x32_bf16 v[96:99], v[232:235], v[152:155], v[96:99]
	v_mfma_f32_16x16x32_bf16 v[84:87], v[208:211], v[190:193], v[84:87]
	v_mfma_f32_16x16x32_bf16 v[80:83], v[232:235], v[190:193], v[80:83]
	v_mfma_f32_16x16x32_bf16 v[68:71], v[208:211], v[198:201], v[68:71]
	v_mfma_f32_16x16x32_bf16 v[64:67], v[232:235], v[198:201], v[64:67]
	v_mfma_f32_16x16x32_bf16 v[116:119], v[226:229], v[148:151], v[116:119]
	v_mfma_f32_16x16x32_bf16 v[112:115], v[236:239], v[148:151], v[112:115]
	v_mfma_f32_16x16x32_bf16 v[100:103], v[226:229], v[186:189], v[100:103]
	v_mfma_f32_16x16x32_bf16 v[96:99], v[236:239], v[186:189], v[96:99]
	v_mfma_f32_16x16x32_bf16 v[84:87], v[226:229], v[194:197], v[84:87]
	v_mfma_f32_16x16x32_bf16 v[80:83], v[236:239], v[194:197], v[80:83]
	v_mfma_f32_16x16x32_bf16 v[68:71], v[226:229], v[204:207], v[68:71]
	v_mfma_f32_16x16x32_bf16 v[64:67], v[236:239], v[204:207], v[64:67]
	s_mov_b32 m0, s65
	v_lshl_add_u64 v[212:213], v[240:241], 0, s[80:81]
	s_barrier
	ds_read_b128 v[144:147], v203 offset:49152
	ds_read_b128 v[148:151], v203 offset:50176
	ds_read_b128 v[152:155], v203 offset:51200
	ds_read_b128 v[186:189], v203 offset:52224
	ds_read_b128 v[190:193], v203 offset:53248
	ds_read_b128 v[194:197], v203 offset:54272
	ds_read_b128 v[198:201], v203 offset:55296
	ds_read_b128 v[204:207], v203 offset:56320
	global_load_lds_dwordx4 v[212:213], off
	v_lshl_add_u64 v[212:213], v[242:243], 0, s[80:81]
	s_mov_b32 m0, s70
	s_nop 0
	global_load_lds_dwordx4 v[212:213], off
	s_barrier
	s_waitcnt lgkmcnt(0)
	s_waitcnt lgkmcnt(0)
	v_mfma_f32_16x16x32_bf16 v[60:63], v[128:131], v[144:147], v[60:63]
	v_mfma_f32_16x16x32_bf16 v[56:59], v[136:139], v[144:147], v[56:59]
	v_mfma_f32_16x16x32_bf16 v[44:47], v[128:131], v[152:155], v[44:47]
	v_mfma_f32_16x16x32_bf16 v[40:43], v[136:139], v[152:155], v[40:43]
	v_mfma_f32_16x16x32_bf16 v[28:31], v[128:131], v[190:193], v[28:31]
	v_mfma_f32_16x16x32_bf16 v[24:27], v[136:139], v[190:193], v[24:27]
	v_mfma_f32_16x16x32_bf16 v[12:15], v[128:131], v[198:201], v[12:15]
	v_mfma_f32_16x16x32_bf16 v[8:11], v[136:139], v[198:201], v[8:11]
	v_mfma_f32_16x16x32_bf16 v[60:63], v[132:135], v[148:151], v[60:63]
	v_mfma_f32_16x16x32_bf16 v[56:59], v[140:143], v[148:151], v[56:59]
	v_mfma_f32_16x16x32_bf16 v[44:47], v[132:135], v[186:189], v[44:47]
	v_mfma_f32_16x16x32_bf16 v[40:43], v[140:143], v[186:189], v[40:43]
	v_mfma_f32_16x16x32_bf16 v[28:31], v[132:135], v[194:197], v[28:31]
	v_mfma_f32_16x16x32_bf16 v[24:27], v[140:143], v[194:197], v[24:27]
	v_mfma_f32_16x16x32_bf16 v[12:15], v[132:135], v[204:207], v[12:15]
	v_mfma_f32_16x16x32_bf16 v[8:11], v[140:143], v[204:207], v[8:11]
	s_barrier
	s_add_u32 s48, vcc_lo, 0x40080
	s_addc_u32 s49, vcc_hi, 0
	s_add_i32 s74, s75, s7
	s_mov_b32 m0, s74
	s_nop 0
	global_load_lds_dwordx4 v174, s[48:49]
	s_add_i32 m0, s74, 0x2000
	s_nop 0
	global_load_lds_dwordx4 v156, s[48:49]
	s_waitcnt vmcnt(6)
	s_barrier
	v_mfma_f32_16x16x32_bf16 v[52:55], v[208:211], v[144:147], v[52:55]
	v_mfma_f32_16x16x32_bf16 v[48:51], v[232:235], v[144:147], v[48:51]
	v_mfma_f32_16x16x32_bf16 v[36:39], v[208:211], v[152:155], v[36:39]
	v_mfma_f32_16x16x32_bf16 v[32:35], v[232:235], v[152:155], v[32:35]
	v_mfma_f32_16x16x32_bf16 v[20:23], v[208:211], v[190:193], v[20:23]
	v_mfma_f32_16x16x32_bf16 v[16:19], v[232:235], v[190:193], v[16:19]
	v_mfma_f32_16x16x32_bf16 v[4:7], v[208:211], v[198:201], v[4:7]
	v_mfma_f32_16x16x32_bf16 v[0:3], v[232:235], v[198:201], v[0:3]
	v_mfma_f32_16x16x32_bf16 v[52:55], v[226:229], v[148:151], v[52:55]
	v_mfma_f32_16x16x32_bf16 v[48:51], v[236:239], v[148:151], v[48:51]
	v_mfma_f32_16x16x32_bf16 v[36:39], v[226:229], v[186:189], v[36:39]
	v_mfma_f32_16x16x32_bf16 v[32:35], v[236:239], v[186:189], v[32:35]
	v_mfma_f32_16x16x32_bf16 v[20:23], v[226:229], v[194:197], v[20:23]
	v_mfma_f32_16x16x32_bf16 v[16:19], v[236:239], v[194:197], v[16:19]
	v_mfma_f32_16x16x32_bf16 v[4:7], v[226:229], v[204:207], v[4:7]
	v_mfma_f32_16x16x32_bf16 v[0:3], v[236:239], v[204:207], v[0:3]
	s_add_i32 s73, s73, 2
	s_add_u32 s34, s34, 0x100
	s_addc_u32 s35, s35, 0
	s_add_u32 s52, s52, 0x100
	s_addc_u32 s72, s72, 0
	s_cmp_gt_u32 s73, 13
	s_barrier
	s_cbranch_scc0 .LBB0_863
	s_cmp_lt_u32 s101, 0x100
	s_cbranch_scc0 .Lxa_6
	s_barrier

; #define PG8_STAGE(bufoff, gbase, voff) do { _Pragma("unroll") for (int _i = 0; _i < 2; ++_i) \
;     __builtin_amdgcn_global_load_lds((const unsigned*)((const char*)(gbase) + (voff)[_i]), (LAS unsigned*)(lds + (bufoff) + ldsw + _i * 8192), 16, 0, 0); } while (0)
; #define PG8_LDA(dst, b, h) do { _Pragma("unroll") for (int m = 0; m < 4; ++m) _Pragma("unroll") for (int k = 0; k < 2; ++k) dst[m][k] = *(const LAS bf16x8*)(lds + PG8_SA(b, h) + aoff + m * 2048 + k * 1024); } while (0)
; #define PG8_LDB(dst, b, h) do { _Pragma("unroll") for (int n = 0; n < 2; ++n) _Pragma("unroll") for (int k = 0; k < 2; ++k) dst[n][k] = *(const LAS bf16x8*)(lds + PG8_SB(b, h) + boff + n * 2048 + k * 1024); } while (0)
; #define PG8_MMA(ai, bj, At, Bt) do { __builtin_amdgcn_s_setprio(1); _Pragma("unroll") for (int m = 0; m < 4; ++m) _Pragma("unroll") for (int n = 0; n < 2; ++n) _Pragma("unroll") for (int k = 0; k < 2; ++k) \
;     acc[ai][bj][m][n] = __builtin_amdgcn_mfma_f32_16x16x32_bf16(Bt[n][k], At[m][k], acc[ai][bj][m][n], 0, 0, 0); __builtin_amdgcn_s_setprio(0); } while (0)
; #define PG8_WAIT_V(n) asm volatile("s_waitcnt vmcnt(" #n ")" ::: "memory")
; #define PG8_WAIT_L(n) asm volatile("s_waitcnt lgkmcnt(" #n ")" ::: "memory")
; #define PG8_BAR __builtin_amdgcn_s_barrier()
; template <class Epi, class Sched>
; __device__ __forceinline__ void gemm_phase(LAS unsigned char* lds, const Gemm g, const Sched& S, const Epi& E) {
;     ...
;     for (int t = 0; t < nt; t += 2) {
;       const bool last = (t == nt - 2);
;       const char* a1 = cA + (size_t)(t + 1) * kstep;
;       const char* a2 = last ? nA : cA + (size_t)(t + 2) * kstep; const char* b2 = last ? nB : cB + (size_t)(t + 2) * kstep;
;       const char* a3 = a2 + kstep; const char* b3 = b2 + kstep;
;       if (last && has_next) S.a_ready(nxt);
;       PG8_LDB(B0, 0, 0); PG8_SCHED; PG8_LDA(At, 0, 0); PG8_STAGE(PG8_SA(1, 1), a1 + hstep, voffA);
;       PG8_WAIT_L(8); PG8_BAR; PG8_WAIT_L(0); PG8_MMA(0, 0, At, B0); PG8_BAR; PG8_SCHED;
;       PG8_LDB(B1, 0, 1); PG8_STAGE(PG8_SB(0, 0), b2, voffB);
;       PG8_BAR; PG8_WAIT_L(0); PG8_MMA(0, 1, At, B1); PG8_BAR;
;       PG8_LDA(At, 0, 1); PG8_STAGE(PG8_SA(0, 0), a2, voffA);
;       PG8_BAR; PG8_WAIT_L(0); PG8_MMA(1, 0, At, B0); PG8_BAR; PG8_SCHED;
;       PG8_STAGE(PG8_SB(0, 1), b2 + hstep, voffB);
;       PG8_WAIT_V(6); PG8_BAR; PG8_MMA(1, 1, At, B1); PG8_BAR;
.Lxs_e7:
.LBB0_890:
	s_add_u32 s44, s42, 0xfffc0080
	s_addc_u32 s45, s43, -1
	s_add_i32 s74, 0, 0x10000
	v_add_u32_e32 v143, s74, v141
	ds_read_b128 v[144:147], v143
	ds_read_b128 v[148:151], v143 offset:1024
	ds_read_b128 v[152:155], v143 offset:2048
	ds_read_b128 v[156:159], v143 offset:3072
	s_cmp_eq_u32 s73, 12
	s_cselect_b32 s49, s35, s45
	s_cselect_b32 s48, s70, s44
	s_cselect_b32 s45, s23, s72
	s_cselect_b32 s44, s71, s52
	s_add_i32 m0, s12, 0xc000
	ds_read_b128 v[174:177], v142
	ds_read_b128 v[178:181], v142 offset:1024
	ds_read_b128 v[182:185], v142 offset:2048
	ds_read_b128 v[186:189], v142 offset:3072
	ds_read_b128 v[190:193], v142 offset:4096
	ds_read_b128 v[194:197], v142 offset:5120
	ds_read_b128 v[198:201], v142 offset:6144
	ds_read_b128 v[202:205], v142 offset:7168
	global_load_lds_dwordx4 v136, s[42:43]
	s_add_i32 m0, s12, 0xe000
	s_nop 0
	global_load_lds_dwordx4 v138, s[42:43]
	s_waitcnt lgkmcnt(8)
	s_barrier
	s_waitcnt lgkmcnt(0)
	s_waitcnt lgkmcnt(0)
	v_mfma_f32_16x16x32_bf16 v[124:127], v[144:147], v[174:177], v[124:127]
	v_mfma_f32_16x16x32_bf16 v[120:123], v[152:155], v[174:177], v[120:123]
	v_mfma_f32_16x16x32_bf16 v[116:119], v[144:147], v[182:185], v[116:119]
	v_mfma_f32_16x16x32_bf16 v[112:115], v[152:155], v[182:185], v[112:115]
	v_mfma_f32_16x16x32_bf16 v[100:103], v[144:147], v[190:193], v[100:103]
	v_mfma_f32_16x16x32_bf16 v[96:99], v[152:155], v[190:193], v[96:99]
	v_mfma_f32_16x16x32_bf16 v[84:87], v[144:147], v[198:201], v[84:87]
	v_mfma_f32_16x16x32_bf16 v[80:83], v[152:155], v[198:201], v[80:83]
	v_mfma_f32_16x16x32_bf16 v[124:127], v[148:151], v[178:181], v[124:127]
	v_mfma_f32_16x16x32_bf16 v[120:123], v[156:159], v[178:181], v[120:123]
	v_mfma_f32_16x16x32_bf16 v[116:119], v[148:151], v[186:189], v[116:119]
	v_mfma_f32_16x16x32_bf16 v[112:115], v[156:159], v[186:189], v[112:115]
	v_mfma_f32_16x16x32_bf16 v[100:103], v[148:151], v[194:197], v[100:103]
	v_mfma_f32_16x16x32_bf16 v[96:99], v[156:159], v[194:197], v[96:99]
	v_mfma_f32_16x16x32_bf16 v[84:87], v[148:151], v[202:205], v[84:87]
	v_mfma_f32_16x16x32_bf16 v[80:83], v[156:159], v[202:205], v[80:83]
	s_barrier
	s_add_i32 s76, 0, 0x14000
	s_add_i32 s74, s74, s7
	v_add_u32_e32 v143, s76, v141
	s_mov_b32 m0, s74
	ds_read_b128 v[206:209], v143
	ds_read_b128 v[210:213], v143 offset:1024
	ds_read_b128 v[226:229], v143 offset:2048
	ds_read_b128 v[232:235], v143 offset:3072
	global_load_lds_dwordx4 v132, s[44:45]
	s_add_i32 m0, s74, 0x2000
	s_nop 0
	global_load_lds_dwordx4 v128, s[44:45]
	s_barrier
	s_waitcnt lgkmcnt(0)
	s_waitcnt lgkmcnt(0)
	v_mfma_f32_16x16x32_bf16 v[108:111], v[206:209], v[174:177], v[108:111]
	v_mfma_f32_16x16x32_bf16 v[104:107], v[226:229], v[174:177], v[104:107]
	v_mfma_f32_16x16x32_bf16 v[92:95], v[206:209], v[182:185], v[92:95]
	v_mfma_f32_16x16x32_bf16 v[88:91], v[226:229], v[182:185], v[88:91]
	v_mfma_f32_16x16x32_bf16 v[76:79], v[206:209], v[190:193], v[76:79]
	v_mfma_f32_16x16x32_bf16 v[72:75], v[226:229], v[190:193], v[72:75]
	v_mfma_f32_16x16x32_bf16 v[68:71], v[206:209], v[198:201], v[68:71]
	v_mfma_f32_16x16x32_bf16 v[64:67], v[226:229], v[198:201], v[64:67]
	v_mfma_f32_16x16x32_bf16 v[108:111], v[210:213], v[178:181], v[108:111]
	v_mfma_f32_16x16x32_bf16 v[104:107], v[232:235], v[178:181], v[104:107]
	v_mfma_f32_16x16x32_bf16 v[92:95], v[210:213], v[186:189], v[92:95]
	v_mfma_f32_16x16x32_bf16 v[88:91], v[232:235], v[186:189], v[88:91]
	v_mfma_f32_16x16x32_bf16 v[76:79], v[210:213], v[194:197], v[76:79]
	v_mfma_f32_16x16x32_bf16 v[72:75], v[232:235], v[194:197], v[72:75]
	v_mfma_f32_16x16x32_bf16 v[68:71], v[210:213], v[202:205], v[68:71]
	v_mfma_f32_16x16x32_bf16 v[64:67], v[232:235], v[202:205], v[64:67]
	s_mov_b32 m0, s12
	v_lshl_add_u64 v[238:239], s[48:49], 0, v[134:135]
	s_barrier
	ds_read_b128 v[174:177], v142 offset:16384
	ds_read_b128 v[178:181], v142 offset:17408
	ds_read_b128 v[182:185], v142 offset:18432
	ds_read_b128 v[186:189], v142 offset:19456
	ds_read_b128 v[190:193], v142 offset:20480
	ds_read_b128 v[194:197], v142 offset:21504
	ds_read_b128 v[198:201], v142 offset:22528
	ds_read_b128 v[202:205], v142 offset:23552
	global_load_lds_dwordx4 v134, s[48:49]
	v_lshl_add_u64 v[240:241], s[48:49], 0, v[130:131]
	s_mov_b32 m0, s13
	s_nop 0
	global_load_lds_dwordx4 v130, s[48:49]
	s_barrier
	s_waitcnt lgkmcnt(0)
	s_waitcnt lgkmcnt(0)
	v_mfma_f32_16x16x32_bf16 v[60:63], v[144:147], v[174:177], v[60:63]
	v_mfma_f32_16x16x32_bf16 v[56:59], v[152:155], v[174:177], v[56:59]
	v_mfma_f32_16x16x32_bf16 v[52:55], v[144:147], v[182:185], v[52:55]
	v_mfma_f32_16x16x32_bf16 v[48:51], v[152:155], v[182:185], v[48:51]
	v_mfma_f32_16x16x32_bf16 v[36:39], v[144:147], v[190:193], v[36:39]
	v_mfma_f32_16x16x32_bf16 v[32:35], v[152:155], v[190:193], v[32:35]
	v_mfma_f32_16x16x32_bf16 v[20:23], v[144:147], v[198:201], v[20:23]
	v_mfma_f32_16x16x32_bf16 v[16:19], v[152:155], v[198:201], v[16:19]
	v_mfma_f32_16x16x32_bf16 v[60:63], v[148:151], v[178:181], v[60:63]
	v_mfma_f32_16x16x32_bf16 v[56:59], v[156:159], v[178:181], v[56:59]
	v_mfma_f32_16x16x32_bf16 v[52:55], v[148:151], v[186:189], v[52:55]
	v_mfma_f32_16x16x32_bf16 v[48:51], v[156:159], v[186:189], v[48:51]
	v_mfma_f32_16x16x32_bf16 v[36:39], v[148:151], v[194:197], v[36:39]
	v_mfma_f32_16x16x32_bf16 v[32:35], v[156:159], v[194:197], v[32:35]
	v_mfma_f32_16x16x32_bf16 v[20:23], v[148:151], v[202:205], v[20:23]
	v_mfma_f32_16x16x32_bf16 v[16:19], v[156:159], v[202:205], v[16:19]
	s_barrier
	s_add_u32 s74, s44, 0x40000
	s_addc_u32 s75, s45, 0
	s_add_i32 s76, s76, s7
	s_mov_b32 m0, s76
	s_nop 0
	global_load_lds_dwordx4 v132, s[74:75]
	s_add_i32 m0, s76, 0x2000
	s_nop 0
	global_load_lds_dwordx4 v128, s[74:75]
	s_waitcnt vmcnt(6)
	s_barrier
; #define PG8_STAGE(bufoff, gbase, voff) do { _Pragma("unroll") for (int _i = 0; _i < 2; ++_i) \
;     __builtin_amdgcn_global_load_lds((const unsigned*)((const char*)(gbase) + (voff)[_i]), (LAS unsigned*)(lds + (bufoff) + ldsw + _i * 8192), 16, 0, 0); } while (0)
; #define PG8_LDA(dst, b, h) do { _Pragma("unroll") for (int m = 0; m < 4; ++m) _Pragma("unroll") for (int k = 0; k < 2; ++k) dst[m][k] = *(const LAS bf16x8*)(lds + PG8_SA(b, h) + aoff + m * 2048 + k * 1024); } while (0)
; #define PG8_LDB(dst, b, h) do { _Pragma("unroll") for (int n = 0; n < 2; ++n) _Pragma("unroll") for (int k = 0; k < 2; ++k) dst[n][k] = *(const LAS bf16x8*)(lds + PG8_SB(b, h) + boff + n * 2048 + k * 1024); } while (0)
; #define PG8_MMA(ai, bj, At, Bt) do { __builtin_amdgcn_s_setprio(1); _Pragma("unroll") for (int m = 0; m < 4; ++m) _Pragma("unroll") for (int n = 0; n < 2; ++n) _Pragma("unroll") for (int k = 0; k < 2; ++k) \
;     acc[ai][bj][m][n] = __builtin_amdgcn_mfma_f32_16x16x32_bf16(Bt[n][k], At[m][k], acc[ai][bj][m][n], 0, 0, 0); __builtin_amdgcn_s_setprio(0); } while (0)
; #define PG8_WAIT_V(n) asm volatile("s_waitcnt vmcnt(" #n ")" ::: "memory")
; #define PG8_WAIT_L(n) asm volatile("s_waitcnt lgkmcnt(" #n ")" ::: "memory")
; #define PG8_BAR __builtin_amdgcn_s_barrier()
; #define PG8_SCHED __builtin_amdgcn_sched_barrier(0)
; template <class Epi, class Sched>
; __device__ __forceinline__ void gemm_phase(LAS unsigned char* lds, const Gemm g, const Sched& S, const Epi& E) {
;     ...
;       PG8_WAIT_V(6); PG8_BAR; PG8_MMA(1, 1, At, B1); PG8_BAR;
;       PG8_LDB(B0, 1, 0); PG8_SCHED; PG8_LDA(At, 1, 0); PG8_STAGE(PG8_SA(0, 1), a2 + hstep, voffA);
;       PG8_WAIT_L(8); PG8_BAR; PG8_WAIT_L(0); PG8_MMA(0, 0, At, B0); PG8_BAR; PG8_SCHED;
;       PG8_LDB(B1, 1, 1); PG8_STAGE(PG8_SB(1, 0), b3, voffB);
	v_mfma_f32_16x16x32_bf16 v[44:47], v[206:209], v[174:177], v[44:47]
	v_mfma_f32_16x16x32_bf16 v[40:43], v[226:229], v[174:177], v[40:43]
	v_mfma_f32_16x16x32_bf16 v[28:31], v[206:209], v[182:185], v[28:31]
	v_mfma_f32_16x16x32_bf16 v[24:27], v[226:229], v[182:185], v[24:27]
	v_mfma_f32_16x16x32_bf16 v[12:15], v[206:209], v[190:193], v[12:15]
	v_mfma_f32_16x16x32_bf16 v[8:11], v[226:229], v[190:193], v[8:11]
	v_mfma_f32_16x16x32_bf16 v[4:7], v[206:209], v[198:201], v[4:7]
	v_mfma_f32_16x16x32_bf16 v[0:3], v[226:229], v[198:201], v[0:3]
	v_mfma_f32_16x16x32_bf16 v[44:47], v[210:213], v[178:181], v[44:47]
	v_mfma_f32_16x16x32_bf16 v[40:43], v[232:235], v[178:181], v[40:43]
	v_mfma_f32_16x16x32_bf16 v[28:31], v[210:213], v[186:189], v[28:31]
	v_mfma_f32_16x16x32_bf16 v[24:27], v[232:235], v[186:189], v[24:27]
	v_mfma_f32_16x16x32_bf16 v[12:15], v[210:213], v[194:197], v[12:15]
	v_mfma_f32_16x16x32_bf16 v[8:11], v[232:235], v[194:197], v[8:11]
	v_mfma_f32_16x16x32_bf16 v[4:7], v[210:213], v[202:205], v[4:7]
	v_mfma_f32_16x16x32_bf16 v[0:3], v[232:235], v[202:205], v[0:3]
	s_add_i32 s74, 0, 0x18000
	v_add_u32_e32 v143, s74, v141
	s_barrier
	ds_read_b128 v[144:147], v143
	ds_read_b128 v[148:151], v143 offset:1024
	ds_read_b128 v[152:155], v143 offset:2048
	ds_read_b128 v[156:159], v143 offset:3072
	s_add_u32 s48, s48, 0x40000
	s_addc_u32 s49, s49, 0
	s_mov_b32 m0, s51
	ds_read_b128 v[174:177], v142 offset:32768
	ds_read_b128 v[178:181], v142 offset:33792
	ds_read_b128 v[182:185], v142 offset:34816
	ds_read_b128 v[186:189], v142 offset:35840
	ds_read_b128 v[190:193], v142 offset:36864
	ds_read_b128 v[194:197], v142 offset:37888
	ds_read_b128 v[198:201], v142 offset:38912
	ds_read_b128 v[202:205], v142 offset:39936
	global_load_lds_dwordx4 v134, s[48:49]
	s_mov_b32 m0, s62
	s_nop 0
	global_load_lds_dwordx4 v130, s[48:49]
	s_waitcnt lgkmcnt(8)
	s_barrier
	s_waitcnt lgkmcnt(0)
	s_waitcnt lgkmcnt(0)
	v_mfma_f32_16x16x32_bf16 v[124:127], v[144:147], v[174:177], v[124:127]
	v_mfma_f32_16x16x32_bf16 v[120:123], v[152:155], v[174:177], v[120:123]
	v_mfma_f32_16x16x32_bf16 v[116:119], v[144:147], v[182:185], v[116:119]
	v_mfma_f32_16x16x32_bf16 v[112:115], v[152:155], v[182:185], v[112:115]
	v_mfma_f32_16x16x32_bf16 v[100:103], v[144:147], v[190:193], v[100:103]
	v_mfma_f32_16x16x32_bf16 v[96:99], v[152:155], v[190:193], v[96:99]
	v_mfma_f32_16x16x32_bf16 v[84:87], v[144:147], v[198:201], v[84:87]
	v_mfma_f32_16x16x32_bf16 v[80:83], v[152:155], v[198:201], v[80:83]
	v_mfma_f32_16x16x32_bf16 v[124:127], v[148:151], v[178:181], v[124:127]
	v_mfma_f32_16x16x32_bf16 v[120:123], v[156:159], v[178:181], v[120:123]
	v_mfma_f32_16x16x32_bf16 v[116:119], v[148:151], v[186:189], v[116:119]
	v_mfma_f32_16x16x32_bf16 v[112:115], v[156:159], v[186:189], v[112:115]
	v_mfma_f32_16x16x32_bf16 v[100:103], v[148:151], v[194:197], v[100:103]
	v_mfma_f32_16x16x32_bf16 v[96:99], v[156:159], v[194:197], v[96:99]
	v_mfma_f32_16x16x32_bf16 v[84:87], v[148:151], v[202:205], v[84:87]
	v_mfma_f32_16x16x32_bf16 v[80:83], v[156:159], v[202:205], v[80:83]
	s_barrier
	s_add_i32 s48, 0, 0x1c000
	s_add_i32 s49, s74, s7
	v_add_u32_e32 v143, s48, v141
	s_add_u32 s98, s44, s80
	s_addc_u32 s99, s45, s81
	s_mov_b32 m0, s49
	ds_read_b128 v[206:209], v143
	ds_read_b128 v[210:213], v143 offset:1024
	ds_read_b128 v[226:229], v143 offset:2048
	ds_read_b128 v[232:235], v143 offset:3072
	global_load_lds_dwordx4 v132, s[98:99]
	v_lshl_add_u64 v[222:223], v[236:237], 0, s[80:81]
	s_add_i32 m0, s49, 0x2000
	s_nop 0
	global_load_lds_dwordx4 v128, s[98:99]
	s_barrier
; #define PG8_STAGE(bufoff, gbase, voff) do { _Pragma("unroll") for (int _i = 0; _i < 2; ++_i) \
;     __builtin_amdgcn_global_load_lds((const unsigned*)((const char*)(gbase) + (voff)[_i]), (LAS unsigned*)(lds + (bufoff) + ldsw + _i * 8192), 16, 0, 0); } while (0)
; #define PG8_LDA(dst, b, h) do { _Pragma("unroll") for (int m = 0; m < 4; ++m) _Pragma("unroll") for (int k = 0; k < 2; ++k) dst[m][k] = *(const LAS bf16x8*)(lds + PG8_SA(b, h) + aoff + m * 2048 + k * 1024); } while (0)
; #define PG8_MMA(ai, bj, At, Bt) do { __builtin_amdgcn_s_setprio(1); _Pragma("unroll") for (int m = 0; m < 4; ++m) _Pragma("unroll") for (int n = 0; n < 2; ++n) _Pragma("unroll") for (int k = 0; k < 2; ++k) \
;     acc[ai][bj][m][n] = __builtin_amdgcn_mfma_f32_16x16x32_bf16(Bt[n][k], At[m][k], acc[ai][bj][m][n], 0, 0, 0); __builtin_amdgcn_s_setprio(0); } while (0)
; #define PG8_WAIT_V(n) asm volatile("s_waitcnt vmcnt(" #n ")" ::: "memory")
; #define PG8_WAIT_L(n) asm volatile("s_waitcnt lgkmcnt(" #n ")" ::: "memory")
; #define PG8_BAR __builtin_amdgcn_s_barrier()
; #define PG8_SCHED __builtin_amdgcn_sched_barrier(0)
; template <class Epi, class Sched>
; __device__ __forceinline__ void gemm_phase(LAS unsigned char* lds, const Gemm g, const Sched& S, const Epi& E) {
;     ...
;       PG8_BAR; PG8_WAIT_L(0); PG8_MMA(0, 1, At, B1); PG8_BAR;
;       PG8_LDA(At, 1, 1); PG8_STAGE(PG8_SA(1, 0), a3, voffA);
;       PG8_BAR; PG8_WAIT_L(0); PG8_MMA(1, 0, At, B0); PG8_BAR; PG8_SCHED;
;       PG8_STAGE(PG8_SB(1, 1), b3 + hstep, voffB);
;       PG8_WAIT_V(6); PG8_BAR; PG8_MMA(1, 1, At, B1); PG8_BAR;
	s_waitcnt lgkmcnt(0)
	s_waitcnt lgkmcnt(0)
	v_mfma_f32_16x16x32_bf16 v[108:111], v[206:209], v[174:177], v[108:111]
	v_mfma_f32_16x16x32_bf16 v[104:107], v[226:229], v[174:177], v[104:107]
	v_mfma_f32_16x16x32_bf16 v[92:95], v[206:209], v[182:185], v[92:95]
	v_mfma_f32_16x16x32_bf16 v[88:91], v[226:229], v[182:185], v[88:91]
	v_mfma_f32_16x16x32_bf16 v[76:79], v[206:209], v[190:193], v[76:79]
	v_mfma_f32_16x16x32_bf16 v[72:75], v[226:229], v[190:193], v[72:75]
	v_mfma_f32_16x16x32_bf16 v[68:71], v[206:209], v[198:201], v[68:71]
	v_mfma_f32_16x16x32_bf16 v[64:67], v[226:229], v[198:201], v[64:67]
	v_mfma_f32_16x16x32_bf16 v[108:111], v[210:213], v[178:181], v[108:111]
	v_mfma_f32_16x16x32_bf16 v[104:107], v[232:235], v[178:181], v[104:107]
	v_mfma_f32_16x16x32_bf16 v[92:95], v[210:213], v[186:189], v[92:95]
	v_mfma_f32_16x16x32_bf16 v[88:91], v[232:235], v[186:189], v[88:91]
	v_mfma_f32_16x16x32_bf16 v[76:79], v[210:213], v[194:197], v[76:79]
	v_mfma_f32_16x16x32_bf16 v[72:75], v[232:235], v[194:197], v[72:75]
	v_mfma_f32_16x16x32_bf16 v[68:71], v[210:213], v[202:205], v[68:71]
	v_mfma_f32_16x16x32_bf16 v[64:67], v[232:235], v[202:205], v[64:67]
	s_mov_b32 m0, s63
	v_lshl_add_u64 v[222:223], v[238:239], 0, s[80:81]
	s_barrier
	ds_read_b128 v[174:177], v142 offset:49152
	ds_read_b128 v[178:181], v142 offset:50176
	ds_read_b128 v[182:185], v142 offset:51200
	ds_read_b128 v[186:189], v142 offset:52224
	ds_read_b128 v[190:193], v142 offset:53248
	ds_read_b128 v[194:197], v142 offset:54272
	ds_read_b128 v[198:201], v142 offset:55296
	ds_read_b128 v[202:205], v142 offset:56320
	global_load_lds_dwordx4 v[222:223], off
	v_lshl_add_u64 v[222:223], v[240:241], 0, s[80:81]
	s_mov_b32 m0, s64
	s_nop 0
	global_load_lds_dwordx4 v[222:223], off
	s_barrier
	s_waitcnt lgkmcnt(0)
	s_waitcnt lgkmcnt(0)
	v_mfma_f32_16x16x32_bf16 v[60:63], v[144:147], v[174:177], v[60:63]
	v_mfma_f32_16x16x32_bf16 v[56:59], v[152:155], v[174:177], v[56:59]
	v_mfma_f32_16x16x32_bf16 v[52:55], v[144:147], v[182:185], v[52:55]
	v_mfma_f32_16x16x32_bf16 v[48:51], v[152:155], v[182:185], v[48:51]
	v_mfma_f32_16x16x32_bf16 v[36:39], v[144:147], v[190:193], v[36:39]
	v_mfma_f32_16x16x32_bf16 v[32:35], v[152:155], v[190:193], v[32:35]
	v_mfma_f32_16x16x32_bf16 v[20:23], v[144:147], v[198:201], v[20:23]
	v_mfma_f32_16x16x32_bf16 v[16:19], v[152:155], v[198:201], v[16:19]
	v_mfma_f32_16x16x32_bf16 v[60:63], v[148:151], v[178:181], v[60:63]
	v_mfma_f32_16x16x32_bf16 v[56:59], v[156:159], v[178:181], v[56:59]
	v_mfma_f32_16x16x32_bf16 v[52:55], v[148:151], v[186:189], v[52:55]
	v_mfma_f32_16x16x32_bf16 v[48:51], v[156:159], v[186:189], v[48:51]
	v_mfma_f32_16x16x32_bf16 v[36:39], v[148:151], v[194:197], v[36:39]
	v_mfma_f32_16x16x32_bf16 v[32:35], v[156:159], v[194:197], v[32:35]
	v_mfma_f32_16x16x32_bf16 v[20:23], v[148:151], v[202:205], v[20:23]
	v_mfma_f32_16x16x32_bf16 v[16:19], v[156:159], v[202:205], v[16:19]
	s_barrier
	s_add_u32 s44, s44, 0x40080
	s_addc_u32 s45, s45, 0
	s_add_i32 s48, s48, s7
	s_mov_b32 m0, s48
	s_nop 0
	global_load_lds_dwordx4 v132, s[44:45]
	s_add_i32 m0, s48, 0x2000
	s_nop 0
	global_load_lds_dwordx4 v128, s[44:45]
	s_waitcnt vmcnt(6)
	s_barrier
	v_mfma_f32_16x16x32_bf16 v[44:47], v[206:209], v[174:177], v[44:47]
	v_mfma_f32_16x16x32_bf16 v[40:43], v[226:229], v[174:177], v[40:43]
	v_mfma_f32_16x16x32_bf16 v[28:31], v[206:209], v[182:185], v[28:31]
	v_mfma_f32_16x16x32_bf16 v[24:27], v[226:229], v[182:185], v[24:27]
	v_mfma_f32_16x16x32_bf16 v[12:15], v[206:209], v[190:193], v[12:15]
	v_mfma_f32_16x16x32_bf16 v[8:11], v[226:229], v[190:193], v[8:11]
	v_mfma_f32_16x16x32_bf16 v[4:7], v[206:209], v[198:201], v[4:7]
	v_mfma_f32_16x16x32_bf16 v[0:3], v[226:229], v[198:201], v[0:3]
	v_mfma_f32_16x16x32_bf16 v[44:47], v[210:213], v[178:181], v[44:47]
	v_mfma_f32_16x16x32_bf16 v[40:43], v[232:235], v[178:181], v[40:43]
	v_mfma_f32_16x16x32_bf16 v[28:31], v[210:213], v[186:189], v[28:31]
	v_mfma_f32_16x16x32_bf16 v[24:27], v[232:235], v[186:189], v[24:27]
	v_mfma_f32_16x16x32_bf16 v[12:15], v[210:213], v[194:197], v[12:15]
	v_mfma_f32_16x16x32_bf16 v[8:11], v[232:235], v[194:197], v[8:11]
	v_mfma_f32_16x16x32_bf16 v[4:7], v[210:213], v[202:205], v[4:7]
	v_mfma_f32_16x16x32_bf16 v[0:3], v[232:235], v[202:205], v[0:3]
	s_add_i32 s73, s73, 2
	s_add_u32 s42, s42, 0x100
	s_addc_u32 s43, s43, 0
	s_add_u32 s52, s52, 0x100
	s_addc_u32 s72, s72, 0
	s_cmp_gt_u32 s73, 13
	s_barrier
	s_cbranch_scc0 .LBB0_890
	s_cmp_lt_u32 s101, 0x100
	s_cbranch_scc0 .Lxa_7
	s_barrier

; #define PG8_STAGE(bufoff, gbase, voff) do { _Pragma("unroll") for (int _i = 0; _i < 2; ++_i) \
;     __builtin_amdgcn_global_load_lds((const unsigned*)((const char*)(gbase) + (voff)[_i]), (LAS unsigned*)(lds + (bufoff) + ldsw + _i * 8192), 16, 0, 0); } while (0)
; #define PG8_LDA(dst, b, h) do { _Pragma("unroll") for (int m = 0; m < 4; ++m) _Pragma("unroll") for (int k = 0; k < 2; ++k) dst[m][k] = *(const LAS bf16x8*)(lds + PG8_SA(b, h) + aoff + m * 2048 + k * 1024); } while (0)
; #define PG8_LDB(dst, b, h) do { _Pragma("unroll") for (int n = 0; n < 2; ++n) _Pragma("unroll") for (int k = 0; k < 2; ++k) dst[n][k] = *(const LAS bf16x8*)(lds + PG8_SB(b, h) + boff + n * 2048 + k * 1024); } while (0)
; #define PG8_MMA(ai, bj, At, Bt) do { __builtin_amdgcn_s_setprio(1); _Pragma("unroll") for (int m = 0; m < 4; ++m) _Pragma("unroll") for (int n = 0; n < 2; ++n) _Pragma("unroll") for (int k = 0; k < 2; ++k) \
;     acc[ai][bj][m][n] = __builtin_amdgcn_mfma_f32_16x16x32_bf16(Bt[n][k], At[m][k], acc[ai][bj][m][n], 0, 0, 0); __builtin_amdgcn_s_setprio(0); } while (0)
; #define PG8_WAIT_L(n) asm volatile("s_waitcnt lgkmcnt(" #n ")" ::: "memory")
; #define PG8_BAR __builtin_amdgcn_s_barrier()
; #define PG8_SCHED __builtin_amdgcn_sched_barrier(0)
; template <class Epi, class Sched>
; __device__ __forceinline__ void gemm_phase(LAS unsigned char* lds, const Gemm g, const Sched& S, const Epi& E) {
;     ...
;     for (int t = 0; t < nt; t += 2) {
;       const bool last = (t == nt - 2);
;       const char* a1 = cA + (size_t)(t + 1) * kstep;
;       const char* a2 = last ? nA : cA + (size_t)(t + 2) * kstep; const char* b2 = last ? nB : cB + (size_t)(t + 2) * kstep;
;       const char* a3 = a2 + kstep; const char* b3 = b2 + kstep;
;       if (last && has_next) S.a_ready(nxt);
;       PG8_LDB(B0, 0, 0); PG8_SCHED; PG8_LDA(At, 0, 0); PG8_STAGE(PG8_SA(1, 1), a1 + hstep, voffA);
;       PG8_WAIT_L(8); PG8_BAR; PG8_WAIT_L(0); PG8_MMA(0, 0, At, B0); PG8_BAR; PG8_SCHED;
;       PG8_LDB(B1, 0, 1); PG8_STAGE(PG8_SB(0, 0), b2, voffB);
;       PG8_BAR; PG8_WAIT_L(0); PG8_MMA(0, 1, At, B1); PG8_BAR;
;       PG8_LDA(At, 0, 1); PG8_STAGE(PG8_SA(0, 0), a2, voffA);
;       PG8_BAR; PG8_WAIT_L(0); PG8_MMA(1, 0, At, B0); PG8_BAR; PG8_SCHED;
.Lxs_e8:
.LBB0_968:
	s_add_u32 s44, s42, 0xfffc0080
	s_addc_u32 s45, s43, -1
	s_add_i32 s74, 0, 0x10000
	v_add_u32_e32 v140, s74, v143
	ds_read_b128 v[146:149], v140
	ds_read_b128 v[150:153], v140 offset:1024
	ds_read_b128 v[154:157], v140 offset:2048
	ds_read_b128 v[174:177], v140 offset:3072
	s_cmp_eq_u32 s73, 12
	s_cselect_b32 s49, s35, s45
	s_cselect_b32 s48, s71, s44
	s_cselect_b32 s45, s23, s72
	s_cselect_b32 s44, vcc_lo, s52
	s_add_i32 m0, s12, 0xc000
	ds_read_b128 v[178:181], v145
	ds_read_b128 v[182:185], v145 offset:1024
	ds_read_b128 v[186:189], v145 offset:2048
	ds_read_b128 v[190:193], v145 offset:3072
	ds_read_b128 v[194:197], v145 offset:4096
	ds_read_b128 v[198:201], v145 offset:5120
	ds_read_b128 v[202:205], v145 offset:6144
	ds_read_b128 v[206:209], v145 offset:7168
	global_load_lds_dwordx4 v136, s[42:43]
	s_add_i32 m0, s12, 0xe000
	s_nop 0
	global_load_lds_dwordx4 v138, s[42:43]
	s_waitcnt lgkmcnt(8)
	s_barrier
	s_waitcnt lgkmcnt(0)
	s_waitcnt lgkmcnt(0)
	v_mfma_f32_16x16x32_bf16 v[124:127], v[146:149], v[178:181], v[124:127]
	v_mfma_f32_16x16x32_bf16 v[120:123], v[154:157], v[178:181], v[120:123]
	v_mfma_f32_16x16x32_bf16 v[116:119], v[146:149], v[186:189], v[116:119]
	v_mfma_f32_16x16x32_bf16 v[108:111], v[154:157], v[186:189], v[108:111]
	v_mfma_f32_16x16x32_bf16 v[96:99], v[146:149], v[194:197], v[96:99]
	v_mfma_f32_16x16x32_bf16 v[88:91], v[154:157], v[194:197], v[88:91]
	v_mfma_f32_16x16x32_bf16 v[84:87], v[146:149], v[202:205], v[84:87]
	v_mfma_f32_16x16x32_bf16 v[76:79], v[154:157], v[202:205], v[76:79]
	v_mfma_f32_16x16x32_bf16 v[124:127], v[150:153], v[182:185], v[124:127]
	v_mfma_f32_16x16x32_bf16 v[120:123], v[174:177], v[182:185], v[120:123]
	v_mfma_f32_16x16x32_bf16 v[116:119], v[150:153], v[190:193], v[116:119]
	v_mfma_f32_16x16x32_bf16 v[108:111], v[174:177], v[190:193], v[108:111]
	v_mfma_f32_16x16x32_bf16 v[96:99], v[150:153], v[198:201], v[96:99]
	v_mfma_f32_16x16x32_bf16 v[88:91], v[174:177], v[198:201], v[88:91]
	v_mfma_f32_16x16x32_bf16 v[84:87], v[150:153], v[206:209], v[84:87]
	v_mfma_f32_16x16x32_bf16 v[76:79], v[174:177], v[206:209], v[76:79]
	s_barrier
	s_add_i32 s76, 0, 0x14000
	v_add_u32_e32 v140, s76, v143
	s_add_i32 s74, s74, s7
	ds_read_b128 v[210:213], v140
	ds_read_b128 v[226:229], v140 offset:1024
	ds_read_b128 v[232:235], v140 offset:2048
	ds_read_b128 v[236:239], v140 offset:3072
	v_lshl_add_u64 v[140:141], s[44:45], 0, v[132:133]
	s_mov_b32 m0, s74
	v_lshl_add_u64 v[158:159], s[44:45], 0, v[128:129]
	global_load_lds_dwordx4 v[140:141], off
	s_add_i32 m0, s74, 0x2000
	s_nop 0
	global_load_lds_dwordx4 v[158:159], off
	s_barrier
	s_waitcnt lgkmcnt(0)
	s_waitcnt lgkmcnt(0)
	v_mfma_f32_16x16x32_bf16 v[112:115], v[210:213], v[178:181], v[112:115]
	v_mfma_f32_16x16x32_bf16 v[104:107], v[232:235], v[178:181], v[104:107]
	v_mfma_f32_16x16x32_bf16 v[100:103], v[210:213], v[186:189], v[100:103]
	v_mfma_f32_16x16x32_bf16 v[92:95], v[232:235], v[186:189], v[92:95]
	v_mfma_f32_16x16x32_bf16 v[80:83], v[210:213], v[194:197], v[80:83]
	v_mfma_f32_16x16x32_bf16 v[72:75], v[232:235], v[194:197], v[72:75]
	v_mfma_f32_16x16x32_bf16 v[68:71], v[210:213], v[202:205], v[68:71]
	v_mfma_f32_16x16x32_bf16 v[64:67], v[232:235], v[202:205], v[64:67]
	v_mfma_f32_16x16x32_bf16 v[112:115], v[226:229], v[182:185], v[112:115]
	v_mfma_f32_16x16x32_bf16 v[104:107], v[236:239], v[182:185], v[104:107]
	v_mfma_f32_16x16x32_bf16 v[100:103], v[226:229], v[190:193], v[100:103]
	v_mfma_f32_16x16x32_bf16 v[92:95], v[236:239], v[190:193], v[92:95]
	v_mfma_f32_16x16x32_bf16 v[80:83], v[226:229], v[198:201], v[80:83]
	v_mfma_f32_16x16x32_bf16 v[72:75], v[236:239], v[198:201], v[72:75]
	v_mfma_f32_16x16x32_bf16 v[68:71], v[226:229], v[206:209], v[68:71]
	v_mfma_f32_16x16x32_bf16 v[64:67], v[236:239], v[206:209], v[64:67]
	s_mov_b32 m0, s12
	v_lshl_add_u64 v[222:223], s[48:49], 0, v[134:135]
	s_barrier
	ds_read_b128 v[178:181], v145 offset:16384
	ds_read_b128 v[182:185], v145 offset:17408
	ds_read_b128 v[186:189], v145 offset:18432
	ds_read_b128 v[190:193], v145 offset:19456
	ds_read_b128 v[194:197], v145 offset:20480
	ds_read_b128 v[198:201], v145 offset:21504
	ds_read_b128 v[202:205], v145 offset:22528
	ds_read_b128 v[206:209], v145 offset:23552
	global_load_lds_dwordx4 v134, s[48:49]
	v_lshl_add_u64 v[240:241], s[48:49], 0, v[130:131]
	s_mov_b32 m0, s13
	s_nop 0
	global_load_lds_dwordx4 v130, s[48:49]
	s_barrier
	s_waitcnt lgkmcnt(0)
	s_waitcnt lgkmcnt(0)
	v_mfma_f32_16x16x32_bf16 v[60:63], v[146:149], v[178:181], v[60:63]
	v_mfma_f32_16x16x32_bf16 v[56:59], v[154:157], v[178:181], v[56:59]
	v_mfma_f32_16x16x32_bf16 v[52:55], v[146:149], v[186:189], v[52:55]
	v_mfma_f32_16x16x32_bf16 v[44:47], v[154:157], v[186:189], v[44:47]
	v_mfma_f32_16x16x32_bf16 v[32:35], v[146:149], v[194:197], v[32:35]
	v_mfma_f32_16x16x32_bf16 v[24:27], v[154:157], v[194:197], v[24:27]
	v_mfma_f32_16x16x32_bf16 v[20:23], v[146:149], v[202:205], v[20:23]
	v_mfma_f32_16x16x32_bf16 v[12:15], v[154:157], v[202:205], v[12:15]
	v_mfma_f32_16x16x32_bf16 v[60:63], v[150:153], v[182:185], v[60:63]
	v_mfma_f32_16x16x32_bf16 v[56:59], v[174:177], v[182:185], v[56:59]
	v_mfma_f32_16x16x32_bf16 v[52:55], v[150:153], v[190:193], v[52:55]
	v_mfma_f32_16x16x32_bf16 v[44:47], v[174:177], v[190:193], v[44:47]
	v_mfma_f32_16x16x32_bf16 v[32:35], v[150:153], v[198:201], v[32:35]
	v_mfma_f32_16x16x32_bf16 v[24:27], v[174:177], v[198:201], v[24:27]
	v_mfma_f32_16x16x32_bf16 v[20:23], v[150:153], v[206:209], v[20:23]
	v_mfma_f32_16x16x32_bf16 v[12:15], v[174:177], v[206:209], v[12:15]
	s_barrier
; #define PG8_STAGE(bufoff, gbase, voff) do { _Pragma("unroll") for (int _i = 0; _i < 2; ++_i) \
;     __builtin_amdgcn_global_load_lds((const unsigned*)((const char*)(gbase) + (voff)[_i]), (LAS unsigned*)(lds + (bufoff) + ldsw + _i * 8192), 16, 0, 0); } while (0)
; #define PG8_LDA(dst, b, h) do { _Pragma("unroll") for (int m = 0; m < 4; ++m) _Pragma("unroll") for (int k = 0; k < 2; ++k) dst[m][k] = *(const LAS bf16x8*)(lds + PG8_SA(b, h) + aoff + m * 2048 + k * 1024); } while (0)
; #define PG8_LDB(dst, b, h) do { _Pragma("unroll") for (int n = 0; n < 2; ++n) _Pragma("unroll") for (int k = 0; k < 2; ++k) dst[n][k] = *(const LAS bf16x8*)(lds + PG8_SB(b, h) + boff + n * 2048 + k * 1024); } while (0)
; #define PG8_MMA(ai, bj, At, Bt) do { __builtin_amdgcn_s_setprio(1); _Pragma("unroll") for (int m = 0; m < 4; ++m) _Pragma("unroll") for (int n = 0; n < 2; ++n) _Pragma("unroll") for (int k = 0; k < 2; ++k) \
;     acc[ai][bj][m][n] = __builtin_amdgcn_mfma_f32_16x16x32_bf16(Bt[n][k], At[m][k], acc[ai][bj][m][n], 0, 0, 0); __builtin_amdgcn_s_setprio(0); } while (0)
; #define PG8_WAIT_V(n) asm volatile("s_waitcnt vmcnt(" #n ")" ::: "memory")
; #define PG8_WAIT_L(n) asm volatile("s_waitcnt lgkmcnt(" #n ")" ::: "memory")
; #define PG8_BAR __builtin_amdgcn_s_barrier()
; #define PG8_SCHED __builtin_amdgcn_sched_barrier(0)
; template <class Epi, class Sched>
; __device__ __forceinline__ void gemm_phase(LAS unsigned char* lds, const Gemm g, const Sched& S, const Epi& E) {
;     ...
;       PG8_STAGE(PG8_SB(0, 1), b2 + hstep, voffB);
;       PG8_WAIT_V(6); PG8_BAR; PG8_MMA(1, 1, At, B1); PG8_BAR;
;       PG8_LDB(B0, 1, 0); PG8_SCHED; PG8_LDA(At, 1, 0); PG8_STAGE(PG8_SA(0, 1), a2 + hstep, voffA);
;       PG8_WAIT_L(8); PG8_BAR; PG8_WAIT_L(0); PG8_MMA(0, 0, At, B0); PG8_BAR; PG8_SCHED;
;       PG8_LDB(B1, 1, 1); PG8_STAGE(PG8_SB(1, 0), b3, voffB);
	s_add_u32 s74, s44, 0x40000
	s_addc_u32 s75, s45, 0
	s_add_i32 s76, s76, s7
	s_mov_b32 m0, s76
	s_nop 0
	global_load_lds_dwordx4 v132, s[74:75]
	s_add_i32 m0, s76, 0x2000
	s_nop 0
	global_load_lds_dwordx4 v128, s[74:75]
	s_waitcnt vmcnt(6)
	s_barrier
	v_mfma_f32_16x16x32_bf16 v[48:51], v[210:213], v[178:181], v[48:51]
	v_mfma_f32_16x16x32_bf16 v[40:43], v[232:235], v[178:181], v[40:43]
	v_mfma_f32_16x16x32_bf16 v[36:39], v[210:213], v[186:189], v[36:39]
	v_mfma_f32_16x16x32_bf16 v[28:31], v[232:235], v[186:189], v[28:31]
	v_mfma_f32_16x16x32_bf16 v[16:19], v[210:213], v[194:197], v[16:19]
	v_mfma_f32_16x16x32_bf16 v[8:11], v[232:235], v[194:197], v[8:11]
	v_mfma_f32_16x16x32_bf16 v[4:7], v[210:213], v[202:205], v[4:7]
	v_mfma_f32_16x16x32_bf16 v[0:3], v[232:235], v[202:205], v[0:3]
	v_mfma_f32_16x16x32_bf16 v[48:51], v[226:229], v[182:185], v[48:51]
	v_mfma_f32_16x16x32_bf16 v[40:43], v[236:239], v[182:185], v[40:43]
	v_mfma_f32_16x16x32_bf16 v[36:39], v[226:229], v[190:193], v[36:39]
	v_mfma_f32_16x16x32_bf16 v[28:31], v[236:239], v[190:193], v[28:31]
	v_mfma_f32_16x16x32_bf16 v[16:19], v[226:229], v[198:201], v[16:19]
	v_mfma_f32_16x16x32_bf16 v[8:11], v[236:239], v[198:201], v[8:11]
	v_mfma_f32_16x16x32_bf16 v[4:7], v[226:229], v[206:209], v[4:7]
	v_mfma_f32_16x16x32_bf16 v[0:3], v[236:239], v[206:209], v[0:3]
	s_add_i32 s74, 0, 0x18000
	v_add_u32_e32 v174, s74, v143
	s_barrier
	ds_read_b128 v[146:149], v174
	ds_read_b128 v[150:153], v174 offset:1024
	ds_read_b128 v[154:157], v174 offset:2048
	ds_read_b128 v[174:177], v174 offset:3072
	s_add_u32 s48, s48, 0x40000
	s_addc_u32 s49, s49, 0
	s_mov_b32 m0, s51
	ds_read_b128 v[178:181], v145 offset:32768
	ds_read_b128 v[182:185], v145 offset:33792
	ds_read_b128 v[186:189], v145 offset:34816
	ds_read_b128 v[190:193], v145 offset:35840
	ds_read_b128 v[194:197], v145 offset:36864
	ds_read_b128 v[198:201], v145 offset:37888
	ds_read_b128 v[202:205], v145 offset:38912
	ds_read_b128 v[206:209], v145 offset:39936
	global_load_lds_dwordx4 v134, s[48:49]
	s_mov_b32 m0, s62
	s_nop 0
	global_load_lds_dwordx4 v130, s[48:49]
	s_waitcnt lgkmcnt(8)
	s_barrier
	s_waitcnt lgkmcnt(0)
	s_waitcnt lgkmcnt(0)
	v_mfma_f32_16x16x32_bf16 v[124:127], v[146:149], v[178:181], v[124:127]
	v_mfma_f32_16x16x32_bf16 v[120:123], v[154:157], v[178:181], v[120:123]
	v_mfma_f32_16x16x32_bf16 v[116:119], v[146:149], v[186:189], v[116:119]
	v_mfma_f32_16x16x32_bf16 v[108:111], v[154:157], v[186:189], v[108:111]
	v_mfma_f32_16x16x32_bf16 v[96:99], v[146:149], v[194:197], v[96:99]
	v_mfma_f32_16x16x32_bf16 v[88:91], v[154:157], v[194:197], v[88:91]
	v_mfma_f32_16x16x32_bf16 v[84:87], v[146:149], v[202:205], v[84:87]
	v_mfma_f32_16x16x32_bf16 v[76:79], v[154:157], v[202:205], v[76:79]
	v_mfma_f32_16x16x32_bf16 v[124:127], v[150:153], v[182:185], v[124:127]
	v_mfma_f32_16x16x32_bf16 v[120:123], v[174:177], v[182:185], v[120:123]
	v_mfma_f32_16x16x32_bf16 v[116:119], v[150:153], v[190:193], v[116:119]
	v_mfma_f32_16x16x32_bf16 v[108:111], v[174:177], v[190:193], v[108:111]
	v_mfma_f32_16x16x32_bf16 v[96:99], v[150:153], v[198:201], v[96:99]
	v_mfma_f32_16x16x32_bf16 v[88:91], v[174:177], v[198:201], v[88:91]
	v_mfma_f32_16x16x32_bf16 v[84:87], v[150:153], v[206:209], v[84:87]
	v_mfma_f32_16x16x32_bf16 v[76:79], v[174:177], v[206:209], v[76:79]
	s_barrier
	s_add_i32 s48, 0, 0x1c000
	s_add_i32 s49, s74, s7
	v_add_u32_e32 v225, s48, v143
	s_add_u32 s60, s44, s80
	s_addc_u32 s61, s45, s81
	s_mov_b32 m0, s49
	ds_read_b128 v[210:213], v225
	ds_read_b128 v[226:229], v225 offset:1024
	ds_read_b128 v[232:235], v225 offset:2048
	ds_read_b128 v[236:239], v225 offset:3072
	global_load_lds_dwordx4 v132, s[60:61]
	v_lshl_add_u64 v[140:141], v[158:159], 0, s[80:81]
	s_add_i32 m0, s49, 0x2000
	s_nop 0
	global_load_lds_dwordx4 v128, s[60:61]
	s_barrier
; #define PG8_STAGE(bufoff, gbase, voff) do { _Pragma("unroll") for (int _i = 0; _i < 2; ++_i) \
;     __builtin_amdgcn_global_load_lds((const unsigned*)((const char*)(gbase) + (voff)[_i]), (LAS unsigned*)(lds + (bufoff) + ldsw + _i * 8192), 16, 0, 0); } while (0)
; #define PG8_LDA(dst, b, h) do { _Pragma("unroll") for (int m = 0; m < 4; ++m) _Pragma("unroll") for (int k = 0; k < 2; ++k) dst[m][k] = *(const LAS bf16x8*)(lds + PG8_SA(b, h) + aoff + m * 2048 + k * 1024); } while (0)
; #define PG8_MMA(ai, bj, At, Bt) do { __builtin_amdgcn_s_setprio(1); _Pragma("unroll") for (int m = 0; m < 4; ++m) _Pragma("unroll") for (int n = 0; n < 2; ++n) _Pragma("unroll") for (int k = 0; k < 2; ++k) \
;     acc[ai][bj][m][n] = __builtin_amdgcn_mfma_f32_16x16x32_bf16(Bt[n][k], At[m][k], acc[ai][bj][m][n], 0, 0, 0); __builtin_amdgcn_s_setprio(0); } while (0)
; #define PG8_WAIT_V(n) asm volatile("s_waitcnt vmcnt(" #n ")" ::: "memory")
; #define PG8_WAIT_L(n) asm volatile("s_waitcnt lgkmcnt(" #n ")" ::: "memory")
; #define PG8_BAR __builtin_amdgcn_s_barrier()
; #define PG8_SCHED __builtin_amdgcn_sched_barrier(0)
; template <class Epi, class Sched>
; __device__ __forceinline__ void gemm_phase(LAS unsigned char* lds, const Gemm g, const Sched& S, const Epi& E) {
;     ...
;       PG8_BAR; PG8_WAIT_L(0); PG8_MMA(0, 1, At, B1); PG8_BAR;
;       PG8_LDA(At, 1, 1); PG8_STAGE(PG8_SA(1, 0), a3, voffA);
;       PG8_BAR; PG8_WAIT_L(0); PG8_MMA(1, 0, At, B0); PG8_BAR; PG8_SCHED;
;       PG8_STAGE(PG8_SB(1, 1), b3 + hstep, voffB);
;       PG8_WAIT_V(6); PG8_BAR; PG8_MMA(1, 1, At, B1); PG8_BAR;
	s_waitcnt lgkmcnt(0)
	s_waitcnt lgkmcnt(0)
	v_mfma_f32_16x16x32_bf16 v[112:115], v[210:213], v[178:181], v[112:115]
	v_mfma_f32_16x16x32_bf16 v[104:107], v[232:235], v[178:181], v[104:107]
	v_mfma_f32_16x16x32_bf16 v[100:103], v[210:213], v[186:189], v[100:103]
	v_mfma_f32_16x16x32_bf16 v[92:95], v[232:235], v[186:189], v[92:95]
	v_mfma_f32_16x16x32_bf16 v[80:83], v[210:213], v[194:197], v[80:83]
	v_mfma_f32_16x16x32_bf16 v[72:75], v[232:235], v[194:197], v[72:75]
	v_mfma_f32_16x16x32_bf16 v[68:71], v[210:213], v[202:205], v[68:71]
	v_mfma_f32_16x16x32_bf16 v[64:67], v[232:235], v[202:205], v[64:67]
	v_mfma_f32_16x16x32_bf16 v[112:115], v[226:229], v[182:185], v[112:115]
	v_mfma_f32_16x16x32_bf16 v[104:107], v[236:239], v[182:185], v[104:107]
	v_mfma_f32_16x16x32_bf16 v[100:103], v[226:229], v[190:193], v[100:103]
	v_mfma_f32_16x16x32_bf16 v[92:95], v[236:239], v[190:193], v[92:95]
	v_mfma_f32_16x16x32_bf16 v[80:83], v[226:229], v[198:201], v[80:83]
	v_mfma_f32_16x16x32_bf16 v[72:75], v[236:239], v[198:201], v[72:75]
	v_mfma_f32_16x16x32_bf16 v[68:71], v[226:229], v[206:209], v[68:71]
	v_mfma_f32_16x16x32_bf16 v[64:67], v[236:239], v[206:209], v[64:67]
	s_mov_b32 m0, s63
	v_lshl_add_u64 v[140:141], v[222:223], 0, s[80:81]
	s_barrier
	ds_read_b128 v[178:181], v145 offset:49152
	ds_read_b128 v[182:185], v145 offset:50176
	ds_read_b128 v[186:189], v145 offset:51200
	ds_read_b128 v[190:193], v145 offset:52224
	ds_read_b128 v[194:197], v145 offset:53248
	ds_read_b128 v[198:201], v145 offset:54272
	ds_read_b128 v[202:205], v145 offset:55296
	ds_read_b128 v[206:209], v145 offset:56320
	global_load_lds_dwordx4 v[140:141], off
	v_lshl_add_u64 v[140:141], v[240:241], 0, s[80:81]
	s_mov_b32 m0, s64
	s_nop 0
	global_load_lds_dwordx4 v[140:141], off
	s_barrier
	s_waitcnt lgkmcnt(0)
	s_waitcnt lgkmcnt(0)
	v_mfma_f32_16x16x32_bf16 v[60:63], v[146:149], v[178:181], v[60:63]
	v_mfma_f32_16x16x32_bf16 v[56:59], v[154:157], v[178:181], v[56:59]
	v_mfma_f32_16x16x32_bf16 v[52:55], v[146:149], v[186:189], v[52:55]
	v_mfma_f32_16x16x32_bf16 v[44:47], v[154:157], v[186:189], v[44:47]
	v_mfma_f32_16x16x32_bf16 v[32:35], v[146:149], v[194:197], v[32:35]
	v_mfma_f32_16x16x32_bf16 v[24:27], v[154:157], v[194:197], v[24:27]
	v_mfma_f32_16x16x32_bf16 v[20:23], v[146:149], v[202:205], v[20:23]
	v_mfma_f32_16x16x32_bf16 v[12:15], v[154:157], v[202:205], v[12:15]
	v_mfma_f32_16x16x32_bf16 v[60:63], v[150:153], v[182:185], v[60:63]
	v_mfma_f32_16x16x32_bf16 v[56:59], v[174:177], v[182:185], v[56:59]
	v_mfma_f32_16x16x32_bf16 v[52:55], v[150:153], v[190:193], v[52:55]
	v_mfma_f32_16x16x32_bf16 v[44:47], v[174:177], v[190:193], v[44:47]
	v_mfma_f32_16x16x32_bf16 v[32:35], v[150:153], v[198:201], v[32:35]
	v_mfma_f32_16x16x32_bf16 v[24:27], v[174:177], v[198:201], v[24:27]
	v_mfma_f32_16x16x32_bf16 v[20:23], v[150:153], v[206:209], v[20:23]
	v_mfma_f32_16x16x32_bf16 v[12:15], v[174:177], v[206:209], v[12:15]
	s_barrier
	s_add_u32 s44, s44, 0x40080
	s_addc_u32 s45, s45, 0
	s_add_i32 s48, s48, s7
	s_mov_b32 m0, s48
	s_nop 0
	global_load_lds_dwordx4 v132, s[44:45]
	s_add_i32 m0, s48, 0x2000
	s_nop 0
	global_load_lds_dwordx4 v128, s[44:45]
	s_waitcnt vmcnt(6)
	s_barrier
	v_mfma_f32_16x16x32_bf16 v[48:51], v[210:213], v[178:181], v[48:51]
	v_mfma_f32_16x16x32_bf16 v[40:43], v[232:235], v[178:181], v[40:43]
	v_mfma_f32_16x16x32_bf16 v[36:39], v[210:213], v[186:189], v[36:39]
	v_mfma_f32_16x16x32_bf16 v[28:31], v[232:235], v[186:189], v[28:31]
	v_mfma_f32_16x16x32_bf16 v[16:19], v[210:213], v[194:197], v[16:19]
	v_mfma_f32_16x16x32_bf16 v[8:11], v[232:235], v[194:197], v[8:11]
	v_mfma_f32_16x16x32_bf16 v[4:7], v[210:213], v[202:205], v[4:7]
	v_mfma_f32_16x16x32_bf16 v[0:3], v[232:235], v[202:205], v[0:3]
	v_mfma_f32_16x16x32_bf16 v[48:51], v[226:229], v[182:185], v[48:51]
	v_mfma_f32_16x16x32_bf16 v[40:43], v[236:239], v[182:185], v[40:43]
	v_mfma_f32_16x16x32_bf16 v[36:39], v[226:229], v[190:193], v[36:39]
	v_mfma_f32_16x16x32_bf16 v[28:31], v[236:239], v[190:193], v[28:31]
	v_mfma_f32_16x16x32_bf16 v[16:19], v[226:229], v[198:201], v[16:19]
	v_mfma_f32_16x16x32_bf16 v[8:11], v[236:239], v[198:201], v[8:11]
	v_mfma_f32_16x16x32_bf16 v[4:7], v[226:229], v[206:209], v[4:7]
	v_mfma_f32_16x16x32_bf16 v[0:3], v[236:239], v[206:209], v[0:3]
	s_add_i32 s73, s73, 2
	s_add_u32 s42, s42, 0x100
	s_addc_u32 s43, s43, 0
	s_add_u32 s52, s52, 0x100
	s_addc_u32 s72, s72, 0
	s_cmp_gt_u32 s73, 13
	s_barrier
	s_cbranch_scc0 .LBB0_968
	s_cmp_lt_u32 s101, 0x100
	s_cbranch_scc0 .Lxa_8
	s_barrier

; #define PG8_STAGE(bufoff, gbase, voff) do { _Pragma("unroll") for (int _i = 0; _i < 2; ++_i) \
;     __builtin_amdgcn_global_load_lds((const unsigned*)((const char*)(gbase) + (voff)[_i]), (LAS unsigned*)(lds + (bufoff) + ldsw + _i * 8192), 16, 0, 0); } while (0)
; #define PG8_LDA(dst, b, h) do { _Pragma("unroll") for (int m = 0; m < 4; ++m) _Pragma("unroll") for (int k = 0; k < 2; ++k) dst[m][k] = *(const LAS bf16x8*)(lds + PG8_SA(b, h) + aoff + m * 2048 + k * 1024); } while (0)
; #define PG8_LDB(dst, b, h) do { _Pragma("unroll") for (int n = 0; n < 2; ++n) _Pragma("unroll") for (int k = 0; k < 2; ++k) dst[n][k] = *(const LAS bf16x8*)(lds + PG8_SB(b, h) + boff + n * 2048 + k * 1024); } while (0)
; #define PG8_MMA(ai, bj, At, Bt) do { __builtin_amdgcn_s_setprio(1); _Pragma("unroll") for (int m = 0; m < 4; ++m) _Pragma("unroll") for (int n = 0; n < 2; ++n) _Pragma("unroll") for (int k = 0; k < 2; ++k) \
;     acc[ai][bj][m][n] = __builtin_amdgcn_mfma_f32_16x16x32_bf16(Bt[n][k], At[m][k], acc[ai][bj][m][n], 0, 0, 0); __builtin_amdgcn_s_setprio(0); } while (0)
; #define PG8_WAIT_V(n) asm volatile("s_waitcnt vmcnt(" #n ")" ::: "memory")
; #define PG8_WAIT_L(n) asm volatile("s_waitcnt lgkmcnt(" #n ")" ::: "memory")
; #define PG8_BAR __builtin_amdgcn_s_barrier()
; template <class Epi, class Sched>
; __device__ __forceinline__ void gemm_phase(LAS unsigned char* lds, const Gemm g, const Sched& S, const Epi& E) {
;     ...
;     for (int t = 0; t < nt; t += 2) {
;       const bool last = (t == nt - 2);
;       const char* a1 = cA + (size_t)(t + 1) * kstep;
;       const char* a2 = last ? nA : cA + (size_t)(t + 2) * kstep; const char* b2 = last ? nB : cB + (size_t)(t + 2) * kstep;
;       const char* a3 = a2 + kstep; const char* b3 = b2 + kstep;
;       if (last && has_next) S.a_ready(nxt);
;       PG8_LDB(B0, 0, 0); PG8_SCHED; PG8_LDA(At, 0, 0); PG8_STAGE(PG8_SA(1, 1), a1 + hstep, voffA);
;       PG8_WAIT_L(8); PG8_BAR; PG8_WAIT_L(0); PG8_MMA(0, 0, At, B0); PG8_BAR; PG8_SCHED;
;       PG8_LDB(B1, 0, 1); PG8_STAGE(PG8_SB(0, 0), b2, voffB);
;       PG8_BAR; PG8_WAIT_L(0); PG8_MMA(0, 1, At, B1); PG8_BAR;
;       PG8_LDA(At, 0, 1); PG8_STAGE(PG8_SA(0, 0), a2, voffA);
;       PG8_BAR; PG8_WAIT_L(0); PG8_MMA(1, 0, At, B0); PG8_BAR; PG8_SCHED;
;       PG8_STAGE(PG8_SB(0, 1), b2 + hstep, voffB);
;       PG8_WAIT_V(6); PG8_BAR; PG8_MMA(1, 1, At, B1); PG8_BAR;
.Lxs_e9:
.LBB0_1057:
	s_add_u32 s48, s34, 0xfffc0080
	s_addc_u32 s49, s35, -1
	s_add_i32 s74, 0, 0x10000
	v_add_u32_e32 v140, s74, v202
	ds_read_b128 v[128:131], v140
	ds_read_b128 v[132:135], v140 offset:1024
	ds_read_b128 v[136:139], v140 offset:2048
	ds_read_b128 v[140:143], v140 offset:3072
	s_cmp_eq_u32 s73, 12
	s_cselect_b32 s49, s37, s49
	s_cselect_b32 s48, s68, s48
	s_cselect_b32 vcc_hi, s23, s72
	s_cselect_b32 vcc_lo, s69, s52
	s_add_i32 m0, s51, 0xc000
	ds_read_b128 v[144:147], v203
	ds_read_b128 v[148:151], v203 offset:1024
	ds_read_b128 v[152:155], v203 offset:2048
	ds_read_b128 v[186:189], v203 offset:3072
	ds_read_b128 v[190:193], v203 offset:4096
	ds_read_b128 v[194:197], v203 offset:5120
	ds_read_b128 v[198:201], v203 offset:6144
	ds_read_b128 v[204:207], v203 offset:7168
	global_load_lds_dwordx4 v182, s[34:35]
	s_add_i32 m0, s51, 0xe000
	s_nop 0
	global_load_lds_dwordx4 v184, s[34:35]
	s_waitcnt lgkmcnt(8)
	s_barrier
	s_waitcnt lgkmcnt(0)
	s_waitcnt lgkmcnt(0)
	v_mfma_f32_16x16x32_bf16 v[124:127], v[128:131], v[144:147], v[124:127]
	v_mfma_f32_16x16x32_bf16 v[120:123], v[136:139], v[144:147], v[120:123]
	v_mfma_f32_16x16x32_bf16 v[108:111], v[128:131], v[152:155], v[108:111]
	v_mfma_f32_16x16x32_bf16 v[104:107], v[136:139], v[152:155], v[104:107]
	v_mfma_f32_16x16x32_bf16 v[92:95], v[128:131], v[190:193], v[92:95]
	v_mfma_f32_16x16x32_bf16 v[88:91], v[136:139], v[190:193], v[88:91]
	v_mfma_f32_16x16x32_bf16 v[76:79], v[128:131], v[198:201], v[76:79]
	v_mfma_f32_16x16x32_bf16 v[72:75], v[136:139], v[198:201], v[72:75]
	v_mfma_f32_16x16x32_bf16 v[124:127], v[132:135], v[148:151], v[124:127]
	v_mfma_f32_16x16x32_bf16 v[120:123], v[140:143], v[148:151], v[120:123]
	v_mfma_f32_16x16x32_bf16 v[108:111], v[132:135], v[186:189], v[108:111]
	v_mfma_f32_16x16x32_bf16 v[104:107], v[140:143], v[186:189], v[104:107]
	v_mfma_f32_16x16x32_bf16 v[92:95], v[132:135], v[194:197], v[92:95]
	v_mfma_f32_16x16x32_bf16 v[88:91], v[140:143], v[194:197], v[88:91]
	v_mfma_f32_16x16x32_bf16 v[76:79], v[132:135], v[204:207], v[76:79]
	v_mfma_f32_16x16x32_bf16 v[72:75], v[140:143], v[204:207], v[72:75]
	s_barrier
	s_add_i32 s76, 0, 0x14000
	s_add_i32 s74, s74, s7
	v_add_u32_e32 v160, s76, v202
	s_mov_b32 m0, s74
	ds_read_b128 v[208:211], v160
	ds_read_b128 v[226:229], v160 offset:1024
	ds_read_b128 v[232:235], v160 offset:2048
	ds_read_b128 v[236:239], v160 offset:3072
	global_load_lds_dwordx4 v174, vcc
	s_add_i32 m0, s74, 0x2000
	s_nop 0
	global_load_lds_dwordx4 v156, vcc
	s_barrier
	s_waitcnt lgkmcnt(0)
	s_waitcnt lgkmcnt(0)
	v_mfma_f32_16x16x32_bf16 v[116:119], v[208:211], v[144:147], v[116:119]
	v_mfma_f32_16x16x32_bf16 v[112:115], v[232:235], v[144:147], v[112:115]
	v_mfma_f32_16x16x32_bf16 v[100:103], v[208:211], v[152:155], v[100:103]
	v_mfma_f32_16x16x32_bf16 v[96:99], v[232:235], v[152:155], v[96:99]
	v_mfma_f32_16x16x32_bf16 v[84:87], v[208:211], v[190:193], v[84:87]
	v_mfma_f32_16x16x32_bf16 v[80:83], v[232:235], v[190:193], v[80:83]
	v_mfma_f32_16x16x32_bf16 v[68:71], v[208:211], v[198:201], v[68:71]
	v_mfma_f32_16x16x32_bf16 v[64:67], v[232:235], v[198:201], v[64:67]
	v_mfma_f32_16x16x32_bf16 v[116:119], v[226:229], v[148:151], v[116:119]
	v_mfma_f32_16x16x32_bf16 v[112:115], v[236:239], v[148:151], v[112:115]
	v_mfma_f32_16x16x32_bf16 v[100:103], v[226:229], v[186:189], v[100:103]
	v_mfma_f32_16x16x32_bf16 v[96:99], v[236:239], v[186:189], v[96:99]
	v_mfma_f32_16x16x32_bf16 v[84:87], v[226:229], v[194:197], v[84:87]
	v_mfma_f32_16x16x32_bf16 v[80:83], v[236:239], v[194:197], v[80:83]
	v_mfma_f32_16x16x32_bf16 v[68:71], v[226:229], v[204:207], v[68:71]
	v_mfma_f32_16x16x32_bf16 v[64:67], v[236:239], v[204:207], v[64:67]
	s_mov_b32 m0, s51
	v_lshl_add_u64 v[240:241], s[48:49], 0, v[176:177]
	s_barrier
	ds_read_b128 v[144:147], v203 offset:16384
	ds_read_b128 v[148:151], v203 offset:17408
	ds_read_b128 v[152:155], v203 offset:18432
	ds_read_b128 v[186:189], v203 offset:19456
	ds_read_b128 v[190:193], v203 offset:20480
	ds_read_b128 v[194:197], v203 offset:21504
	ds_read_b128 v[198:201], v203 offset:22528
	ds_read_b128 v[204:207], v203 offset:23552
	global_load_lds_dwordx4 v176, s[48:49]
	v_lshl_add_u64 v[242:243], s[48:49], 0, v[158:159]
	s_mov_b32 m0, s62
	s_nop 0
	global_load_lds_dwordx4 v158, s[48:49]
	s_barrier
	s_waitcnt lgkmcnt(0)
	s_waitcnt lgkmcnt(0)
	v_mfma_f32_16x16x32_bf16 v[60:63], v[128:131], v[144:147], v[60:63]
	v_mfma_f32_16x16x32_bf16 v[56:59], v[136:139], v[144:147], v[56:59]
	v_mfma_f32_16x16x32_bf16 v[44:47], v[128:131], v[152:155], v[44:47]
	v_mfma_f32_16x16x32_bf16 v[40:43], v[136:139], v[152:155], v[40:43]
	v_mfma_f32_16x16x32_bf16 v[28:31], v[128:131], v[190:193], v[28:31]
	v_mfma_f32_16x16x32_bf16 v[24:27], v[136:139], v[190:193], v[24:27]
	v_mfma_f32_16x16x32_bf16 v[12:15], v[128:131], v[198:201], v[12:15]
	v_mfma_f32_16x16x32_bf16 v[8:11], v[136:139], v[198:201], v[8:11]
	v_mfma_f32_16x16x32_bf16 v[60:63], v[132:135], v[148:151], v[60:63]
	v_mfma_f32_16x16x32_bf16 v[56:59], v[140:143], v[148:151], v[56:59]
	v_mfma_f32_16x16x32_bf16 v[44:47], v[132:135], v[186:189], v[44:47]
	v_mfma_f32_16x16x32_bf16 v[40:43], v[140:143], v[186:189], v[40:43]
	v_mfma_f32_16x16x32_bf16 v[28:31], v[132:135], v[194:197], v[28:31]
	v_mfma_f32_16x16x32_bf16 v[24:27], v[140:143], v[194:197], v[24:27]
	v_mfma_f32_16x16x32_bf16 v[12:15], v[132:135], v[204:207], v[12:15]
	v_mfma_f32_16x16x32_bf16 v[8:11], v[140:143], v[204:207], v[8:11]
	s_barrier
	s_add_u32 s74, vcc_lo, 0x40000
	s_addc_u32 s75, vcc_hi, 0
	s_add_i32 s76, s76, s7
	s_mov_b32 m0, s76
	s_nop 0
	global_load_lds_dwordx4 v174, s[74:75]
	s_add_i32 m0, s76, 0x2000
	s_nop 0
	global_load_lds_dwordx4 v156, s[74:75]
	s_waitcnt vmcnt(6)
	s_barrier
; #define PG8_STAGE(bufoff, gbase, voff) do { _Pragma("unroll") for (int _i = 0; _i < 2; ++_i) \
;     __builtin_amdgcn_global_load_lds((const unsigned*)((const char*)(gbase) + (voff)[_i]), (LAS unsigned*)(lds + (bufoff) + ldsw + _i * 8192), 16, 0, 0); } while (0)
; #define PG8_LDA(dst, b, h) do { _Pragma("unroll") for (int m = 0; m < 4; ++m) _Pragma("unroll") for (int k = 0; k < 2; ++k) dst[m][k] = *(const LAS bf16x8*)(lds + PG8_SA(b, h) + aoff + m * 2048 + k * 1024); } while (0)
; #define PG8_LDB(dst, b, h) do { _Pragma("unroll") for (int n = 0; n < 2; ++n) _Pragma("unroll") for (int k = 0; k < 2; ++k) dst[n][k] = *(const LAS bf16x8*)(lds + PG8_SB(b, h) + boff + n * 2048 + k * 1024); } while (0)
; #define PG8_MMA(ai, bj, At, Bt) do { __builtin_amdgcn_s_setprio(1); _Pragma("unroll") for (int m = 0; m < 4; ++m) _Pragma("unroll") for (int n = 0; n < 2; ++n) _Pragma("unroll") for (int k = 0; k < 2; ++k) \
;     acc[ai][bj][m][n] = __builtin_amdgcn_mfma_f32_16x16x32_bf16(Bt[n][k], At[m][k], acc[ai][bj][m][n], 0, 0, 0); __builtin_amdgcn_s_setprio(0); } while (0)
; #define PG8_WAIT_V(n) asm volatile("s_waitcnt vmcnt(" #n ")" ::: "memory")
; #define PG8_WAIT_L(n) asm volatile("s_waitcnt lgkmcnt(" #n ")" ::: "memory")
; #define PG8_BAR __builtin_amdgcn_s_barrier()
; #define PG8_SCHED __builtin_amdgcn_sched_barrier(0)
; template <class Epi, class Sched>
; __device__ __forceinline__ void gemm_phase(LAS unsigned char* lds, const Gemm g, const Sched& S, const Epi& E) {
;     ...
;       PG8_WAIT_V(6); PG8_BAR; PG8_MMA(1, 1, At, B1); PG8_BAR;
;       PG8_LDB(B0, 1, 0); PG8_SCHED; PG8_LDA(At, 1, 0); PG8_STAGE(PG8_SA(0, 1), a2 + hstep, voffA);
;       PG8_WAIT_L(8); PG8_BAR; PG8_WAIT_L(0); PG8_MMA(0, 0, At, B0); PG8_BAR; PG8_SCHED;
;       PG8_LDB(B1, 1, 1); PG8_STAGE(PG8_SB(1, 0), b3, voffB);
	v_mfma_f32_16x16x32_bf16 v[52:55], v[208:211], v[144:147], v[52:55]
	v_mfma_f32_16x16x32_bf16 v[48:51], v[232:235], v[144:147], v[48:51]
	v_mfma_f32_16x16x32_bf16 v[36:39], v[208:211], v[152:155], v[36:39]
	v_mfma_f32_16x16x32_bf16 v[32:35], v[232:235], v[152:155], v[32:35]
	v_mfma_f32_16x16x32_bf16 v[20:23], v[208:211], v[190:193], v[20:23]
	v_mfma_f32_16x16x32_bf16 v[16:19], v[232:235], v[190:193], v[16:19]
	v_mfma_f32_16x16x32_bf16 v[4:7], v[208:211], v[198:201], v[4:7]
	v_mfma_f32_16x16x32_bf16 v[0:3], v[232:235], v[198:201], v[0:3]
	v_mfma_f32_16x16x32_bf16 v[52:55], v[226:229], v[148:151], v[52:55]
	v_mfma_f32_16x16x32_bf16 v[48:51], v[236:239], v[148:151], v[48:51]
	v_mfma_f32_16x16x32_bf16 v[36:39], v[226:229], v[186:189], v[36:39]
	v_mfma_f32_16x16x32_bf16 v[32:35], v[236:239], v[186:189], v[32:35]
	v_mfma_f32_16x16x32_bf16 v[20:23], v[226:229], v[194:197], v[20:23]
	v_mfma_f32_16x16x32_bf16 v[16:19], v[236:239], v[194:197], v[16:19]
	v_mfma_f32_16x16x32_bf16 v[4:7], v[226:229], v[204:207], v[4:7]
	v_mfma_f32_16x16x32_bf16 v[0:3], v[236:239], v[204:207], v[0:3]
	s_add_i32 s74, 0, 0x18000
	v_add_u32_e32 v140, s74, v202
	s_barrier
	ds_read_b128 v[128:131], v140
	ds_read_b128 v[132:135], v140 offset:1024
	ds_read_b128 v[136:139], v140 offset:2048
	ds_read_b128 v[140:143], v140 offset:3072
	s_add_u32 s48, s48, 0x40000
	s_addc_u32 s49, s49, 0
	s_mov_b32 m0, s63
	ds_read_b128 v[144:147], v203 offset:32768
	ds_read_b128 v[148:151], v203 offset:33792
	ds_read_b128 v[152:155], v203 offset:34816
	ds_read_b128 v[186:189], v203 offset:35840
	ds_read_b128 v[190:193], v203 offset:36864
	ds_read_b128 v[194:197], v203 offset:37888
	ds_read_b128 v[198:201], v203 offset:38912
	ds_read_b128 v[204:207], v203 offset:39936
	global_load_lds_dwordx4 v176, s[48:49]
	s_mov_b32 m0, s64
	s_nop 0
	global_load_lds_dwordx4 v158, s[48:49]
	s_waitcnt lgkmcnt(8)
	s_barrier
	s_waitcnt lgkmcnt(0)
	s_waitcnt lgkmcnt(0)
	v_mfma_f32_16x16x32_bf16 v[124:127], v[128:131], v[144:147], v[124:127]
	v_mfma_f32_16x16x32_bf16 v[120:123], v[136:139], v[144:147], v[120:123]
	v_mfma_f32_16x16x32_bf16 v[108:111], v[128:131], v[152:155], v[108:111]
	v_mfma_f32_16x16x32_bf16 v[104:107], v[136:139], v[152:155], v[104:107]
	v_mfma_f32_16x16x32_bf16 v[92:95], v[128:131], v[190:193], v[92:95]
	v_mfma_f32_16x16x32_bf16 v[88:91], v[136:139], v[190:193], v[88:91]
	v_mfma_f32_16x16x32_bf16 v[76:79], v[128:131], v[198:201], v[76:79]
	v_mfma_f32_16x16x32_bf16 v[72:75], v[136:139], v[198:201], v[72:75]
	v_mfma_f32_16x16x32_bf16 v[124:127], v[132:135], v[148:151], v[124:127]
	v_mfma_f32_16x16x32_bf16 v[120:123], v[140:143], v[148:151], v[120:123]
	v_mfma_f32_16x16x32_bf16 v[108:111], v[132:135], v[186:189], v[108:111]
	v_mfma_f32_16x16x32_bf16 v[104:107], v[140:143], v[186:189], v[104:107]
	v_mfma_f32_16x16x32_bf16 v[92:95], v[132:135], v[194:197], v[92:95]
	v_mfma_f32_16x16x32_bf16 v[88:91], v[140:143], v[194:197], v[88:91]
	v_mfma_f32_16x16x32_bf16 v[76:79], v[132:135], v[204:207], v[76:79]
	v_mfma_f32_16x16x32_bf16 v[72:75], v[140:143], v[204:207], v[72:75]
	s_barrier
	s_add_i32 s75, 0, 0x1c000
	s_add_i32 s48, s74, s7
	v_add_u32_e32 v160, s75, v202
	s_add_u32 s60, vcc_lo, s80
	s_addc_u32 s61, vcc_hi, s81
	s_mov_b32 m0, s48
	ds_read_b128 v[208:211], v160
	ds_read_b128 v[226:229], v160 offset:1024
	ds_read_b128 v[232:235], v160 offset:2048
	ds_read_b128 v[236:239], v160 offset:3072
	global_load_lds_dwordx4 v174, s[60:61]
	v_lshl_add_u64 v[212:213], v[222:223], 0, s[80:81]
	s_add_i32 m0, s48, 0x2000
	s_nop 0
	global_load_lds_dwordx4 v156, s[60:61]
	s_barrier
; #define PG8_STAGE(bufoff, gbase, voff) do { _Pragma("unroll") for (int _i = 0; _i < 2; ++_i) \
;     __builtin_amdgcn_global_load_lds((const unsigned*)((const char*)(gbase) + (voff)[_i]), (LAS unsigned*)(lds + (bufoff) + ldsw + _i * 8192), 16, 0, 0); } while (0)
; #define PG8_LDA(dst, b, h) do { _Pragma("unroll") for (int m = 0; m < 4; ++m) _Pragma("unroll") for (int k = 0; k < 2; ++k) dst[m][k] = *(const LAS bf16x8*)(lds + PG8_SA(b, h) + aoff + m * 2048 + k * 1024); } while (0)
; #define PG8_MMA(ai, bj, At, Bt) do { __builtin_amdgcn_s_setprio(1); _Pragma("unroll") for (int m = 0; m < 4; ++m) _Pragma("unroll") for (int n = 0; n < 2; ++n) _Pragma("unroll") for (int k = 0; k < 2; ++k) \
;     acc[ai][bj][m][n] = __builtin_amdgcn_mfma_f32_16x16x32_bf16(Bt[n][k], At[m][k], acc[ai][bj][m][n], 0, 0, 0); __builtin_amdgcn_s_setprio(0); } while (0)
; #define PG8_WAIT_V(n) asm volatile("s_waitcnt vmcnt(" #n ")" ::: "memory")
; #define PG8_WAIT_L(n) asm volatile("s_waitcnt lgkmcnt(" #n ")" ::: "memory")
; #define PG8_BAR __builtin_amdgcn_s_barrier()
; #define PG8_SCHED __builtin_amdgcn_sched_barrier(0)
; template <class Epi, class Sched>
; __device__ __forceinline__ void gemm_phase(LAS unsigned char* lds, const Gemm g, const Sched& S, const Epi& E) {
;     ...
;       PG8_BAR; PG8_WAIT_L(0); PG8_MMA(0, 1, At, B1); PG8_BAR;
;       PG8_LDA(At, 1, 1); PG8_STAGE(PG8_SA(1, 0), a3, voffA);
;       PG8_BAR; PG8_WAIT_L(0); PG8_MMA(1, 0, At, B0); PG8_BAR; PG8_SCHED;
;       PG8_STAGE(PG8_SB(1, 1), b3 + hstep, voffB);
;       PG8_WAIT_V(6); PG8_BAR; PG8_MMA(1, 1, At, B1); PG8_BAR;
	s_waitcnt lgkmcnt(0)
	s_waitcnt lgkmcnt(0)
	v_mfma_f32_16x16x32_bf16 v[116:119], v[208:211], v[144:147], v[116:119]
	v_mfma_f32_16x16x32_bf16 v[112:115], v[232:235], v[144:147], v[112:115]
	v_mfma_f32_16x16x32_bf16 v[100:103], v[208:211], v[152:155], v[100:103]
	v_mfma_f32_16x16x32_bf16 v[96:99], v[232:235], v[152:155], v[96:99]
	v_mfma_f32_16x16x32_bf16 v[84:87], v[208:211], v[190:193], v[84:87]
	v_mfma_f32_16x16x32_bf16 v[80:83], v[232:235], v[190:193], v[80:83]
	v_mfma_f32_16x16x32_bf16 v[68:71], v[208:211], v[198:201], v[68:71]
	v_mfma_f32_16x16x32_bf16 v[64:67], v[232:235], v[198:201], v[64:67]
	v_mfma_f32_16x16x32_bf16 v[116:119], v[226:229], v[148:151], v[116:119]
	v_mfma_f32_16x16x32_bf16 v[112:115], v[236:239], v[148:151], v[112:115]
	v_mfma_f32_16x16x32_bf16 v[100:103], v[226:229], v[186:189], v[100:103]
	v_mfma_f32_16x16x32_bf16 v[96:99], v[236:239], v[186:189], v[96:99]
	v_mfma_f32_16x16x32_bf16 v[84:87], v[226:229], v[194:197], v[84:87]
	v_mfma_f32_16x16x32_bf16 v[80:83], v[236:239], v[194:197], v[80:83]
	v_mfma_f32_16x16x32_bf16 v[68:71], v[226:229], v[204:207], v[68:71]
	v_mfma_f32_16x16x32_bf16 v[64:67], v[236:239], v[204:207], v[64:67]
	s_mov_b32 m0, s65
	v_lshl_add_u64 v[212:213], v[240:241], 0, s[80:81]
	s_barrier
	ds_read_b128 v[144:147], v203 offset:49152
	ds_read_b128 v[148:151], v203 offset:50176
	ds_read_b128 v[152:155], v203 offset:51200
	ds_read_b128 v[186:189], v203 offset:52224
	ds_read_b128 v[190:193], v203 offset:53248
	ds_read_b128 v[194:197], v203 offset:54272
	ds_read_b128 v[198:201], v203 offset:55296
	ds_read_b128 v[204:207], v203 offset:56320
	global_load_lds_dwordx4 v[212:213], off
	v_lshl_add_u64 v[212:213], v[242:243], 0, s[80:81]
	s_mov_b32 m0, s70
	s_nop 0
	global_load_lds_dwordx4 v[212:213], off
	s_barrier
	s_waitcnt lgkmcnt(0)
	s_waitcnt lgkmcnt(0)
	v_mfma_f32_16x16x32_bf16 v[60:63], v[128:131], v[144:147], v[60:63]
	v_mfma_f32_16x16x32_bf16 v[56:59], v[136:139], v[144:147], v[56:59]
	v_mfma_f32_16x16x32_bf16 v[44:47], v[128:131], v[152:155], v[44:47]
	v_mfma_f32_16x16x32_bf16 v[40:43], v[136:139], v[152:155], v[40:43]
	v_mfma_f32_16x16x32_bf16 v[28:31], v[128:131], v[190:193], v[28:31]
	v_mfma_f32_16x16x32_bf16 v[24:27], v[136:139], v[190:193], v[24:27]
	v_mfma_f32_16x16x32_bf16 v[12:15], v[128:131], v[198:201], v[12:15]
	v_mfma_f32_16x16x32_bf16 v[8:11], v[136:139], v[198:201], v[8:11]
	v_mfma_f32_16x16x32_bf16 v[60:63], v[132:135], v[148:151], v[60:63]
	v_mfma_f32_16x16x32_bf16 v[56:59], v[140:143], v[148:151], v[56:59]
	v_mfma_f32_16x16x32_bf16 v[44:47], v[132:135], v[186:189], v[44:47]
	v_mfma_f32_16x16x32_bf16 v[40:43], v[140:143], v[186:189], v[40:43]
	v_mfma_f32_16x16x32_bf16 v[28:31], v[132:135], v[194:197], v[28:31]
	v_mfma_f32_16x16x32_bf16 v[24:27], v[140:143], v[194:197], v[24:27]
	v_mfma_f32_16x16x32_bf16 v[12:15], v[132:135], v[204:207], v[12:15]
	v_mfma_f32_16x16x32_bf16 v[8:11], v[140:143], v[204:207], v[8:11]
	s_barrier
	s_add_u32 s48, vcc_lo, 0x40080
	s_addc_u32 s49, vcc_hi, 0
	s_add_i32 s74, s75, s7
	s_mov_b32 m0, s74
	s_nop 0
	global_load_lds_dwordx4 v174, s[48:49]
	s_add_i32 m0, s74, 0x2000
	s_nop 0
	global_load_lds_dwordx4 v156, s[48:49]
	s_waitcnt vmcnt(6)
	s_barrier
	v_mfma_f32_16x16x32_bf16 v[52:55], v[208:211], v[144:147], v[52:55]
	v_mfma_f32_16x16x32_bf16 v[48:51], v[232:235], v[144:147], v[48:51]
	v_mfma_f32_16x16x32_bf16 v[36:39], v[208:211], v[152:155], v[36:39]
	v_mfma_f32_16x16x32_bf16 v[32:35], v[232:235], v[152:155], v[32:35]
	v_mfma_f32_16x16x32_bf16 v[20:23], v[208:211], v[190:193], v[20:23]
	v_mfma_f32_16x16x32_bf16 v[16:19], v[232:235], v[190:193], v[16:19]
	v_mfma_f32_16x16x32_bf16 v[4:7], v[208:211], v[198:201], v[4:7]
	v_mfma_f32_16x16x32_bf16 v[0:3], v[232:235], v[198:201], v[0:3]
	v_mfma_f32_16x16x32_bf16 v[52:55], v[226:229], v[148:151], v[52:55]
	v_mfma_f32_16x16x32_bf16 v[48:51], v[236:239], v[148:151], v[48:51]
	v_mfma_f32_16x16x32_bf16 v[36:39], v[226:229], v[186:189], v[36:39]
	v_mfma_f32_16x16x32_bf16 v[32:35], v[236:239], v[186:189], v[32:35]
	v_mfma_f32_16x16x32_bf16 v[20:23], v[226:229], v[194:197], v[20:23]
	v_mfma_f32_16x16x32_bf16 v[16:19], v[236:239], v[194:197], v[16:19]
	v_mfma_f32_16x16x32_bf16 v[4:7], v[226:229], v[204:207], v[4:7]
	v_mfma_f32_16x16x32_bf16 v[0:3], v[236:239], v[204:207], v[0:3]
	s_add_i32 s73, s73, 2
	s_add_u32 s34, s34, 0x100
	s_addc_u32 s35, s35, 0
	s_add_u32 s52, s52, 0x100
	s_addc_u32 s72, s72, 0
	s_cmp_gt_u32 s73, 13
	s_barrier
	s_cbranch_scc0 .LBB0_1057
	s_cmp_lt_u32 s101, 0x100
	s_cbranch_scc0 .Lxa_9
	s_barrier

; #define PG8_STAGE(bufoff, gbase, voff) do { _Pragma("unroll") for (int _i = 0; _i < 2; ++_i) \
;     __builtin_amdgcn_global_load_lds((const unsigned*)((const char*)(gbase) + (voff)[_i]), (LAS unsigned*)(lds + (bufoff) + ldsw + _i * 8192), 16, 0, 0); } while (0)
; #define PG8_LDA(dst, b, h) do { _Pragma("unroll") for (int m = 0; m < 4; ++m) _Pragma("unroll") for (int k = 0; k < 2; ++k) dst[m][k] = *(const LAS bf16x8*)(lds + PG8_SA(b, h) + aoff + m * 2048 + k * 1024); } while (0)
; #define PG8_LDB(dst, b, h) do { _Pragma("unroll") for (int n = 0; n < 2; ++n) _Pragma("unroll") for (int k = 0; k < 2; ++k) dst[n][k] = *(const LAS bf16x8*)(lds + PG8_SB(b, h) + boff + n * 2048 + k * 1024); } while (0)
; #define PG8_MMA(ai, bj, At, Bt) do { __builtin_amdgcn_s_setprio(1); _Pragma("unroll") for (int m = 0; m < 4; ++m) _Pragma("unroll") for (int n = 0; n < 2; ++n) _Pragma("unroll") for (int k = 0; k < 2; ++k) \
;     acc[ai][bj][m][n] = __builtin_amdgcn_mfma_f32_16x16x32_bf16(Bt[n][k], At[m][k], acc[ai][bj][m][n], 0, 0, 0); __builtin_amdgcn_s_setprio(0); } while (0)
; #define PG8_WAIT_V(n) asm volatile("s_waitcnt vmcnt(" #n ")" ::: "memory")
; #define PG8_WAIT_L(n) asm volatile("s_waitcnt lgkmcnt(" #n ")" ::: "memory")
; #define PG8_BAR __builtin_amdgcn_s_barrier()
; template <class Epi, class Sched>
; __device__ __forceinline__ void gemm_phase(LAS unsigned char* lds, const Gemm g, const Sched& S, const Epi& E) {
;     ...
;     for (int t = 0; t < nt; t += 2) {
;       const bool last = (t == nt - 2);
;       const char* a1 = cA + (size_t)(t + 1) * kstep;
;       const char* a2 = last ? nA : cA + (size_t)(t + 2) * kstep; const char* b2 = last ? nB : cB + (size_t)(t + 2) * kstep;
;       const char* a3 = a2 + kstep; const char* b3 = b2 + kstep;
;       if (last && has_next) S.a_ready(nxt);
;       PG8_LDB(B0, 0, 0); PG8_SCHED; PG8_LDA(At, 0, 0); PG8_STAGE(PG8_SA(1, 1), a1 + hstep, voffA);
;       PG8_WAIT_L(8); PG8_BAR; PG8_WAIT_L(0); PG8_MMA(0, 0, At, B0); PG8_BAR; PG8_SCHED;
;       PG8_LDB(B1, 0, 1); PG8_STAGE(PG8_SB(0, 0), b2, voffB);
;       PG8_BAR; PG8_WAIT_L(0); PG8_MMA(0, 1, At, B1); PG8_BAR;
;       PG8_LDA(At, 0, 1); PG8_STAGE(PG8_SA(0, 0), a2, voffA);
;       PG8_BAR; PG8_WAIT_L(0); PG8_MMA(1, 0, At, B0); PG8_BAR; PG8_SCHED;
;       PG8_STAGE(PG8_SB(0, 1), b2 + hstep, voffB);
;       PG8_WAIT_V(6); PG8_BAR; PG8_MMA(1, 1, At, B1); PG8_BAR;
.Lxs_e10:
.LBB0_1142:
	s_add_u32 s44, s42, 0xfffc0080
	s_addc_u32 s45, s43, -1
	s_add_i32 s74, 0, 0x10000
	v_add_u32_e32 v151, s74, v141
	ds_read_b128 v[152:155], v151
	ds_read_b128 v[156:159], v151 offset:1024
	ds_read_b128 v[174:177], v151 offset:2048
	ds_read_b128 v[178:181], v151 offset:3072
	s_cmp_eq_u32 s73, 12
	s_cselect_b32 s49, s35, s45
	s_cselect_b32 s48, s71, s44
	s_cselect_b32 s45, s23, s72
	s_cselect_b32 s44, vcc_lo, s52
	s_add_i32 m0, s12, 0xc000
	ds_read_b128 v[182:185], v150
	ds_read_b128 v[186:189], v150 offset:1024
	ds_read_b128 v[190:193], v150 offset:2048
	ds_read_b128 v[194:197], v150 offset:3072
	ds_read_b128 v[198:201], v150 offset:4096
	ds_read_b128 v[202:205], v150 offset:5120
	ds_read_b128 v[206:209], v150 offset:6144
	ds_read_b128 v[210:213], v150 offset:7168
	global_load_lds_dwordx4 v136, s[42:43]
	s_add_i32 m0, s12, 0xe000
	s_nop 0
	global_load_lds_dwordx4 v138, s[42:43]
	s_waitcnt lgkmcnt(8)
	s_barrier
	s_waitcnt lgkmcnt(0)
	s_waitcnt lgkmcnt(0)
	v_mfma_f32_16x16x32_bf16 v[124:127], v[152:155], v[182:185], v[124:127]
	v_mfma_f32_16x16x32_bf16 v[116:119], v[174:177], v[182:185], v[116:119]
	v_mfma_f32_16x16x32_bf16 v[108:111], v[152:155], v[190:193], v[108:111]
	v_mfma_f32_16x16x32_bf16 v[100:103], v[174:177], v[190:193], v[100:103]
	v_mfma_f32_16x16x32_bf16 v[92:95], v[152:155], v[198:201], v[92:95]
	v_mfma_f32_16x16x32_bf16 v[84:87], v[174:177], v[198:201], v[84:87]
	v_mfma_f32_16x16x32_bf16 v[76:79], v[152:155], v[206:209], v[76:79]
	v_mfma_f32_16x16x32_bf16 v[68:71], v[174:177], v[206:209], v[68:71]
	v_mfma_f32_16x16x32_bf16 v[124:127], v[156:159], v[186:189], v[124:127]
	v_mfma_f32_16x16x32_bf16 v[116:119], v[178:181], v[186:189], v[116:119]
	v_mfma_f32_16x16x32_bf16 v[108:111], v[156:159], v[194:197], v[108:111]
	v_mfma_f32_16x16x32_bf16 v[100:103], v[178:181], v[194:197], v[100:103]
	v_mfma_f32_16x16x32_bf16 v[92:95], v[156:159], v[202:205], v[92:95]
	v_mfma_f32_16x16x32_bf16 v[84:87], v[178:181], v[202:205], v[84:87]
	v_mfma_f32_16x16x32_bf16 v[76:79], v[156:159], v[210:213], v[76:79]
	v_mfma_f32_16x16x32_bf16 v[68:71], v[178:181], v[210:213], v[68:71]
	s_barrier
	s_add_i32 s76, 0, 0x14000
	s_add_i32 s74, s74, s7
	v_add_u32_e32 v151, s76, v141
	s_mov_b32 m0, s74
	ds_read_b128 v[226:229], v151
	ds_read_b128 v[232:235], v151 offset:1024
	ds_read_b128 v[236:239], v151 offset:2048
	ds_read_b128 v[240:243], v151 offset:3072
	global_load_lds_dwordx4 v132, s[44:45]
	s_add_i32 m0, s74, 0x2000
	s_nop 0
	global_load_lds_dwordx4 v128, s[44:45]
	s_barrier
	s_waitcnt lgkmcnt(0)
	s_waitcnt lgkmcnt(0)
	v_mfma_f32_16x16x32_bf16 v[120:123], v[226:229], v[182:185], v[120:123]
	v_mfma_f32_16x16x32_bf16 v[112:115], v[236:239], v[182:185], v[112:115]
	v_mfma_f32_16x16x32_bf16 v[104:107], v[226:229], v[190:193], v[104:107]
	v_mfma_f32_16x16x32_bf16 v[96:99], v[236:239], v[190:193], v[96:99]
	v_mfma_f32_16x16x32_bf16 v[88:91], v[226:229], v[198:201], v[88:91]
	v_mfma_f32_16x16x32_bf16 v[80:83], v[236:239], v[198:201], v[80:83]
	v_mfma_f32_16x16x32_bf16 v[72:75], v[226:229], v[206:209], v[72:75]
	v_mfma_f32_16x16x32_bf16 v[64:67], v[236:239], v[206:209], v[64:67]
	v_mfma_f32_16x16x32_bf16 v[120:123], v[232:235], v[186:189], v[120:123]
	v_mfma_f32_16x16x32_bf16 v[112:115], v[240:243], v[186:189], v[112:115]
	v_mfma_f32_16x16x32_bf16 v[104:107], v[232:235], v[194:197], v[104:107]
	v_mfma_f32_16x16x32_bf16 v[96:99], v[240:243], v[194:197], v[96:99]
	v_mfma_f32_16x16x32_bf16 v[88:91], v[232:235], v[202:205], v[88:91]
	v_mfma_f32_16x16x32_bf16 v[80:83], v[240:243], v[202:205], v[80:83]
	v_mfma_f32_16x16x32_bf16 v[72:75], v[232:235], v[210:213], v[72:75]
	v_mfma_f32_16x16x32_bf16 v[64:67], v[240:243], v[210:213], v[64:67]
	s_mov_b32 m0, s12
	v_lshl_add_u64 v[246:247], s[48:49], 0, v[134:135]
	s_barrier
	ds_read_b128 v[182:185], v150 offset:16384
	ds_read_b128 v[186:189], v150 offset:17408
	ds_read_b128 v[190:193], v150 offset:18432
	ds_read_b128 v[194:197], v150 offset:19456
	ds_read_b128 v[198:201], v150 offset:20480
	ds_read_b128 v[202:205], v150 offset:21504
	ds_read_b128 v[206:209], v150 offset:22528
	ds_read_b128 v[210:213], v150 offset:23552
	global_load_lds_dwordx4 v134, s[48:49]
	v_lshl_add_u64 v[248:249], s[48:49], 0, v[130:131]
	s_mov_b32 m0, s13
	s_nop 0
	global_load_lds_dwordx4 v130, s[48:49]
	s_barrier
	s_waitcnt lgkmcnt(0)
	s_waitcnt lgkmcnt(0)
	v_mfma_f32_16x16x32_bf16 v[60:63], v[152:155], v[182:185], v[60:63]
	v_mfma_f32_16x16x32_bf16 v[52:55], v[174:177], v[182:185], v[52:55]
	v_mfma_f32_16x16x32_bf16 v[44:47], v[152:155], v[190:193], v[44:47]
	v_mfma_f32_16x16x32_bf16 v[36:39], v[174:177], v[190:193], v[36:39]
	v_mfma_f32_16x16x32_bf16 v[28:31], v[152:155], v[198:201], v[28:31]
	v_mfma_f32_16x16x32_bf16 v[20:23], v[174:177], v[198:201], v[20:23]
	v_mfma_f32_16x16x32_bf16 v[12:15], v[152:155], v[206:209], v[12:15]
	v_mfma_f32_16x16x32_bf16 v[4:7], v[174:177], v[206:209], v[4:7]
	v_mfma_f32_16x16x32_bf16 v[60:63], v[156:159], v[186:189], v[60:63]
	v_mfma_f32_16x16x32_bf16 v[52:55], v[178:181], v[186:189], v[52:55]
	v_mfma_f32_16x16x32_bf16 v[44:47], v[156:159], v[194:197], v[44:47]
	v_mfma_f32_16x16x32_bf16 v[36:39], v[178:181], v[194:197], v[36:39]
	v_mfma_f32_16x16x32_bf16 v[28:31], v[156:159], v[202:205], v[28:31]
	v_mfma_f32_16x16x32_bf16 v[20:23], v[178:181], v[202:205], v[20:23]
	v_mfma_f32_16x16x32_bf16 v[12:15], v[156:159], v[210:213], v[12:15]
	v_mfma_f32_16x16x32_bf16 v[4:7], v[178:181], v[210:213], v[4:7]
	s_barrier
	s_add_u32 s74, s44, 0x40000
	s_addc_u32 s75, s45, 0
	s_add_i32 s76, s76, s7
	s_mov_b32 m0, s76
	s_nop 0
	global_load_lds_dwordx4 v132, s[74:75]
	s_add_i32 m0, s76, 0x2000
	s_nop 0
	global_load_lds_dwordx4 v128, s[74:75]
	s_waitcnt vmcnt(6)
	s_barrier
; #define PG8_STAGE(bufoff, gbase, voff) do { _Pragma("unroll") for (int _i = 0; _i < 2; ++_i) \
;     __builtin_amdgcn_global_load_lds((const unsigned*)((const char*)(gbase) + (voff)[_i]), (LAS unsigned*)(lds + (bufoff) + ldsw + _i * 8192), 16, 0, 0); } while (0)
; #define PG8_LDA(dst, b, h) do { _Pragma("unroll") for (int m = 0; m < 4; ++m) _Pragma("unroll") for (int k = 0; k < 2; ++k) dst[m][k] = *(const LAS bf16x8*)(lds + PG8_SA(b, h) + aoff + m * 2048 + k * 1024); } while (0)
; #define PG8_LDB(dst, b, h) do { _Pragma("unroll") for (int n = 0; n < 2; ++n) _Pragma("unroll") for (int k = 0; k < 2; ++k) dst[n][k] = *(const LAS bf16x8*)(lds + PG8_SB(b, h) + boff + n * 2048 + k * 1024); } while (0)
; #define PG8_MMA(ai, bj, At, Bt) do { __builtin_amdgcn_s_setprio(1); _Pragma("unroll") for (int m = 0; m < 4; ++m) _Pragma("unroll") for (int n = 0; n < 2; ++n) _Pragma("unroll") for (int k = 0; k < 2; ++k) \
;     acc[ai][bj][m][n] = __builtin_amdgcn_mfma_f32_16x16x32_bf16(Bt[n][k], At[m][k], acc[ai][bj][m][n], 0, 0, 0); __builtin_amdgcn_s_setprio(0); } while (0)
; #define PG8_WAIT_V(n) asm volatile("s_waitcnt vmcnt(" #n ")" ::: "memory")
; #define PG8_WAIT_L(n) asm volatile("s_waitcnt lgkmcnt(" #n ")" ::: "memory")
; #define PG8_BAR __builtin_amdgcn_s_barrier()
; #define PG8_SCHED __builtin_amdgcn_sched_barrier(0)
; template <class Epi, class Sched>
; __device__ __forceinline__ void gemm_phase(LAS unsigned char* lds, const Gemm g, const Sched& S, const Epi& E) {
;     ...
;       PG8_WAIT_V(6); PG8_BAR; PG8_MMA(1, 1, At, B1); PG8_BAR;
;       PG8_LDB(B0, 1, 0); PG8_SCHED; PG8_LDA(At, 1, 0); PG8_STAGE(PG8_SA(0, 1), a2 + hstep, voffA);
;       PG8_WAIT_L(8); PG8_BAR; PG8_WAIT_L(0); PG8_MMA(0, 0, At, B0); PG8_BAR; PG8_SCHED;
;       PG8_LDB(B1, 1, 1); PG8_STAGE(PG8_SB(1, 0), b3, voffB);
	v_mfma_f32_16x16x32_bf16 v[56:59], v[226:229], v[182:185], v[56:59]
	v_mfma_f32_16x16x32_bf16 v[48:51], v[236:239], v[182:185], v[48:51]
	v_mfma_f32_16x16x32_bf16 v[40:43], v[226:229], v[190:193], v[40:43]
	v_mfma_f32_16x16x32_bf16 v[32:35], v[236:239], v[190:193], v[32:35]
	v_mfma_f32_16x16x32_bf16 v[24:27], v[226:229], v[198:201], v[24:27]
	v_mfma_f32_16x16x32_bf16 v[16:19], v[236:239], v[198:201], v[16:19]
	v_mfma_f32_16x16x32_bf16 v[8:11], v[226:229], v[206:209], v[8:11]
	v_mfma_f32_16x16x32_bf16 v[0:3], v[236:239], v[206:209], v[0:3]
	v_mfma_f32_16x16x32_bf16 v[56:59], v[232:235], v[186:189], v[56:59]
	v_mfma_f32_16x16x32_bf16 v[48:51], v[240:243], v[186:189], v[48:51]
	v_mfma_f32_16x16x32_bf16 v[40:43], v[232:235], v[194:197], v[40:43]
	v_mfma_f32_16x16x32_bf16 v[32:35], v[240:243], v[194:197], v[32:35]
	v_mfma_f32_16x16x32_bf16 v[24:27], v[232:235], v[202:205], v[24:27]
	v_mfma_f32_16x16x32_bf16 v[16:19], v[240:243], v[202:205], v[16:19]
	v_mfma_f32_16x16x32_bf16 v[8:11], v[232:235], v[210:213], v[8:11]
	v_mfma_f32_16x16x32_bf16 v[0:3], v[240:243], v[210:213], v[0:3]
	s_add_i32 s74, 0, 0x18000
	v_add_u32_e32 v151, s74, v141
	s_barrier
	ds_read_b128 v[152:155], v151
	ds_read_b128 v[156:159], v151 offset:1024
	ds_read_b128 v[174:177], v151 offset:2048
	ds_read_b128 v[178:181], v151 offset:3072
	s_add_u32 s48, s48, 0x40000
	s_addc_u32 s49, s49, 0
	s_mov_b32 m0, s51
	ds_read_b128 v[182:185], v150 offset:32768
	ds_read_b128 v[186:189], v150 offset:33792
	ds_read_b128 v[190:193], v150 offset:34816
	ds_read_b128 v[194:197], v150 offset:35840
	ds_read_b128 v[198:201], v150 offset:36864
	ds_read_b128 v[202:205], v150 offset:37888
	ds_read_b128 v[206:209], v150 offset:38912
	ds_read_b128 v[210:213], v150 offset:39936
	global_load_lds_dwordx4 v134, s[48:49]
	s_mov_b32 m0, s62
	s_nop 0
	global_load_lds_dwordx4 v130, s[48:49]
	s_waitcnt lgkmcnt(8)
	s_barrier
	s_waitcnt lgkmcnt(0)
	s_waitcnt lgkmcnt(0)
	v_mfma_f32_16x16x32_bf16 v[124:127], v[152:155], v[182:185], v[124:127]
	v_mfma_f32_16x16x32_bf16 v[116:119], v[174:177], v[182:185], v[116:119]
	v_mfma_f32_16x16x32_bf16 v[108:111], v[152:155], v[190:193], v[108:111]
	v_mfma_f32_16x16x32_bf16 v[100:103], v[174:177], v[190:193], v[100:103]
	v_mfma_f32_16x16x32_bf16 v[92:95], v[152:155], v[198:201], v[92:95]
	v_mfma_f32_16x16x32_bf16 v[84:87], v[174:177], v[198:201], v[84:87]
	v_mfma_f32_16x16x32_bf16 v[76:79], v[152:155], v[206:209], v[76:79]
	v_mfma_f32_16x16x32_bf16 v[68:71], v[174:177], v[206:209], v[68:71]
	v_mfma_f32_16x16x32_bf16 v[124:127], v[156:159], v[186:189], v[124:127]
	v_mfma_f32_16x16x32_bf16 v[116:119], v[178:181], v[186:189], v[116:119]
	v_mfma_f32_16x16x32_bf16 v[108:111], v[156:159], v[194:197], v[108:111]
	v_mfma_f32_16x16x32_bf16 v[100:103], v[178:181], v[194:197], v[100:103]
	v_mfma_f32_16x16x32_bf16 v[92:95], v[156:159], v[202:205], v[92:95]
	v_mfma_f32_16x16x32_bf16 v[84:87], v[178:181], v[202:205], v[84:87]
	v_mfma_f32_16x16x32_bf16 v[76:79], v[156:159], v[210:213], v[76:79]
	v_mfma_f32_16x16x32_bf16 v[68:71], v[178:181], v[210:213], v[68:71]
	s_barrier
	s_add_i32 s48, 0, 0x1c000
	s_add_i32 s49, s74, s7
	v_add_u32_e32 v151, s48, v141
	s_add_u32 s60, s44, s80
	s_addc_u32 s61, s45, s81
	s_mov_b32 m0, s49
	ds_read_b128 v[226:229], v151
	ds_read_b128 v[232:235], v151 offset:1024
	ds_read_b128 v[236:239], v151 offset:2048
	ds_read_b128 v[240:243], v151 offset:3072
	global_load_lds_dwordx4 v132, s[60:61]
	v_lshl_add_u64 v[222:223], v[244:245], 0, s[80:81]
	s_add_i32 m0, s49, 0x2000
	s_nop 0
	global_load_lds_dwordx4 v128, s[60:61]
	s_barrier
; #define PG8_STAGE(bufoff, gbase, voff) do { _Pragma("unroll") for (int _i = 0; _i < 2; ++_i) \
;     __builtin_amdgcn_global_load_lds((const unsigned*)((const char*)(gbase) + (voff)[_i]), (LAS unsigned*)(lds + (bufoff) + ldsw + _i * 8192), 16, 0, 0); } while (0)
; #define PG8_LDA(dst, b, h) do { _Pragma("unroll") for (int m = 0; m < 4; ++m) _Pragma("unroll") for (int k = 0; k < 2; ++k) dst[m][k] = *(const LAS bf16x8*)(lds + PG8_SA(b, h) + aoff + m * 2048 + k * 1024); } while (0)
; #define PG8_MMA(ai, bj, At, Bt) do { __builtin_amdgcn_s_setprio(1); _Pragma("unroll") for (int m = 0; m < 4; ++m) _Pragma("unroll") for (int n = 0; n < 2; ++n) _Pragma("unroll") for (int k = 0; k < 2; ++k) \
;     acc[ai][bj][m][n] = __builtin_amdgcn_mfma_f32_16x16x32_bf16(Bt[n][k], At[m][k], acc[ai][bj][m][n], 0, 0, 0); __builtin_amdgcn_s_setprio(0); } while (0)
; #define PG8_WAIT_V(n) asm volatile("s_waitcnt vmcnt(" #n ")" ::: "memory")
; #define PG8_WAIT_L(n) asm volatile("s_waitcnt lgkmcnt(" #n ")" ::: "memory")
; #define PG8_BAR __builtin_amdgcn_s_barrier()
; #define PG8_SCHED __builtin_amdgcn_sched_barrier(0)
; template <class Epi, class Sched>
; __device__ __forceinline__ void gemm_phase(LAS unsigned char* lds, const Gemm g, const Sched& S, const Epi& E) {
;     ...
;       PG8_BAR; PG8_WAIT_L(0); PG8_MMA(0, 1, At, B1); PG8_BAR;
;       PG8_LDA(At, 1, 1); PG8_STAGE(PG8_SA(1, 0), a3, voffA);
;       PG8_BAR; PG8_WAIT_L(0); PG8_MMA(1, 0, At, B0); PG8_BAR; PG8_SCHED;
;       PG8_STAGE(PG8_SB(1, 1), b3 + hstep, voffB);
;       PG8_WAIT_V(6); PG8_BAR; PG8_MMA(1, 1, At, B1); PG8_BAR;
	s_waitcnt lgkmcnt(0)
	s_waitcnt lgkmcnt(0)
	v_mfma_f32_16x16x32_bf16 v[120:123], v[226:229], v[182:185], v[120:123]
	v_mfma_f32_16x16x32_bf16 v[112:115], v[236:239], v[182:185], v[112:115]
	v_mfma_f32_16x16x32_bf16 v[104:107], v[226:229], v[190:193], v[104:107]
	v_mfma_f32_16x16x32_bf16 v[96:99], v[236:239], v[190:193], v[96:99]
	v_mfma_f32_16x16x32_bf16 v[88:91], v[226:229], v[198:201], v[88:91]
	v_mfma_f32_16x16x32_bf16 v[80:83], v[236:239], v[198:201], v[80:83]
	v_mfma_f32_16x16x32_bf16 v[72:75], v[226:229], v[206:209], v[72:75]
	v_mfma_f32_16x16x32_bf16 v[64:67], v[236:239], v[206:209], v[64:67]
	v_mfma_f32_16x16x32_bf16 v[120:123], v[232:235], v[186:189], v[120:123]
	v_mfma_f32_16x16x32_bf16 v[112:115], v[240:243], v[186:189], v[112:115]
	v_mfma_f32_16x16x32_bf16 v[104:107], v[232:235], v[194:197], v[104:107]
	v_mfma_f32_16x16x32_bf16 v[96:99], v[240:243], v[194:197], v[96:99]
	v_mfma_f32_16x16x32_bf16 v[88:91], v[232:235], v[202:205], v[88:91]
	v_mfma_f32_16x16x32_bf16 v[80:83], v[240:243], v[202:205], v[80:83]
	v_mfma_f32_16x16x32_bf16 v[72:75], v[232:235], v[210:213], v[72:75]
	v_mfma_f32_16x16x32_bf16 v[64:67], v[240:243], v[210:213], v[64:67]
	s_mov_b32 m0, s63
	v_lshl_add_u64 v[222:223], v[246:247], 0, s[80:81]
	s_barrier
	ds_read_b128 v[182:185], v150 offset:49152
	ds_read_b128 v[186:189], v150 offset:50176
	ds_read_b128 v[190:193], v150 offset:51200
	ds_read_b128 v[194:197], v150 offset:52224
	ds_read_b128 v[198:201], v150 offset:53248
	ds_read_b128 v[202:205], v150 offset:54272
	ds_read_b128 v[206:209], v150 offset:55296
	ds_read_b128 v[210:213], v150 offset:56320
	global_load_lds_dwordx4 v[222:223], off
	v_lshl_add_u64 v[222:223], v[248:249], 0, s[80:81]
	s_mov_b32 m0, s64
	s_nop 0
	global_load_lds_dwordx4 v[222:223], off
	s_barrier
	s_waitcnt lgkmcnt(0)
	s_waitcnt lgkmcnt(0)
	v_mfma_f32_16x16x32_bf16 v[60:63], v[152:155], v[182:185], v[60:63]
	v_mfma_f32_16x16x32_bf16 v[52:55], v[174:177], v[182:185], v[52:55]
	v_mfma_f32_16x16x32_bf16 v[44:47], v[152:155], v[190:193], v[44:47]
	v_mfma_f32_16x16x32_bf16 v[36:39], v[174:177], v[190:193], v[36:39]
	v_mfma_f32_16x16x32_bf16 v[28:31], v[152:155], v[198:201], v[28:31]
	v_mfma_f32_16x16x32_bf16 v[20:23], v[174:177], v[198:201], v[20:23]
	v_mfma_f32_16x16x32_bf16 v[12:15], v[152:155], v[206:209], v[12:15]
	v_mfma_f32_16x16x32_bf16 v[4:7], v[174:177], v[206:209], v[4:7]
	v_mfma_f32_16x16x32_bf16 v[60:63], v[156:159], v[186:189], v[60:63]
	v_mfma_f32_16x16x32_bf16 v[52:55], v[178:181], v[186:189], v[52:55]
	v_mfma_f32_16x16x32_bf16 v[44:47], v[156:159], v[194:197], v[44:47]
	v_mfma_f32_16x16x32_bf16 v[36:39], v[178:181], v[194:197], v[36:39]
	v_mfma_f32_16x16x32_bf16 v[28:31], v[156:159], v[202:205], v[28:31]
	v_mfma_f32_16x16x32_bf16 v[20:23], v[178:181], v[202:205], v[20:23]
	v_mfma_f32_16x16x32_bf16 v[12:15], v[156:159], v[210:213], v[12:15]
	v_mfma_f32_16x16x32_bf16 v[4:7], v[178:181], v[210:213], v[4:7]
	s_barrier
	s_add_u32 s44, s44, 0x40080
	s_addc_u32 s45, s45, 0
	s_add_i32 s48, s48, s7
	s_mov_b32 m0, s48
	s_nop 0
	global_load_lds_dwordx4 v132, s[44:45]
	s_add_i32 m0, s48, 0x2000
	s_nop 0
	global_load_lds_dwordx4 v128, s[44:45]
	s_waitcnt vmcnt(6)
	s_barrier
	v_mfma_f32_16x16x32_bf16 v[56:59], v[226:229], v[182:185], v[56:59]
	v_mfma_f32_16x16x32_bf16 v[48:51], v[236:239], v[182:185], v[48:51]
	v_mfma_f32_16x16x32_bf16 v[40:43], v[226:229], v[190:193], v[40:43]
	v_mfma_f32_16x16x32_bf16 v[32:35], v[236:239], v[190:193], v[32:35]
	v_mfma_f32_16x16x32_bf16 v[24:27], v[226:229], v[198:201], v[24:27]
	v_mfma_f32_16x16x32_bf16 v[16:19], v[236:239], v[198:201], v[16:19]
	v_mfma_f32_16x16x32_bf16 v[8:11], v[226:229], v[206:209], v[8:11]
	v_mfma_f32_16x16x32_bf16 v[0:3], v[236:239], v[206:209], v[0:3]
	v_mfma_f32_16x16x32_bf16 v[56:59], v[232:235], v[186:189], v[56:59]
	v_mfma_f32_16x16x32_bf16 v[48:51], v[240:243], v[186:189], v[48:51]
	v_mfma_f32_16x16x32_bf16 v[40:43], v[232:235], v[194:197], v[40:43]
	v_mfma_f32_16x16x32_bf16 v[32:35], v[240:243], v[194:197], v[32:35]
	v_mfma_f32_16x16x32_bf16 v[24:27], v[232:235], v[202:205], v[24:27]
	v_mfma_f32_16x16x32_bf16 v[16:19], v[240:243], v[202:205], v[16:19]
	v_mfma_f32_16x16x32_bf16 v[8:11], v[232:235], v[210:213], v[8:11]
	v_mfma_f32_16x16x32_bf16 v[0:3], v[240:243], v[210:213], v[0:3]
	s_add_i32 s73, s73, 2
	s_add_u32 s42, s42, 0x100
	s_addc_u32 s43, s43, 0
	s_add_u32 s52, s52, 0x100
	s_addc_u32 s72, s72, 0
	s_cmp_gt_u32 s73, 13
	s_barrier
	s_cbranch_scc0 .LBB0_1142
	s_cmp_lt_u32 s101, 0x100
	s_cbranch_scc0 .Lxa_10
	s_barrier

; #define PG8_STAGE(bufoff, gbase, voff) do { _Pragma("unroll") for (int _i = 0; _i < 2; ++_i) \
;     __builtin_amdgcn_global_load_lds((const unsigned*)((const char*)(gbase) + (voff)[_i]), (LAS unsigned*)(lds + (bufoff) + ldsw + _i * 8192), 16, 0, 0); } while (0)
; #define PG8_LDA(dst, b, h) do { _Pragma("unroll") for (int m = 0; m < 4; ++m) _Pragma("unroll") for (int k = 0; k < 2; ++k) dst[m][k] = *(const LAS bf16x8*)(lds + PG8_SA(b, h) + aoff + m * 2048 + k * 1024); } while (0)
; #define PG8_LDB(dst, b, h) do { _Pragma("unroll") for (int n = 0; n < 2; ++n) _Pragma("unroll") for (int k = 0; k < 2; ++k) dst[n][k] = *(const LAS bf16x8*)(lds + PG8_SB(b, h) + boff + n * 2048 + k * 1024); } while (0)
; #define PG8_MMA(ai, bj, At, Bt) do { __builtin_amdgcn_s_setprio(1); _Pragma("unroll") for (int m = 0; m < 4; ++m) _Pragma("unroll") for (int n = 0; n < 2; ++n) _Pragma("unroll") for (int k = 0; k < 2; ++k) \
;     acc[ai][bj][m][n] = __builtin_amdgcn_mfma_f32_16x16x32_bf16(Bt[n][k], At[m][k], acc[ai][bj][m][n], 0, 0, 0); __builtin_amdgcn_s_setprio(0); } while (0)
; #define PG8_WAIT_V(n) asm volatile("s_waitcnt vmcnt(" #n ")" ::: "memory")
; #define PG8_WAIT_L(n) asm volatile("s_waitcnt lgkmcnt(" #n ")" ::: "memory")
; #define PG8_BAR __builtin_amdgcn_s_barrier()
; template <class Epi, class Sched>
; __device__ __forceinline__ void gemm_phase(LAS unsigned char* lds, const Gemm g, const Sched& S, const Epi& E) {
;     ...
;     for (int t = 0; t < nt; t += 2) {
;       const bool last = (t == nt - 2);
;       const char* a1 = cA + (size_t)(t + 1) * kstep;
;       const char* a2 = last ? nA : cA + (size_t)(t + 2) * kstep; const char* b2 = last ? nB : cB + (size_t)(t + 2) * kstep;
;       const char* a3 = a2 + kstep; const char* b3 = b2 + kstep;
;       if (last && has_next) S.a_ready(nxt);
;       PG8_LDB(B0, 0, 0); PG8_SCHED; PG8_LDA(At, 0, 0); PG8_STAGE(PG8_SA(1, 1), a1 + hstep, voffA);
;       PG8_WAIT_L(8); PG8_BAR; PG8_WAIT_L(0); PG8_MMA(0, 0, At, B0); PG8_BAR; PG8_SCHED;
;       PG8_LDB(B1, 0, 1); PG8_STAGE(PG8_SB(0, 0), b2, voffB);
;       PG8_BAR; PG8_WAIT_L(0); PG8_MMA(0, 1, At, B1); PG8_BAR;
;       PG8_LDA(At, 0, 1); PG8_STAGE(PG8_SA(0, 0), a2, voffA);
;       PG8_BAR; PG8_WAIT_L(0); PG8_MMA(1, 0, At, B0); PG8_BAR; PG8_SCHED;
;       PG8_STAGE(PG8_SB(0, 1), b2 + hstep, voffB);
;       PG8_WAIT_V(6); PG8_BAR; PG8_MMA(1, 1, At, B1); PG8_BAR;
.Lxs_e11:
.LBB0_1215:
	s_add_u32 s42, s34, 0x100
	s_addc_u32 s43, s35, 0
	s_add_i32 s74, 0, 0x10000
	v_add_u32_e32 v140, s74, v202
	ds_read_b128 v[128:131], v140
	ds_read_b128 v[132:135], v140 offset:1024
	ds_read_b128 v[136:139], v140 offset:2048
	ds_read_b128 v[140:143], v140 offset:3072
	s_cmp_eq_u32 s73, 40
	s_cselect_b32 s49, s23, s43
	s_cselect_b32 s48, s22, s42
	s_cselect_b32 s45, s41, s72
	s_cselect_b32 s44, s40, s52
	s_add_i32 m0, s51, 0xc000
	ds_read_b128 v[144:147], v203
	ds_read_b128 v[148:151], v203 offset:1024
	ds_read_b128 v[152:155], v203 offset:2048
	ds_read_b128 v[186:189], v203 offset:3072
	ds_read_b128 v[190:193], v203 offset:4096
	ds_read_b128 v[194:197], v203 offset:5120
	ds_read_b128 v[198:201], v203 offset:6144
	ds_read_b128 v[204:207], v203 offset:7168
	global_load_lds_dwordx4 v182, s[34:35]
	s_add_i32 m0, s51, 0xe000
	s_nop 0
	global_load_lds_dwordx4 v184, s[34:35]
	s_waitcnt lgkmcnt(8)
	s_barrier
	s_waitcnt lgkmcnt(0)
	s_waitcnt lgkmcnt(0)
	v_mfma_f32_16x16x32_bf16 v[124:127], v[128:131], v[144:147], v[124:127]
	v_mfma_f32_16x16x32_bf16 v[120:123], v[136:139], v[144:147], v[120:123]
	v_mfma_f32_16x16x32_bf16 v[108:111], v[128:131], v[152:155], v[108:111]
	v_mfma_f32_16x16x32_bf16 v[104:107], v[136:139], v[152:155], v[104:107]
	v_mfma_f32_16x16x32_bf16 v[92:95], v[128:131], v[190:193], v[92:95]
	v_mfma_f32_16x16x32_bf16 v[88:91], v[136:139], v[190:193], v[88:91]
	v_mfma_f32_16x16x32_bf16 v[76:79], v[128:131], v[198:201], v[76:79]
	v_mfma_f32_16x16x32_bf16 v[72:75], v[136:139], v[198:201], v[72:75]
	v_mfma_f32_16x16x32_bf16 v[124:127], v[132:135], v[148:151], v[124:127]
	v_mfma_f32_16x16x32_bf16 v[120:123], v[140:143], v[148:151], v[120:123]
	v_mfma_f32_16x16x32_bf16 v[108:111], v[132:135], v[186:189], v[108:111]
	v_mfma_f32_16x16x32_bf16 v[104:107], v[140:143], v[186:189], v[104:107]
	v_mfma_f32_16x16x32_bf16 v[92:95], v[132:135], v[194:197], v[92:95]
	v_mfma_f32_16x16x32_bf16 v[88:91], v[140:143], v[194:197], v[88:91]
	v_mfma_f32_16x16x32_bf16 v[76:79], v[132:135], v[204:207], v[76:79]
	v_mfma_f32_16x16x32_bf16 v[72:75], v[140:143], v[204:207], v[72:75]
	s_barrier
	s_add_i32 s75, 0, 0x14000
	s_add_i32 s34, s74, s7
	v_add_u32_e32 v160, s75, v202
	s_mov_b32 m0, s34
	ds_read_b128 v[208:211], v160
	ds_read_b128 v[226:229], v160 offset:1024
	ds_read_b128 v[232:235], v160 offset:2048
	ds_read_b128 v[236:239], v160 offset:3072
	global_load_lds_dwordx4 v174, s[44:45]
	s_add_i32 m0, s34, 0x2000
	s_nop 0
	global_load_lds_dwordx4 v156, s[44:45]
	s_barrier
	s_waitcnt lgkmcnt(0)
	s_waitcnt lgkmcnt(0)
	v_mfma_f32_16x16x32_bf16 v[116:119], v[208:211], v[144:147], v[116:119]
	v_mfma_f32_16x16x32_bf16 v[112:115], v[232:235], v[144:147], v[112:115]
	v_mfma_f32_16x16x32_bf16 v[100:103], v[208:211], v[152:155], v[100:103]
	v_mfma_f32_16x16x32_bf16 v[96:99], v[232:235], v[152:155], v[96:99]
	v_mfma_f32_16x16x32_bf16 v[84:87], v[208:211], v[190:193], v[84:87]
	v_mfma_f32_16x16x32_bf16 v[80:83], v[232:235], v[190:193], v[80:83]
	v_mfma_f32_16x16x32_bf16 v[68:71], v[208:211], v[198:201], v[68:71]
	v_mfma_f32_16x16x32_bf16 v[64:67], v[232:235], v[198:201], v[64:67]
	v_mfma_f32_16x16x32_bf16 v[116:119], v[226:229], v[148:151], v[116:119]
	v_mfma_f32_16x16x32_bf16 v[112:115], v[236:239], v[148:151], v[112:115]
	v_mfma_f32_16x16x32_bf16 v[100:103], v[226:229], v[186:189], v[100:103]
	v_mfma_f32_16x16x32_bf16 v[96:99], v[236:239], v[186:189], v[96:99]
	v_mfma_f32_16x16x32_bf16 v[84:87], v[226:229], v[194:197], v[84:87]
	v_mfma_f32_16x16x32_bf16 v[80:83], v[236:239], v[194:197], v[80:83]
	v_mfma_f32_16x16x32_bf16 v[68:71], v[226:229], v[204:207], v[68:71]
	v_mfma_f32_16x16x32_bf16 v[64:67], v[236:239], v[204:207], v[64:67]
	s_mov_b32 m0, s51
	v_lshl_add_u64 v[240:241], s[48:49], 0, v[176:177]
	s_barrier
	ds_read_b128 v[144:147], v203 offset:16384
	ds_read_b128 v[148:151], v203 offset:17408
	ds_read_b128 v[152:155], v203 offset:18432
	ds_read_b128 v[186:189], v203 offset:19456
	ds_read_b128 v[190:193], v203 offset:20480
	ds_read_b128 v[194:197], v203 offset:21504
	ds_read_b128 v[198:201], v203 offset:22528
	ds_read_b128 v[204:207], v203 offset:23552
	global_load_lds_dwordx4 v176, s[48:49]
	v_lshl_add_u64 v[242:243], s[48:49], 0, v[158:159]
	s_mov_b32 m0, s62
	s_nop 0
	global_load_lds_dwordx4 v158, s[48:49]
	s_barrier
	s_waitcnt lgkmcnt(0)
	s_waitcnt lgkmcnt(0)
	v_mfma_f32_16x16x32_bf16 v[60:63], v[128:131], v[144:147], v[60:63]
	v_mfma_f32_16x16x32_bf16 v[56:59], v[136:139], v[144:147], v[56:59]
	v_mfma_f32_16x16x32_bf16 v[44:47], v[128:131], v[152:155], v[44:47]
	v_mfma_f32_16x16x32_bf16 v[40:43], v[136:139], v[152:155], v[40:43]
	v_mfma_f32_16x16x32_bf16 v[28:31], v[128:131], v[190:193], v[28:31]
	v_mfma_f32_16x16x32_bf16 v[24:27], v[136:139], v[190:193], v[24:27]
	v_mfma_f32_16x16x32_bf16 v[12:15], v[128:131], v[198:201], v[12:15]
	v_mfma_f32_16x16x32_bf16 v[8:11], v[136:139], v[198:201], v[8:11]
	v_mfma_f32_16x16x32_bf16 v[60:63], v[132:135], v[148:151], v[60:63]
	v_mfma_f32_16x16x32_bf16 v[56:59], v[140:143], v[148:151], v[56:59]
	v_mfma_f32_16x16x32_bf16 v[44:47], v[132:135], v[186:189], v[44:47]
	v_mfma_f32_16x16x32_bf16 v[40:43], v[140:143], v[186:189], v[40:43]
	v_mfma_f32_16x16x32_bf16 v[28:31], v[132:135], v[194:197], v[28:31]
	v_mfma_f32_16x16x32_bf16 v[24:27], v[140:143], v[194:197], v[24:27]
	v_mfma_f32_16x16x32_bf16 v[12:15], v[132:135], v[204:207], v[12:15]
	v_mfma_f32_16x16x32_bf16 v[8:11], v[140:143], v[204:207], v[8:11]
	s_barrier
	s_add_u32 s34, s44, 0xb0000
	s_addc_u32 s35, s45, 0
	s_add_i32 s74, s75, s7
	s_mov_b32 m0, s74
	s_nop 0
	global_load_lds_dwordx4 v174, s[34:35]
	s_add_i32 m0, s74, 0x2000
	s_nop 0
	global_load_lds_dwordx4 v156, s[34:35]
	s_waitcnt vmcnt(6)
	s_barrier
; #define PG8_STAGE(bufoff, gbase, voff) do { _Pragma("unroll") for (int _i = 0; _i < 2; ++_i) \
;     __builtin_amdgcn_global_load_lds((const unsigned*)((const char*)(gbase) + (voff)[_i]), (LAS unsigned*)(lds + (bufoff) + ldsw + _i * 8192), 16, 0, 0); } while (0)
; #define PG8_LDA(dst, b, h) do { _Pragma("unroll") for (int m = 0; m < 4; ++m) _Pragma("unroll") for (int k = 0; k < 2; ++k) dst[m][k] = *(const LAS bf16x8*)(lds + PG8_SA(b, h) + aoff + m * 2048 + k * 1024); } while (0)
; #define PG8_LDB(dst, b, h) do { _Pragma("unroll") for (int n = 0; n < 2; ++n) _Pragma("unroll") for (int k = 0; k < 2; ++k) dst[n][k] = *(const LAS bf16x8*)(lds + PG8_SB(b, h) + boff + n * 2048 + k * 1024); } while (0)
; #define PG8_MMA(ai, bj, At, Bt) do { __builtin_amdgcn_s_setprio(1); _Pragma("unroll") for (int m = 0; m < 4; ++m) _Pragma("unroll") for (int n = 0; n < 2; ++n) _Pragma("unroll") for (int k = 0; k < 2; ++k) \
;     acc[ai][bj][m][n] = __builtin_amdgcn_mfma_f32_16x16x32_bf16(Bt[n][k], At[m][k], acc[ai][bj][m][n], 0, 0, 0); __builtin_amdgcn_s_setprio(0); } while (0)
; #define PG8_WAIT_V(n) asm volatile("s_waitcnt vmcnt(" #n ")" ::: "memory")
; #define PG8_WAIT_L(n) asm volatile("s_waitcnt lgkmcnt(" #n ")" ::: "memory")
; #define PG8_BAR __builtin_amdgcn_s_barrier()
; #define PG8_SCHED __builtin_amdgcn_sched_barrier(0)
; template <class Epi, class Sched>
; __device__ __forceinline__ void gemm_phase(LAS unsigned char* lds, const Gemm g, const Sched& S, const Epi& E) {
;     ...
;       PG8_WAIT_V(6); PG8_BAR; PG8_MMA(1, 1, At, B1); PG8_BAR;
;       PG8_LDB(B0, 1, 0); PG8_SCHED; PG8_LDA(At, 1, 0); PG8_STAGE(PG8_SA(0, 1), a2 + hstep, voffA);
;       PG8_WAIT_L(8); PG8_BAR; PG8_WAIT_L(0); PG8_MMA(0, 0, At, B0); PG8_BAR; PG8_SCHED;
;       PG8_LDB(B1, 1, 1); PG8_STAGE(PG8_SB(1, 0), b3, voffB);
	v_mfma_f32_16x16x32_bf16 v[52:55], v[208:211], v[144:147], v[52:55]
	v_mfma_f32_16x16x32_bf16 v[48:51], v[232:235], v[144:147], v[48:51]
	v_mfma_f32_16x16x32_bf16 v[36:39], v[208:211], v[152:155], v[36:39]
	v_mfma_f32_16x16x32_bf16 v[32:35], v[232:235], v[152:155], v[32:35]
	v_mfma_f32_16x16x32_bf16 v[20:23], v[208:211], v[190:193], v[20:23]
	v_mfma_f32_16x16x32_bf16 v[16:19], v[232:235], v[190:193], v[16:19]
	v_mfma_f32_16x16x32_bf16 v[4:7], v[208:211], v[198:201], v[4:7]
	v_mfma_f32_16x16x32_bf16 v[0:3], v[232:235], v[198:201], v[0:3]
	v_mfma_f32_16x16x32_bf16 v[52:55], v[226:229], v[148:151], v[52:55]
	v_mfma_f32_16x16x32_bf16 v[48:51], v[236:239], v[148:151], v[48:51]
	v_mfma_f32_16x16x32_bf16 v[36:39], v[226:229], v[186:189], v[36:39]
	v_mfma_f32_16x16x32_bf16 v[32:35], v[236:239], v[186:189], v[32:35]
	v_mfma_f32_16x16x32_bf16 v[20:23], v[226:229], v[194:197], v[20:23]
	v_mfma_f32_16x16x32_bf16 v[16:19], v[236:239], v[194:197], v[16:19]
	v_mfma_f32_16x16x32_bf16 v[4:7], v[226:229], v[204:207], v[4:7]
	v_mfma_f32_16x16x32_bf16 v[0:3], v[236:239], v[204:207], v[0:3]
	s_add_i32 s74, 0, 0x18000
	v_add_u32_e32 v140, s74, v202
	s_barrier
	ds_read_b128 v[128:131], v140
	ds_read_b128 v[132:135], v140 offset:1024
	ds_read_b128 v[136:139], v140 offset:2048
	ds_read_b128 v[140:143], v140 offset:3072
	s_add_u32 s34, s48, 0xb0000
	s_addc_u32 s35, s49, 0
	s_mov_b32 m0, s63
	ds_read_b128 v[144:147], v203 offset:32768
	ds_read_b128 v[148:151], v203 offset:33792
	ds_read_b128 v[152:155], v203 offset:34816
	ds_read_b128 v[186:189], v203 offset:35840
	ds_read_b128 v[190:193], v203 offset:36864
	ds_read_b128 v[194:197], v203 offset:37888
	ds_read_b128 v[198:201], v203 offset:38912
	ds_read_b128 v[204:207], v203 offset:39936
	global_load_lds_dwordx4 v176, s[34:35]
	s_mov_b32 m0, s64
	s_nop 0
	global_load_lds_dwordx4 v158, s[34:35]
	s_waitcnt lgkmcnt(8)
	s_barrier
	s_waitcnt lgkmcnt(0)
	s_waitcnt lgkmcnt(0)
	v_mfma_f32_16x16x32_bf16 v[124:127], v[128:131], v[144:147], v[124:127]
	v_mfma_f32_16x16x32_bf16 v[120:123], v[136:139], v[144:147], v[120:123]
	v_mfma_f32_16x16x32_bf16 v[108:111], v[128:131], v[152:155], v[108:111]
	v_mfma_f32_16x16x32_bf16 v[104:107], v[136:139], v[152:155], v[104:107]
	v_mfma_f32_16x16x32_bf16 v[92:95], v[128:131], v[190:193], v[92:95]
	v_mfma_f32_16x16x32_bf16 v[88:91], v[136:139], v[190:193], v[88:91]
	v_mfma_f32_16x16x32_bf16 v[76:79], v[128:131], v[198:201], v[76:79]
	v_mfma_f32_16x16x32_bf16 v[72:75], v[136:139], v[198:201], v[72:75]
	v_mfma_f32_16x16x32_bf16 v[124:127], v[132:135], v[148:151], v[124:127]
	v_mfma_f32_16x16x32_bf16 v[120:123], v[140:143], v[148:151], v[120:123]
	v_mfma_f32_16x16x32_bf16 v[108:111], v[132:135], v[186:189], v[108:111]
	v_mfma_f32_16x16x32_bf16 v[104:107], v[140:143], v[186:189], v[104:107]
	v_mfma_f32_16x16x32_bf16 v[92:95], v[132:135], v[194:197], v[92:95]
	v_mfma_f32_16x16x32_bf16 v[88:91], v[140:143], v[194:197], v[88:91]
	v_mfma_f32_16x16x32_bf16 v[76:79], v[132:135], v[204:207], v[76:79]
	v_mfma_f32_16x16x32_bf16 v[72:75], v[140:143], v[204:207], v[72:75]
	s_barrier
	s_add_i32 s48, 0, 0x1c000
	s_add_i32 s34, s74, s7
	v_add_u32_e32 v160, s48, v202
	s_add_u32 s60, s44, s80
	s_addc_u32 s61, s45, s81
	s_mov_b32 m0, s34
	ds_read_b128 v[208:211], v160
	ds_read_b128 v[226:229], v160 offset:1024
	ds_read_b128 v[232:235], v160 offset:2048
	ds_read_b128 v[236:239], v160 offset:3072
	global_load_lds_dwordx4 v174, s[60:61]
	v_lshl_add_u64 v[212:213], v[222:223], 0, s[80:81]
	s_add_i32 m0, s34, 0x2000
	s_nop 0
	global_load_lds_dwordx4 v156, s[60:61]
	s_barrier
; #define PG8_STAGE(bufoff, gbase, voff) do { _Pragma("unroll") for (int _i = 0; _i < 2; ++_i) \
;     __builtin_amdgcn_global_load_lds((const unsigned*)((const char*)(gbase) + (voff)[_i]), (LAS unsigned*)(lds + (bufoff) + ldsw + _i * 8192), 16, 0, 0); } while (0)
; #define PG8_LDA(dst, b, h) do { _Pragma("unroll") for (int m = 0; m < 4; ++m) _Pragma("unroll") for (int k = 0; k < 2; ++k) dst[m][k] = *(const LAS bf16x8*)(lds + PG8_SA(b, h) + aoff + m * 2048 + k * 1024); } while (0)
; #define PG8_MMA(ai, bj, At, Bt) do { __builtin_amdgcn_s_setprio(1); _Pragma("unroll") for (int m = 0; m < 4; ++m) _Pragma("unroll") for (int n = 0; n < 2; ++n) _Pragma("unroll") for (int k = 0; k < 2; ++k) \
;     acc[ai][bj][m][n] = __builtin_amdgcn_mfma_f32_16x16x32_bf16(Bt[n][k], At[m][k], acc[ai][bj][m][n], 0, 0, 0); __builtin_amdgcn_s_setprio(0); } while (0)
; #define PG8_WAIT_V(n) asm volatile("s_waitcnt vmcnt(" #n ")" ::: "memory")
; #define PG8_WAIT_L(n) asm volatile("s_waitcnt lgkmcnt(" #n ")" ::: "memory")
; #define PG8_BAR __builtin_amdgcn_s_barrier()
; #define PG8_SCHED __builtin_amdgcn_sched_barrier(0)
; template <class Epi, class Sched>
; __device__ __forceinline__ void gemm_phase(LAS unsigned char* lds, const Gemm g, const Sched& S, const Epi& E) {
;     ...
;       PG8_BAR; PG8_WAIT_L(0); PG8_MMA(0, 1, At, B1); PG8_BAR;
;       PG8_LDA(At, 1, 1); PG8_STAGE(PG8_SA(1, 0), a3, voffA);
;       PG8_BAR; PG8_WAIT_L(0); PG8_MMA(1, 0, At, B0); PG8_BAR; PG8_SCHED;
;       PG8_STAGE(PG8_SB(1, 1), b3 + hstep, voffB);
;       PG8_WAIT_V(6); PG8_BAR; PG8_MMA(1, 1, At, B1); PG8_BAR;
	s_waitcnt lgkmcnt(0)
	s_waitcnt lgkmcnt(0)
	v_mfma_f32_16x16x32_bf16 v[116:119], v[208:211], v[144:147], v[116:119]
	v_mfma_f32_16x16x32_bf16 v[112:115], v[232:235], v[144:147], v[112:115]
	v_mfma_f32_16x16x32_bf16 v[100:103], v[208:211], v[152:155], v[100:103]
	v_mfma_f32_16x16x32_bf16 v[96:99], v[232:235], v[152:155], v[96:99]
	v_mfma_f32_16x16x32_bf16 v[84:87], v[208:211], v[190:193], v[84:87]
	v_mfma_f32_16x16x32_bf16 v[80:83], v[232:235], v[190:193], v[80:83]
	v_mfma_f32_16x16x32_bf16 v[68:71], v[208:211], v[198:201], v[68:71]
	v_mfma_f32_16x16x32_bf16 v[64:67], v[232:235], v[198:201], v[64:67]
	v_mfma_f32_16x16x32_bf16 v[116:119], v[226:229], v[148:151], v[116:119]
	v_mfma_f32_16x16x32_bf16 v[112:115], v[236:239], v[148:151], v[112:115]
	v_mfma_f32_16x16x32_bf16 v[100:103], v[226:229], v[186:189], v[100:103]
	v_mfma_f32_16x16x32_bf16 v[96:99], v[236:239], v[186:189], v[96:99]
	v_mfma_f32_16x16x32_bf16 v[84:87], v[226:229], v[194:197], v[84:87]
	v_mfma_f32_16x16x32_bf16 v[80:83], v[236:239], v[194:197], v[80:83]
	v_mfma_f32_16x16x32_bf16 v[68:71], v[226:229], v[204:207], v[68:71]
	v_mfma_f32_16x16x32_bf16 v[64:67], v[236:239], v[204:207], v[64:67]
	s_mov_b32 m0, s65
	v_lshl_add_u64 v[212:213], v[240:241], 0, s[80:81]
	s_barrier
	ds_read_b128 v[144:147], v203 offset:49152
	ds_read_b128 v[148:151], v203 offset:50176
	ds_read_b128 v[152:155], v203 offset:51200
	ds_read_b128 v[186:189], v203 offset:52224
	ds_read_b128 v[190:193], v203 offset:53248
	ds_read_b128 v[194:197], v203 offset:54272
	ds_read_b128 v[198:201], v203 offset:55296
	ds_read_b128 v[204:207], v203 offset:56320
	global_load_lds_dwordx4 v[212:213], off
	v_lshl_add_u64 v[212:213], v[242:243], 0, s[80:81]
	s_mov_b32 m0, s70
	s_nop 0
	global_load_lds_dwordx4 v[212:213], off
	s_barrier
	s_waitcnt lgkmcnt(0)
	s_waitcnt lgkmcnt(0)
	v_mfma_f32_16x16x32_bf16 v[60:63], v[128:131], v[144:147], v[60:63]
	v_mfma_f32_16x16x32_bf16 v[56:59], v[136:139], v[144:147], v[56:59]
	v_mfma_f32_16x16x32_bf16 v[44:47], v[128:131], v[152:155], v[44:47]
	v_mfma_f32_16x16x32_bf16 v[40:43], v[136:139], v[152:155], v[40:43]
	v_mfma_f32_16x16x32_bf16 v[28:31], v[128:131], v[190:193], v[28:31]
	v_mfma_f32_16x16x32_bf16 v[24:27], v[136:139], v[190:193], v[24:27]
	v_mfma_f32_16x16x32_bf16 v[12:15], v[128:131], v[198:201], v[12:15]
	v_mfma_f32_16x16x32_bf16 v[8:11], v[136:139], v[198:201], v[8:11]
	v_mfma_f32_16x16x32_bf16 v[60:63], v[132:135], v[148:151], v[60:63]
	v_mfma_f32_16x16x32_bf16 v[56:59], v[140:143], v[148:151], v[56:59]
	v_mfma_f32_16x16x32_bf16 v[44:47], v[132:135], v[186:189], v[44:47]
	v_mfma_f32_16x16x32_bf16 v[40:43], v[140:143], v[186:189], v[40:43]
	v_mfma_f32_16x16x32_bf16 v[28:31], v[132:135], v[194:197], v[28:31]
	v_mfma_f32_16x16x32_bf16 v[24:27], v[140:143], v[194:197], v[24:27]
	v_mfma_f32_16x16x32_bf16 v[12:15], v[132:135], v[204:207], v[12:15]
	v_mfma_f32_16x16x32_bf16 v[8:11], v[140:143], v[204:207], v[8:11]
	s_barrier
	s_add_u32 s34, s44, 0xb0080
	s_addc_u32 s35, s45, 0
	s_add_i32 s44, s48, s7
	s_mov_b32 m0, s44
	s_nop 0
	global_load_lds_dwordx4 v174, s[34:35]
	s_add_i32 m0, s44, 0x2000
	s_nop 0
	global_load_lds_dwordx4 v156, s[34:35]
	s_waitcnt vmcnt(6)
	s_barrier
	v_mfma_f32_16x16x32_bf16 v[52:55], v[208:211], v[144:147], v[52:55]
	v_mfma_f32_16x16x32_bf16 v[48:51], v[232:235], v[144:147], v[48:51]
	v_mfma_f32_16x16x32_bf16 v[36:39], v[208:211], v[152:155], v[36:39]
	v_mfma_f32_16x16x32_bf16 v[32:35], v[232:235], v[152:155], v[32:35]
	v_mfma_f32_16x16x32_bf16 v[20:23], v[208:211], v[190:193], v[20:23]
	v_mfma_f32_16x16x32_bf16 v[16:19], v[232:235], v[190:193], v[16:19]
	v_mfma_f32_16x16x32_bf16 v[4:7], v[208:211], v[198:201], v[4:7]
	v_mfma_f32_16x16x32_bf16 v[0:3], v[232:235], v[198:201], v[0:3]
	v_mfma_f32_16x16x32_bf16 v[52:55], v[226:229], v[148:151], v[52:55]
	v_mfma_f32_16x16x32_bf16 v[48:51], v[236:239], v[148:151], v[48:51]
	v_mfma_f32_16x16x32_bf16 v[36:39], v[226:229], v[186:189], v[36:39]
	v_mfma_f32_16x16x32_bf16 v[32:35], v[236:239], v[186:189], v[32:35]
	v_mfma_f32_16x16x32_bf16 v[20:23], v[226:229], v[194:197], v[20:23]
	v_mfma_f32_16x16x32_bf16 v[16:19], v[236:239], v[194:197], v[16:19]
	v_mfma_f32_16x16x32_bf16 v[4:7], v[226:229], v[204:207], v[4:7]
	v_mfma_f32_16x16x32_bf16 v[0:3], v[236:239], v[204:207], v[0:3]
	s_add_i32 s73, s73, 2
	s_add_u32 s52, s52, 0x100
	s_addc_u32 s72, s72, 0
	s_cmp_gt_u32 s73, 41
	s_mov_b64 s[34:35], s[42:43]
	s_barrier
	s_cbranch_scc0 .LBB0_1215
	s_cmp_lt_u32 s101, 0x100
	s_cbranch_scc0 .Lxa_11
	s_barrier
